# plus gdn_prep l2norm shuffle reductions: ds_bpermute xor butterflies replaced by exact DPP adds
# speedup vs baseline: 1.0726x; 1.0056x over previous
; DEV float bflo(unsigned u) { return __uint_as_float(u << 16); }
; DEV float bfhi(unsigned u) { return __uint_as_float(u & 0xffff0000u); }
; DEV float silu_f(float x) { return x / (1.f + __expf(-x)); }
; DEV void gdn_prep_chunk(const Params& p, int item, unsigned char* lds) {
;     ...
;         const int tl0 = rg * 16;
;         uint4 raw[19];
; #pragma unroll
;         for (int i = 0; i < 19; ++i) {
;             const int tl = tl0 - 3 + i;
;             if (c * 64 + tl >= 0) raw[i] = *(const uint4*)(proj + (size_t)(row0 + tl) * NPJ + colg);
;             else raw[i] = make_uint4(0u, 0u, 0u, 0u);
;         }
;         bf16_t* dst = (mat == 0 ? qs : (mat == 1 ? ks : vs));
; #pragma unroll
;         for (int r = 0; r < 16; ++r) {
;             float y[8]; float ss = 0.f;
; #pragma unroll
;             for (int e = 0; e < 8; ++e) {
;                 float a = 0.f;
; #pragma unroll
;                 for (int j = 0; j < 4; ++j) {
;                     const uint4 u = raw[r + j];
;                     const unsigned wd = (e < 2 ? u.x : (e < 4 ? u.y : (e < 6 ? u.z : u.w)));
;                     const float xv = (e & 1) ? bfhi(wd) : bflo(wd);
;                     a += w[j][e] * xv;
;                 }
;                 y[e] = silu_f(a); ss += y[e] * y[e];
.LBB0_472:
	s_or_b64 exec, exec, s[4:5]
	v_or_b32_e32 v38, s31, v133
	v_mad_i64_i32 v[36:37], s[4:5], v38, s55, v[34:35]
	global_load_dwordx4 v[106:109], v[36:37], off
	s_waitcnt vmcnt(1)
	v_lshlrev_b32_e32 v36, 16, v98
	v_and_b32_e32 v37, 0xffff0000, v98
	v_lshlrev_b32_e32 v116, 16, v94
	v_and_b32_e32 v117, 0xffff0000, v94
	v_or_b32_e32 v39, 1, v38
	v_or_b32_e32 v50, 7, v38
	v_or_b32_e32 v52, 8, v38
	v_or_b32_e32 v54, 9, v38
	v_or_b32_e32 v56, 10, v38
	v_or_b32_e32 v58, 11, v38
	v_pk_fma_f32 v[36:37], v[18:19], v[36:37], 0 op_sel_hi:[1,1,0]
	v_lshlrev_b32_e32 v112, 16, v102
	v_and_b32_e32 v113, 0xffff0000, v102
	v_or_b32_e32 v40, 2, v38
	v_or_b32_e32 v42, 3, v38
	v_or_b32_e32 v44, 4, v38
	v_or_b32_e32 v46, 5, v38
	v_or_b32_e32 v48, 6, v38
	v_or_b32_e32 v59, 12, v38
	v_or_b32_e32 v60, 13, v38
	v_or_b32_e32 v61, 14, v38
	v_or_b32_e32 v62, 15, v38
	v_mad_i64_i32 v[38:39], s[36:37], v39, s55, v[34:35]
	v_mad_i64_i32 v[50:51], s[36:37], v50, s55, v[34:35]
	v_mad_i64_i32 v[52:53], s[36:37], v52, s55, v[34:35]
	v_mad_i64_i32 v[54:55], s[36:37], v54, s55, v[34:35]
	v_mad_i64_i32 v[56:57], s[36:37], v56, s55, v[34:35]
	v_mad_i64_i32 v[110:111], s[36:37], v58, s55, v[34:35]
	v_pk_fma_f32 v[36:37], v[22:23], v[116:117], v[36:37]
	v_mad_i64_i32 v[40:41], s[36:37], v40, s55, v[34:35]
	v_mad_i64_i32 v[42:43], s[36:37], v42, s55, v[34:35]
	v_mad_i64_i32 v[44:45], s[36:37], v44, s55, v[34:35]
	v_mad_i64_i32 v[46:47], s[36:37], v46, s55, v[34:35]
	v_mad_i64_i32 v[48:49], s[36:37], v48, s55, v[34:35]
	v_mad_i64_i32 v[114:115], s[36:37], v59, s55, v[34:35]
	v_mad_i64_i32 v[118:119], s[36:37], v60, s55, v[34:35]
	v_mad_i64_i32 v[120:121], s[36:37], v61, s55, v[34:35]
	v_mad_i64_i32 v[34:35], s[36:37], v62, s55, v[34:35]
	global_load_dwordx4 v[90:93], v[38:39], off
	global_load_dwordx4 v[86:89], v[40:41], off
	global_load_dwordx4 v[82:85], v[42:43], off
	global_load_dwordx4 v[78:81], v[44:45], off
	global_load_dwordx4 v[74:77], v[46:47], off
	global_load_dwordx4 v[70:73], v[48:49], off
	global_load_dwordx4 v[66:69], v[50:51], off
	global_load_dwordx4 v[62:65], v[52:53], off
	global_load_dwordx4 v[58:61], v[54:55], off
	s_nop 0
	global_load_dwordx4 v[54:57], v[56:57], off
	s_nop 0
	global_load_dwordx4 v[50:53], v[110:111], off
	v_pk_fma_f32 v[36:37], v[26:27], v[112:113], v[36:37]
	v_cmp_gt_u32_e64 s[4:5], 64, v130
	v_cmp_gt_i32_e64 s[6:7], 2, v131
	s_waitcnt vmcnt(11)
	v_lshlrev_b32_e32 v110, 16, v106
	v_and_b32_e32 v111, 0xffff0000, v106
	v_pk_fma_f32 v[122:123], v[30:31], v[110:111], v[36:37]
	s_nop 0
	v_mul_f32_e32 v36, 0xbfb8aa3b, v122
	v_mul_f32_e32 v37, 0xbfb8aa3b, v123
	v_exp_f32_e32 v124, v36
	v_exp_f32_e32 v125, v37
	global_load_dwordx4 v[46:49], v[114:115], off
	global_load_dwordx4 v[42:45], v[118:119], off
	global_load_dwordx4 v[38:41], v[120:121], off
	s_nop 0
	global_load_dwordx4 v[34:37], v[34:35], off
	v_lshlrev_b32_e32 v118, 16, v95
	v_and_b32_e32 v119, 0xffff0000, v95
	v_pk_add_f32 v[120:121], v[124:125], 1.0 op_sel_hi:[1,0]
	v_and_b32_e32 v95, 0xffff0000, v107


; DEV float bflo(unsigned u) { return __uint_as_float(u << 16); }
; DEV float bfhi(unsigned u) { return __uint_as_float(u & 0xffff0000u); }
; DEV float silu_f(float x) { return x / (1.f + __expf(-x)); }
; DEV void gdn_prep_chunk(const Params& p, int item, unsigned char* lds) {
;     ...
;             for (int e = 0; e < 8; ++e) {
;                 float a = 0.f;
; #pragma unroll
;                 for (int j = 0; j < 4; ++j) {
;                     const uint4 u = raw[r + j];
;                     const unsigned wd = (e < 2 ? u.x : (e < 4 ? u.y : (e < 6 ? u.z : u.w)));
;                     const float xv = (e & 1) ? bfhi(wd) : bflo(wd);
;                     a += w[j][e] * xv;
;                 }
;                 y[e] = silu_f(a); ss += y[e] * y[e];
	v_lshlrev_b32_e32 v98, 16, v99
	v_and_b32_e32 v99, 0xffff0000, v99
	v_pk_fma_f32 v[98:99], v[20:21], v[98:99], 0 op_sel_hi:[1,1,0]
	v_lshlrev_b32_e32 v114, 16, v103
	v_and_b32_e32 v115, 0xffff0000, v103
	v_pk_fma_f32 v[98:99], v[24:25], v[118:119], v[98:99]
	v_rcp_f32_e32 v94, v121
	s_nop 0
	v_mul_f32_e32 v125, v123, v94
	v_lshlrev_b32_e32 v94, 16, v107
	v_pk_fma_f32 v[98:99], v[28:29], v[114:115], v[98:99]

; DEV float bflo(unsigned u) { return __uint_as_float(u << 16); }
; DEV float bfhi(unsigned u) { return __uint_as_float(u & 0xffff0000u); }
; DEV float silu_f(float x) { return x / (1.f + __expf(-x)); }
; DEV void gdn_prep_chunk(const Params& p, int item, unsigned char* lds) {
;     ...
;             for (int e = 0; e < 8; ++e) {
;                 float a = 0.f;
; #pragma unroll
;                 for (int j = 0; j < 4; ++j) {
;                     const uint4 u = raw[r + j];
;                     const unsigned wd = (e < 2 ? u.x : (e < 4 ? u.y : (e < 6 ? u.z : u.w)));
;                     const float xv = (e & 1) ? bfhi(wd) : bflo(wd);
;                     a += w[j][e] * xv;
;                 }
;                 y[e] = silu_f(a); ss += y[e] * y[e];
	v_pk_fma_f32 v[102:103], v[32:33], v[94:95], v[98:99]

; DEV float bflo(unsigned u) { return __uint_as_float(u << 16); }
; DEV float bfhi(unsigned u) { return __uint_as_float(u & 0xffff0000u); }
; DEV float silu_f(float x) { return x / (1.f + __expf(-x)); }
; DEV void gdn_prep_chunk(const Params& p, int item, unsigned char* lds) {
;     ...
;             for (int e = 0; e < 8; ++e) {
;                 float a = 0.f;
; #pragma unroll
;                 for (int j = 0; j < 4; ++j) {
;                     const uint4 u = raw[r + j];
;                     const unsigned wd = (e < 2 ? u.x : (e < 4 ? u.y : (e < 6 ? u.z : u.w)));
;                     const float xv = (e & 1) ? bfhi(wd) : bflo(wd);
;                     a += w[j][e] * xv;
;                 }
;                 y[e] = silu_f(a); ss += y[e] * y[e];
	v_mul_f32_e32 v98, 0xbfb8aa3b, v102
	v_mul_f32_e32 v99, 0xbfb8aa3b, v103
	v_exp_f32_e32 v98, v98
	v_exp_f32_e32 v99, v99


; DEV float bflo(unsigned u) { return __uint_as_float(u << 16); }
; DEV float bfhi(unsigned u) { return __uint_as_float(u & 0xffff0000u); }
; DEV float silu_f(float x) { return x / (1.f + __expf(-x)); }
; DEV void gdn_prep_chunk(const Params& p, int item, unsigned char* lds) {
;     ...
;             for (int e = 0; e < 8; ++e) {
;                 float a = 0.f;
; #pragma unroll
;                 for (int j = 0; j < 4; ++j) {
;                     const uint4 u = raw[r + j];
;                     const unsigned wd = (e < 2 ? u.x : (e < 4 ? u.y : (e < 6 ? u.z : u.w)));
;                     const float xv = (e & 1) ? bfhi(wd) : bflo(wd);
;                     a += w[j][e] * xv;
;                 }
;                 y[e] = silu_f(a); ss += y[e] * y[e];
	s_nop 0
	v_pk_add_f32 v[126:127], v[98:99], 1.0 op_sel_hi:[1,0]


; DEV float bflo(unsigned u) { return __uint_as_float(u << 16); }
; DEV float bfhi(unsigned u) { return __uint_as_float(u & 0xffff0000u); }
; DEV float silu_f(float x) { return x / (1.f + __expf(-x)); }
; DEV void gdn_prep_chunk(const Params& p, int item, unsigned char* lds) {
;     ...
;             for (int e = 0; e < 8; ++e) {
;                 float a = 0.f;
; #pragma unroll
;                 for (int j = 0; j < 4; ++j) {
;                     const uint4 u = raw[r + j];
;                     const unsigned wd = (e < 2 ? u.x : (e < 4 ? u.y : (e < 6 ? u.z : u.w)));
;                     const float xv = (e & 1) ? bfhi(wd) : bflo(wd);
;                     a += w[j][e] * xv;
;                 }
;                 y[e] = silu_f(a); ss += y[e] * y[e];
	v_rcp_f32_e32 v106, v120
	s_nop 0
	v_mul_f32_e32 v124, v122, v106


; DEV float bflo(unsigned u) { return __uint_as_float(u << 16); }
; DEV float bfhi(unsigned u) { return __uint_as_float(u & 0xffff0000u); }
; DEV float silu_f(float x) { return x / (1.f + __expf(-x)); }
; DEV void gdn_prep_chunk(const Params& p, int item, unsigned char* lds) {
;     ...
;             for (int e = 0; e < 8; ++e) {
;                 float a = 0.f;
; #pragma unroll
;                 for (int j = 0; j < 4; ++j) {
;                     const uint4 u = raw[r + j];
;                     const unsigned wd = (e < 2 ? u.x : (e < 4 ? u.y : (e < 6 ? u.z : u.w)));
;                     const float xv = (e & 1) ? bfhi(wd) : bflo(wd);
;                     a += w[j][e] * xv;
;                 }
;                 y[e] = silu_f(a); ss += y[e] * y[e];
	v_lshlrev_b32_e32 v120, 16, v100
	v_and_b32_e32 v121, 0xffff0000, v100

; DEV float bflo(unsigned u) { return __uint_as_float(u << 16); }
; DEV float bfhi(unsigned u) { return __uint_as_float(u & 0xffff0000u); }
; DEV float silu_f(float x) { return x / (1.f + __expf(-x)); }
; DEV void gdn_prep_chunk(const Params& p, int item, unsigned char* lds) {
;     ...
;             for (int e = 0; e < 8; ++e) {
;                 float a = 0.f;
; #pragma unroll
;                 for (int j = 0; j < 4; ++j) {
;                     const uint4 u = raw[r + j];
;                     const unsigned wd = (e < 2 ? u.x : (e < 4 ? u.y : (e < 6 ? u.z : u.w)));
;                     const float xv = (e & 1) ? bfhi(wd) : bflo(wd);
;                     a += w[j][e] * xv;
;                 }
;                 y[e] = silu_f(a); ss += y[e] * y[e];
	v_lshlrev_b32_e32 v122, 16, v96
	v_and_b32_e32 v123, 0xffff0000, v96
	v_pk_fma_f32 v[120:121], v[2:3], v[120:121], 0 op_sel_hi:[1,1,0]
	v_rcp_f32_e32 v98, v127
	s_nop 0
	v_mul_f32_e32 v103, v103, v98

; DEV float bflo(unsigned u) { return __uint_as_float(u << 16); }
; DEV float bfhi(unsigned u) { return __uint_as_float(u & 0xffff0000u); }
; DEV float silu_f(float x) { return x / (1.f + __expf(-x)); }
; DEV void gdn_prep_chunk(const Params& p, int item, unsigned char* lds) {
;     ...
;             for (int e = 0; e < 8; ++e) {
;                 float a = 0.f;
; #pragma unroll
;                 for (int j = 0; j < 4; ++j) {
;                     const uint4 u = raw[r + j];
;                     const unsigned wd = (e < 2 ? u.x : (e < 4 ? u.y : (e < 6 ? u.z : u.w)));
;                     const float xv = (e & 1) ? bfhi(wd) : bflo(wd);
;                     a += w[j][e] * xv;
;                 }
;                 y[e] = silu_f(a); ss += y[e] * y[e];
	v_lshlrev_b32_e32 v106, 16, v104
	v_and_b32_e32 v107, 0xffff0000, v104
	v_pk_fma_f32 v[120:121], v[6:7], v[122:123], v[120:121]

; DEV float bflo(unsigned u) { return __uint_as_float(u << 16); }
; DEV float bfhi(unsigned u) { return __uint_as_float(u & 0xffff0000u); }
; DEV float silu_f(float x) { return x / (1.f + __expf(-x)); }
; DEV void gdn_prep_chunk(const Params& p, int item, unsigned char* lds) {
;     ...
;             for (int e = 0; e < 8; ++e) {
;                 float a = 0.f;
; #pragma unroll
;                 for (int j = 0; j < 4; ++j) {
;                     const uint4 u = raw[r + j];
;                     const unsigned wd = (e < 2 ? u.x : (e < 4 ? u.y : (e < 6 ? u.z : u.w)));
;                     const float xv = (e & 1) ? bfhi(wd) : bflo(wd);
;                     a += w[j][e] * xv;
;                 }
;                 y[e] = silu_f(a); ss += y[e] * y[e];
	v_lshlrev_b32_e32 v98, 16, v108
	v_and_b32_e32 v99, 0xffff0000, v108
	v_pk_fma_f32 v[120:121], v[10:11], v[106:107], v[120:121]

; DEV float bflo(unsigned u) { return __uint_as_float(u << 16); }
; DEV float bfhi(unsigned u) { return __uint_as_float(u & 0xffff0000u); }
; DEV float silu_f(float x) { return x / (1.f + __expf(-x)); }
; DEV void gdn_prep_chunk(const Params& p, int item, unsigned char* lds) {
;     ...
;             for (int e = 0; e < 8; ++e) {
;                 float a = 0.f;
; #pragma unroll
;                 for (int j = 0; j < 4; ++j) {
;                     const uint4 u = raw[r + j];
;                     const unsigned wd = (e < 2 ? u.x : (e < 4 ? u.y : (e < 6 ? u.z : u.w)));
;                     const float xv = (e & 1) ? bfhi(wd) : bflo(wd);
;                     a += w[j][e] * xv;
;                 }
;                 y[e] = silu_f(a); ss += y[e] * y[e];
	v_pk_fma_f32 v[128:129], v[14:15], v[98:99], v[120:121]

; DEV float bflo(unsigned u) { return __uint_as_float(u << 16); }
; DEV float bfhi(unsigned u) { return __uint_as_float(u & 0xffff0000u); }
; DEV float silu_f(float x) { return x / (1.f + __expf(-x)); }
; DEV void gdn_prep_chunk(const Params& p, int item, unsigned char* lds) {
;     ...
;             for (int e = 0; e < 8; ++e) {
;                 float a = 0.f;
; #pragma unroll
;                 for (int j = 0; j < 4; ++j) {
;                     const uint4 u = raw[r + j];
;                     const unsigned wd = (e < 2 ? u.x : (e < 4 ? u.y : (e < 6 ? u.z : u.w)));
;                     const float xv = (e & 1) ? bfhi(wd) : bflo(wd);
;                     a += w[j][e] * xv;
;                 }
;                 y[e] = silu_f(a); ss += y[e] * y[e];
	v_mul_f32_e32 v96, 0xbfb8aa3b, v128
	v_exp_f32_e32 v120, v96
	v_mul_f32_e32 v96, 0xbfb8aa3b, v129
	v_exp_f32_e32 v121, v96


; DEV float bflo(unsigned u) { return __uint_as_float(u << 16); }
; DEV float bfhi(unsigned u) { return __uint_as_float(u & 0xffff0000u); }
; DEV float silu_f(float x) { return x / (1.f + __expf(-x)); }
; DEV void gdn_prep_chunk(const Params& p, int item, unsigned char* lds) {
;     ...
;             for (int e = 0; e < 8; ++e) {
;                 float a = 0.f;
; #pragma unroll
;                 for (int j = 0; j < 4; ++j) {
;                     const uint4 u = raw[r + j];
;                     const unsigned wd = (e < 2 ? u.x : (e < 4 ? u.y : (e < 6 ? u.z : u.w)));
;                     const float xv = (e & 1) ? bfhi(wd) : bflo(wd);
;                     a += w[j][e] * xv;
;                 }
;                 y[e] = silu_f(a); ss += y[e] * y[e];
	s_nop 0
	v_pk_add_f32 v[134:135], v[120:121], 1.0 op_sel_hi:[1,0]


; DEV float bflo(unsigned u) { return __uint_as_float(u << 16); }
; DEV float bfhi(unsigned u) { return __uint_as_float(u & 0xffff0000u); }
; DEV float silu_f(float x) { return x / (1.f + __expf(-x)); }
; DEV void gdn_prep_chunk(const Params& p, int item, unsigned char* lds) {
;     ...
;             for (int e = 0; e < 8; ++e) {
;                 float a = 0.f;
; #pragma unroll
;                 for (int j = 0; j < 4; ++j) {
;                     const uint4 u = raw[r + j];
;                     const unsigned wd = (e < 2 ? u.x : (e < 4 ? u.y : (e < 6 ? u.z : u.w)));
;                     const float xv = (e & 1) ? bfhi(wd) : bflo(wd);
;                     a += w[j][e] * xv;
;                 }
;                 y[e] = silu_f(a); ss += y[e] * y[e];
	v_rcp_f32_e32 v96, v126
	s_nop 0
	v_mul_f32_e32 v102, v102, v96


; DEV float bflo(unsigned u) { return __uint_as_float(u << 16); }
; DEV float bfhi(unsigned u) { return __uint_as_float(u & 0xffff0000u); }
; DEV float silu_f(float x) { return x / (1.f + __expf(-x)); }
; DEV void gdn_prep_chunk(const Params& p, int item, unsigned char* lds) {
;     ...
;             for (int e = 0; e < 8; ++e) {
;                 float a = 0.f;
; #pragma unroll
;                 for (int j = 0; j < 4; ++j) {
;                     const uint4 u = raw[r + j];
;                     const unsigned wd = (e < 2 ? u.x : (e < 4 ? u.y : (e < 6 ? u.z : u.w)));
;                     const float xv = (e & 1) ? bfhi(wd) : bflo(wd);
;                     a += w[j][e] * xv;
;                 }
;                 y[e] = silu_f(a); ss += y[e] * y[e];
	v_lshlrev_b32_e32 v100, 16, v101
	v_and_b32_e32 v101, 0xffff0000, v101

; DEV float bflo(unsigned u) { return __uint_as_float(u << 16); }
; DEV float bfhi(unsigned u) { return __uint_as_float(u & 0xffff0000u); }
; DEV float silu_f(float x) { return x / (1.f + __expf(-x)); }
; DEV void gdn_prep_chunk(const Params& p, int item, unsigned char* lds) {
;     ...
;             for (int e = 0; e < 8; ++e) {
;                 float a = 0.f;
; #pragma unroll
;                 for (int j = 0; j < 4; ++j) {
;                     const uint4 u = raw[r + j];
;                     const unsigned wd = (e < 2 ? u.x : (e < 4 ? u.y : (e < 6 ? u.z : u.w)));
;                     const float xv = (e & 1) ? bfhi(wd) : bflo(wd);
;                     a += w[j][e] * xv;
;                 }
;                 y[e] = silu_f(a); ss += y[e] * y[e];
	v_lshlrev_b32_e32 v126, 16, v97
	v_and_b32_e32 v127, 0xffff0000, v97
	v_pk_fma_f32 v[100:101], v[4:5], v[100:101], 0 op_sel_hi:[1,1,0]
	v_rcp_f32_e32 v96, v135
	s_nop 0
	v_mul_f32_e32 v129, v129, v96

; DEV float bflo(unsigned u) { return __uint_as_float(u << 16); }
; DEV float bfhi(unsigned u) { return __uint_as_float(u & 0xffff0000u); }
; DEV float silu_f(float x) { return x / (1.f + __expf(-x)); }
; DEV void gdn_prep_chunk(const Params& p, int item, unsigned char* lds) {
;     ...
;             for (int e = 0; e < 8; ++e) {
;                 float a = 0.f;
; #pragma unroll
;                 for (int j = 0; j < 4; ++j) {
;                     const uint4 u = raw[r + j];
;                     const unsigned wd = (e < 2 ? u.x : (e < 4 ? u.y : (e < 6 ? u.z : u.w)));
;                     const float xv = (e & 1) ? bfhi(wd) : bflo(wd);
;                     a += w[j][e] * xv;
;                 }
;                 y[e] = silu_f(a); ss += y[e] * y[e];
	v_lshlrev_b32_e32 v120, 16, v105
	v_and_b32_e32 v121, 0xffff0000, v105
	v_pk_fma_f32 v[100:101], v[8:9], v[126:127], v[100:101]

; DEV float bflo(unsigned u) { return __uint_as_float(u << 16); }
; DEV float bfhi(unsigned u) { return __uint_as_float(u & 0xffff0000u); }
; DEV float silu_f(float x) { return x / (1.f + __expf(-x)); }
; DEV void gdn_prep_chunk(const Params& p, int item, unsigned char* lds) {
;     ...
;             for (int e = 0; e < 8; ++e) {
;                 float a = 0.f;
; #pragma unroll
;                 for (int j = 0; j < 4; ++j) {
;                     const uint4 u = raw[r + j];
;                     const unsigned wd = (e < 2 ? u.x : (e < 4 ? u.y : (e < 6 ? u.z : u.w)));
;                     const float xv = (e & 1) ? bfhi(wd) : bflo(wd);
;                     a += w[j][e] * xv;
;                 }
;                 y[e] = silu_f(a); ss += y[e] * y[e];
	v_lshlrev_b32_e32 v96, 16, v109
	v_and_b32_e32 v97, 0xffff0000, v109
	v_pk_fma_f32 v[100:101], v[12:13], v[120:121], v[100:101]

; DEV float bflo(unsigned u) { return __uint_as_float(u << 16); }
; DEV float bfhi(unsigned u) { return __uint_as_float(u & 0xffff0000u); }
; DEV float silu_f(float x) { return x / (1.f + __expf(-x)); }
; DEV void gdn_prep_chunk(const Params& p, int item, unsigned char* lds) {
;     ...
;             for (int e = 0; e < 8; ++e) {
;                 float a = 0.f;
; #pragma unroll
;                 for (int j = 0; j < 4; ++j) {
;                     const uint4 u = raw[r + j];
;                     const unsigned wd = (e < 2 ? u.x : (e < 4 ? u.y : (e < 6 ? u.z : u.w)));
;                     const float xv = (e & 1) ? bfhi(wd) : bflo(wd);
;                     a += w[j][e] * xv;
;                 }
;                 y[e] = silu_f(a); ss += y[e] * y[e];
	v_pk_fma_f32 v[100:101], v[16:17], v[96:97], v[100:101]

; DEV float bflo(unsigned u) { return __uint_as_float(u << 16); }
; DEV float bfhi(unsigned u) { return __uint_as_float(u & 0xffff0000u); }
; DEV float silu_f(float x) { return x / (1.f + __expf(-x)); }
; DEV void gdn_prep_chunk(const Params& p, int item, unsigned char* lds) {
;     ...
;             for (int e = 0; e < 8; ++e) {
;                 float a = 0.f;
; #pragma unroll
;                 for (int j = 0; j < 4; ++j) {
;                     const uint4 u = raw[r + j];
;                     const unsigned wd = (e < 2 ? u.x : (e < 4 ? u.y : (e < 6 ? u.z : u.w)));
;                     const float xv = (e & 1) ? bfhi(wd) : bflo(wd);
;                     a += w[j][e] * xv;
;                 }
;                 y[e] = silu_f(a); ss += y[e] * y[e];
	v_mul_f32_e32 v104, 0xbfb8aa3b, v100
	v_mul_f32_e32 v105, 0xbfb8aa3b, v101
	v_exp_f32_e32 v104, v104
	v_exp_f32_e32 v105, v105


; DEV float bflo(unsigned u) { return __uint_as_float(u << 16); }
; DEV float bfhi(unsigned u) { return __uint_as_float(u & 0xffff0000u); }
; DEV float silu_f(float x) { return x / (1.f + __expf(-x)); }
; DEV void gdn_prep_chunk(const Params& p, int item, unsigned char* lds) {
;     ...
;             for (int e = 0; e < 8; ++e) {
;                 float a = 0.f;
; #pragma unroll
;                 for (int j = 0; j < 4; ++j) {
;                     const uint4 u = raw[r + j];
;                     const unsigned wd = (e < 2 ? u.x : (e < 4 ? u.y : (e < 6 ? u.z : u.w)));
;                     const float xv = (e & 1) ? bfhi(wd) : bflo(wd);
;                     a += w[j][e] * xv;
;                 }
;                 y[e] = silu_f(a); ss += y[e] * y[e];
	s_nop 0
	v_pk_add_f32 v[104:105], v[104:105], 1.0 op_sel_hi:[1,0]


; DEV float bflo(unsigned u) { return __uint_as_float(u << 16); }
; DEV float bfhi(unsigned u) { return __uint_as_float(u & 0xffff0000u); }
; DEV float silu_f(float x) { return x / (1.f + __expf(-x)); }
; DEV void gdn_prep_chunk(const Params& p, int item, unsigned char* lds) {
;     ...
;             for (int e = 0; e < 8; ++e) {
;                 float a = 0.f;
; #pragma unroll
;                 for (int j = 0; j < 4; ++j) {
;                     const uint4 u = raw[r + j];
;                     const unsigned wd = (e < 2 ? u.x : (e < 4 ? u.y : (e < 6 ? u.z : u.w)));
;                     const float xv = (e & 1) ? bfhi(wd) : bflo(wd);
;                     a += w[j][e] * xv;
;                 }
;                 y[e] = silu_f(a); ss += y[e] * y[e];
	v_rcp_f32_e32 v108, v134
	s_nop 0
	v_mul_f32_e32 v128, v128, v108


; DEV float bflo(unsigned u) { return __uint_as_float(u << 16); }
; DEV float bfhi(unsigned u) { return __uint_as_float(u & 0xffff0000u); }
; DEV float silu_f(float x) { return x / (1.f + __expf(-x)); }
; DEV void gdn_prep_chunk(const Params& p, int item, unsigned char* lds) {
;     ...
;             for (int e = 0; e < 8; ++e) {
;                 float a = 0.f;
; #pragma unroll
;                 for (int j = 0; j < 4; ++j) {
;                     const uint4 u = raw[r + j];
;                     const unsigned wd = (e < 2 ? u.x : (e < 4 ? u.y : (e < 6 ? u.z : u.w)));
;                     const float xv = (e & 1) ? bfhi(wd) : bflo(wd);
;                     a += w[j][e] * xv;
;                 }
;                 y[e] = silu_f(a); ss += y[e] * y[e];
	v_rcp_f32_e32 v108, v105
	s_nop 0
	v_mul_f32_e32 v101, v101, v108


; DEV float silu_f(float x) { return x / (1.f + __expf(-x)); }
; DEV void gdn_prep_chunk(const Params& p, int item, unsigned char* lds) {
;     ...
;                 y[e] = silu_f(a); ss += y[e] * y[e];
;             }
;             if (mat < 2) {
;                 ss += __shfl_xor(ss, 1); ss += __shfl_xor(ss, 2); ss += __shfl_xor(ss, 4); ss += __shfl_xor(ss, 8);
	v_rcp_f32_e32 v105, v104
	s_nop 0
	v_mul_f32_e32 v100, v100, v105
	s_and_saveexec_b64 s[36:37], s[6:7]
	s_cbranch_execz .LBB0_474
	v_pk_mul_f32 v[104:105], v[124:125], v[124:125]
	v_pk_mul_f32 v[108:109], v[102:103], v[102:103]
	v_add_f32_e32 v104, v104, v105
	v_add_f32_e32 v104, v104, v108
	v_pk_mul_f32 v[134:135], v[128:129], v[128:129]
	v_add_f32_e32 v104, v109, v104
	v_and_b32_e32 v108, 64, v182
	v_add_f32_e32 v104, v134, v104

; DEV float silu_f(float x) { return x / (1.f + __expf(-x)); }
; DEV void gdn_prep_chunk(const Params& p, int item, unsigned char* lds) {
;     ...
;                 y[e] = silu_f(a); ss += y[e] * y[e];
;             }
;             if (mat < 2) {
;                 ss += __shfl_xor(ss, 1); ss += __shfl_xor(ss, 2); ss += __shfl_xor(ss, 4); ss += __shfl_xor(ss, 8);
	v_add_u32_e32 v108, 64, v108
	v_pk_mul_f32 v[136:137], v[100:101], v[100:101]
	v_add_f32_e32 v104, v135, v104

; DEV float silu_f(float x) { return x / (1.f + __expf(-x)); }
; DEV void gdn_prep_chunk(const Params& p, int item, unsigned char* lds) {
;     ...
;                 y[e] = silu_f(a); ss += y[e] * y[e];
;             }
;             if (mat < 2) {
;                 ss += __shfl_xor(ss, 1); ss += __shfl_xor(ss, 2); ss += __shfl_xor(ss, 4); ss += __shfl_xor(ss, 8);
	v_add_f32_e32 v104, v136, v104
	v_add_f32_e32 v104, v137, v104


; DEV void gdn_prep_chunk(const Params& p, int item, unsigned char* lds) {
;     ...
;                 ss += __shfl_xor(ss, 1); ss += __shfl_xor(ss, 2); ss += __shfl_xor(ss, 4); ss += __shfl_xor(ss, 8);
	s_waitcnt lgkmcnt(0)
	s_nop 1
	v_add_f32_dpp v104, v104, v104 quad_perm:[1,0,3,2] row_mask:0xf bank_mask:0xf


; DEV void gdn_prep_chunk(const Params& p, int item, unsigned char* lds) {
;     ...
;                 ss += __shfl_xor(ss, 1); ss += __shfl_xor(ss, 2); ss += __shfl_xor(ss, 4); ss += __shfl_xor(ss, 8);
	s_nop 1


; DEV void gdn_prep_chunk(const Params& p, int item, unsigned char* lds) {
;     ...
;                 ss += __shfl_xor(ss, 1); ss += __shfl_xor(ss, 2); ss += __shfl_xor(ss, 4); ss += __shfl_xor(ss, 8);
	s_waitcnt lgkmcnt(0)
	s_nop 1
	v_add_f32_dpp v104, v104, v104 quad_perm:[2,3,0,1] row_mask:0xf bank_mask:0xf


; DEV void gdn_prep_chunk(const Params& p, int item, unsigned char* lds) {
;     ...
;                 ss += __shfl_xor(ss, 1); ss += __shfl_xor(ss, 2); ss += __shfl_xor(ss, 4); ss += __shfl_xor(ss, 8);
	s_nop 1


; DEV void gdn_prep_chunk(const Params& p, int item, unsigned char* lds) {
;     ...
;                 ss += __shfl_xor(ss, 1); ss += __shfl_xor(ss, 2); ss += __shfl_xor(ss, 4); ss += __shfl_xor(ss, 8);
	s_waitcnt lgkmcnt(0)
	s_nop 1
	v_add_f32_dpp v104, v104, v104 row_half_mirror row_mask:0xf bank_mask:0xf


; DEV void gdn_prep_chunk(const Params& p, int item, unsigned char* lds) {
;     ...
;                 ss += __shfl_xor(ss, 1); ss += __shfl_xor(ss, 2); ss += __shfl_xor(ss, 4); ss += __shfl_xor(ss, 8);
	s_nop 1


; DEV unsigned cvt_pk_bf16(float lo, float hi) { const f32x2_t v = {lo, hi}; const bf16x2_t b = __builtin_convertvector(v, bf16x2_t); return __builtin_bit_cast(unsigned, b); }
; DEV float bflo(unsigned u) { return __uint_as_float(u << 16); }
; DEV float bfhi(unsigned u) { return __uint_as_float(u & 0xffff0000u); }
; DEV float silu_f(float x) { return x / (1.f + __expf(-x)); }
; DEV void gdn_prep_chunk(const Params& p, int item, unsigned char* lds) {
;     ...
;             for (int e = 0; e < 8; ++e) {
;                 float a = 0.f;
; #pragma unroll
;                 for (int j = 0; j < 4; ++j) {
;                     const uint4 u = raw[r + j];
;                     const unsigned wd = (e < 2 ? u.x : (e < 4 ? u.y : (e < 6 ? u.z : u.w)));
;                     const float xv = (e & 1) ? bfhi(wd) : bflo(wd);
;                     a += w[j][e] * xv;
;                 }
;                 y[e] = silu_f(a); ss += y[e] * y[e];
;     ...
;                 ss += __shfl_xor(ss, 1); ss += __shfl_xor(ss, 2); ss += __shfl_xor(ss, 4); ss += __shfl_xor(ss, 8);
;                 float inv = rsqrtf(ss + EPS); if (mat == 0) inv *= 0.08838834764831845f;
; #pragma unroll
;                 for (int e = 0; e < 8; ++e) y[e] *= inv;
;             }
;             uint4 o; o.x = cvt_pk_bf16(y[0], y[1]); o.y = cvt_pk_bf16(y[2], y[3]); o.z = cvt_pk_bf16(y[4], y[5]); o.w = cvt_pk_bf16(y[6], y[7]);
;             *(uint4*)(dst + (tl0 + r) * QS + cv * 8) = o;
	s_waitcnt lgkmcnt(0)
	s_nop 1
	v_add_f32_dpp v104, v104, v104 row_mirror row_mask:0xf bank_mask:0xf
	v_add_f32_e32 v104, 0x358637bd, v104
	v_mul_f32_e32 v105, 0x4b800000, v104
	v_cmp_gt_f32_e32 vcc, s56, v104
	s_nop 1
	v_cndmask_b32_e32 v104, v104, v105, vcc
	v_rsq_f32_e32 v104, v104
	s_nop 0
	v_mul_f32_e32 v105, 0x45800000, v104
	v_cndmask_b32_e32 v104, v104, v105, vcc
	v_mul_f32_e32 v105, 0x3db504f3, v104
	v_cndmask_b32_e64 v104, v104, v105, s[4:5]
	v_pk_mul_f32 v[124:125], v[124:125], v[104:105] op_sel_hi:[1,0]
	v_pk_mul_f32 v[102:103], v[102:103], v[104:105] op_sel_hi:[1,0]
	v_pk_mul_f32 v[128:129], v[128:129], v[104:105] op_sel_hi:[1,0]
	v_pk_mul_f32 v[100:101], v[100:101], v[104:105] op_sel_hi:[1,0]
.LBB0_474:
	s_or_b64 exec, exec, s[36:37]
	v_mov_b32_e32 v104, s42
	v_mov_b32_e32 v105, s41
	v_cmp_eq_u32_e32 vcc, 1, v131
	v_pk_fma_f32 v[108:109], v[18:19], v[116:117], 0 op_sel_hi:[1,1,0]
	v_cvt_pk_bf16_f32 v135, v102, v103
	v_cndmask_b32_e32 v104, v104, v105, vcc
	v_mov_b32_e32 v105, s39
	v_cndmask_b32_e64 v104, v104, v105, s[4:5]
	v_pk_fma_f32 v[108:109], v[22:23], v[112:113], v[108:109]
	v_lshl_add_u32 v132, v132, 1, v104
	s_waitcnt vmcnt(14)
	v_lshlrev_b32_e32 v104, 16, v90
	v_and_b32_e32 v105, 0xffff0000, v90
	v_pk_fma_f32 v[108:109], v[26:27], v[110:111], v[108:109]
	v_cvt_pk_bf16_f32 v134, v124, v125
	v_pk_fma_f32 v[108:109], v[30:31], v[104:105], v[108:109]
	v_cvt_pk_bf16_f32 v136, v128, v129
	v_mul_f32_e32 v90, 0xbfb8aa3b, v108
	v_exp_f32_e32 v116, v90
	v_mul_f32_e32 v90, 0xbfb8aa3b, v109
	v_exp_f32_e32 v117, v90
	v_cvt_pk_bf16_f32 v137, v100, v101
	v_mad_u32_u24 v100, v133, s57, v132
	ds_write_b128 v100, v[134:137]
	v_pk_add_f32 v[116:117], v[116:117], 1.0 op_sel_hi:[1,0]
	v_pk_fma_f32 v[122:123], v[2:3], v[122:123], 0 op_sel_hi:[1,1,0]


; DEV float bflo(unsigned u) { return __uint_as_float(u << 16); }
; DEV float bfhi(unsigned u) { return __uint_as_float(u & 0xffff0000u); }
; DEV float silu_f(float x) { return x / (1.f + __expf(-x)); }
; DEV void gdn_prep_chunk(const Params& p, int item, unsigned char* lds) {
;     ...
;             for (int e = 0; e < 8; ++e) {
;                 float a = 0.f;
; #pragma unroll
;                 for (int j = 0; j < 4; ++j) {
;                     const uint4 u = raw[r + j];
;                     const unsigned wd = (e < 2 ? u.x : (e < 4 ? u.y : (e < 6 ? u.z : u.w)));
;                     const float xv = (e & 1) ? bfhi(wd) : bflo(wd);
;                     a += w[j][e] * xv;
;                 }
;                 y[e] = silu_f(a); ss += y[e] * y[e];
	v_rcp_f32_e32 v90, v117
	s_nop 0
	v_mul_f32_e32 v109, v109, v90


; DEV float bflo(unsigned u) { return __uint_as_float(u << 16); }
; DEV float bfhi(unsigned u) { return __uint_as_float(u & 0xffff0000u); }
; DEV void gdn_prep_chunk(const Params& p, int item, unsigned char* lds) {
;     ...
;             for (int e = 0; e < 8; ++e) {
;                 float a = 0.f;
; #pragma unroll
;                 for (int j = 0; j < 4; ++j) {
;                     const uint4 u = raw[r + j];
;                     const unsigned wd = (e < 2 ? u.x : (e < 4 ? u.y : (e < 6 ? u.z : u.w)));
;                     const float xv = (e & 1) ? bfhi(wd) : bflo(wd);
;                     a += w[j][e] * xv;
	v_lshlrev_b32_e32 v102, 16, v91
	v_and_b32_e32 v103, 0xffff0000, v91
	v_pk_fma_f32 v[90:91], v[20:21], v[118:119], 0 op_sel_hi:[1,1,0]

; DEV float bflo(unsigned u) { return __uint_as_float(u << 16); }
; DEV float bfhi(unsigned u) { return __uint_as_float(u & 0xffff0000u); }
; DEV void gdn_prep_chunk(const Params& p, int item, unsigned char* lds) {
;     ...
;                 for (int j = 0; j < 4; ++j) {
;                     const uint4 u = raw[r + j];
;                     const unsigned wd = (e < 2 ? u.x : (e < 4 ? u.y : (e < 6 ? u.z : u.w)));
;                     const float xv = (e & 1) ? bfhi(wd) : bflo(wd);
;                     a += w[j][e] * xv;
	v_pk_fma_f32 v[90:91], v[24:25], v[114:115], v[90:91]

; DEV float bflo(unsigned u) { return __uint_as_float(u << 16); }
; DEV float bfhi(unsigned u) { return __uint_as_float(u & 0xffff0000u); }
; DEV void gdn_prep_chunk(const Params& p, int item, unsigned char* lds) {
;     ...
;                 for (int j = 0; j < 4; ++j) {
;                     const uint4 u = raw[r + j];
;                     const unsigned wd = (e < 2 ? u.x : (e < 4 ? u.y : (e < 6 ? u.z : u.w)));
;                     const float xv = (e & 1) ? bfhi(wd) : bflo(wd);
;                     a += w[j][e] * xv;
	v_pk_fma_f32 v[90:91], v[28:29], v[94:95], v[90:91]

; DEV float bflo(unsigned u) { return __uint_as_float(u << 16); }
; DEV float bfhi(unsigned u) { return __uint_as_float(u & 0xffff0000u); }
; DEV void gdn_prep_chunk(const Params& p, int item, unsigned char* lds) {
;     ...
;                 for (int j = 0; j < 4; ++j) {
;                     const uint4 u = raw[r + j];
;                     const unsigned wd = (e < 2 ? u.x : (e < 4 ? u.y : (e < 6 ? u.z : u.w)));
;                     const float xv = (e & 1) ? bfhi(wd) : bflo(wd);
;                     a += w[j][e] * xv;
	v_pk_fma_f32 v[90:91], v[32:33], v[102:103], v[90:91]

; DEV float silu_f(float x) { return x / (1.f + __expf(-x)); }
; DEV void gdn_prep_chunk(const Params& p, int item, unsigned char* lds) {
;     ...
;                 y[e] = silu_f(a); ss += y[e] * y[e];
	v_mul_f32_e32 v100, 0xbfb8aa3b, v90
	v_mul_f32_e32 v101, 0xbfb8aa3b, v91
	v_exp_f32_e32 v100, v100
	v_exp_f32_e32 v101, v101


; DEV float bflo(unsigned u) { return __uint_as_float(u << 16); }
; DEV float bfhi(unsigned u) { return __uint_as_float(u & 0xffff0000u); }
; DEV float silu_f(float x) { return x / (1.f + __expf(-x)); }
; DEV void gdn_prep_chunk(const Params& p, int item, unsigned char* lds) {
;     ...
;                 for (int j = 0; j < 4; ++j) {
;                     const uint4 u = raw[r + j];
;                     const unsigned wd = (e < 2 ? u.x : (e < 4 ? u.y : (e < 6 ? u.z : u.w)));
;                     const float xv = (e & 1) ? bfhi(wd) : bflo(wd);
;                     a += w[j][e] * xv;
;     ...
;                 y[e] = silu_f(a); ss += y[e] * y[e];
	v_rcp_f32_e32 v117, v116
	s_nop 0
	v_mul_f32_e32 v108, v108, v117
	v_pk_add_f32 v[118:119], v[100:101], 1.0 op_sel_hi:[1,0]
	v_pk_fma_f32 v[122:123], v[6:7], v[106:107], v[122:123]


; DEV float bflo(unsigned u) { return __uint_as_float(u << 16); }
; DEV float bfhi(unsigned u) { return __uint_as_float(u & 0xffff0000u); }
; DEV void gdn_prep_chunk(const Params& p, int item, unsigned char* lds) {
;     ...
;                 for (int j = 0; j < 4; ++j) {
;                     const uint4 u = raw[r + j];
;                     const unsigned wd = (e < 2 ? u.x : (e < 4 ? u.y : (e < 6 ? u.z : u.w)));
;                     const float xv = (e & 1) ? bfhi(wd) : bflo(wd);
;                     a += w[j][e] * xv;
	v_pk_fma_f32 v[122:123], v[10:11], v[98:99], v[122:123]


; DEV float bflo(unsigned u) { return __uint_as_float(u << 16); }
; DEV float bfhi(unsigned u) { return __uint_as_float(u & 0xffff0000u); }
; DEV float silu_f(float x) { return x / (1.f + __expf(-x)); }
; DEV void gdn_prep_chunk(const Params& p, int item, unsigned char* lds) {
;     ...
;                     const float xv = (e & 1) ? bfhi(wd) : bflo(wd);
;     ...
;                 y[e] = silu_f(a); ss += y[e] * y[e];
	v_rcp_f32_e32 v100, v119
	s_nop 0
	v_mul_f32_e32 v117, v91, v100
	v_lshlrev_b32_e32 v100, 16, v92
	v_and_b32_e32 v101, 0xffff0000, v92

; DEV float bflo(unsigned u) { return __uint_as_float(u << 16); }
; DEV float bfhi(unsigned u) { return __uint_as_float(u & 0xffff0000u); }
; DEV void gdn_prep_chunk(const Params& p, int item, unsigned char* lds) {
;     ...
;                 for (int j = 0; j < 4; ++j) {
;                     const uint4 u = raw[r + j];
;                     const unsigned wd = (e < 2 ? u.x : (e < 4 ? u.y : (e < 6 ? u.z : u.w)));
;                     const float xv = (e & 1) ? bfhi(wd) : bflo(wd);
;                     a += w[j][e] * xv;
	v_pk_fma_f32 v[122:123], v[14:15], v[100:101], v[122:123]

; DEV float silu_f(float x) { return x / (1.f + __expf(-x)); }
; DEV void gdn_prep_chunk(const Params& p, int item, unsigned char* lds) {
;     ...
;                 y[e] = silu_f(a); ss += y[e] * y[e];
	v_mul_f32_e32 v92, 0xbfb8aa3b, v122
	v_exp_f32_e32 v124, v92
	v_mul_f32_e32 v92, 0xbfb8aa3b, v123
	v_exp_f32_e32 v125, v92


; DEV float silu_f(float x) { return x / (1.f + __expf(-x)); }
; DEV void gdn_prep_chunk(const Params& p, int item, unsigned char* lds) {
;     ...
;                 y[e] = silu_f(a); ss += y[e] * y[e];
	s_nop 0
	v_pk_add_f32 v[124:125], v[124:125], 1.0 op_sel_hi:[1,0]


; DEV float silu_f(float x) { return x / (1.f + __expf(-x)); }
; DEV void gdn_prep_chunk(const Params& p, int item, unsigned char* lds) {
;     ...
;                 y[e] = silu_f(a); ss += y[e] * y[e];
	v_rcp_f32_e32 v91, v118
	s_nop 0
	v_mul_f32_e32 v116, v90, v91


; DEV float silu_f(float x) { return x / (1.f + __expf(-x)); }
; DEV void gdn_prep_chunk(const Params& p, int item, unsigned char* lds) {
;     ...
;                 y[e] = silu_f(a); ss += y[e] * y[e];
	v_rcp_f32_e32 v90, v125
	s_nop 0
	v_mul_f32_e32 v123, v123, v90


; DEV float bflo(unsigned u) { return __uint_as_float(u << 16); }
; DEV float bfhi(unsigned u) { return __uint_as_float(u & 0xffff0000u); }
; DEV void gdn_prep_chunk(const Params& p, int item, unsigned char* lds) {
;     ...
;             for (int e = 0; e < 8; ++e) {
;                 float a = 0.f;
; #pragma unroll
;                 for (int j = 0; j < 4; ++j) {
;                     const uint4 u = raw[r + j];
;                     const unsigned wd = (e < 2 ? u.x : (e < 4 ? u.y : (e < 6 ? u.z : u.w)));
;                     const float xv = (e & 1) ? bfhi(wd) : bflo(wd);
;                     a += w[j][e] * xv;
	v_lshlrev_b32_e32 v90, 16, v93
	v_and_b32_e32 v91, 0xffff0000, v93
	v_pk_fma_f32 v[92:93], v[4:5], v[126:127], 0 op_sel_hi:[1,1,0]

; DEV float bflo(unsigned u) { return __uint_as_float(u << 16); }
; DEV float bfhi(unsigned u) { return __uint_as_float(u & 0xffff0000u); }
; DEV void gdn_prep_chunk(const Params& p, int item, unsigned char* lds) {
;     ...
;                 for (int j = 0; j < 4; ++j) {
;                     const uint4 u = raw[r + j];
;                     const unsigned wd = (e < 2 ? u.x : (e < 4 ? u.y : (e < 6 ? u.z : u.w)));
;                     const float xv = (e & 1) ? bfhi(wd) : bflo(wd);
;                     a += w[j][e] * xv;
	v_pk_fma_f32 v[92:93], v[8:9], v[120:121], v[92:93]

; DEV float bflo(unsigned u) { return __uint_as_float(u << 16); }
; DEV float bfhi(unsigned u) { return __uint_as_float(u & 0xffff0000u); }
; DEV void gdn_prep_chunk(const Params& p, int item, unsigned char* lds) {
;     ...
;                 for (int j = 0; j < 4; ++j) {
;                     const uint4 u = raw[r + j];
;                     const unsigned wd = (e < 2 ? u.x : (e < 4 ? u.y : (e < 6 ? u.z : u.w)));
;                     const float xv = (e & 1) ? bfhi(wd) : bflo(wd);
;                     a += w[j][e] * xv;
	v_pk_fma_f32 v[92:93], v[12:13], v[96:97], v[92:93]

; DEV float bflo(unsigned u) { return __uint_as_float(u << 16); }
; DEV float bfhi(unsigned u) { return __uint_as_float(u & 0xffff0000u); }
; DEV void gdn_prep_chunk(const Params& p, int item, unsigned char* lds) {
;     ...
;                 for (int j = 0; j < 4; ++j) {
;                     const uint4 u = raw[r + j];
;                     const unsigned wd = (e < 2 ? u.x : (e < 4 ? u.y : (e < 6 ? u.z : u.w)));
;                     const float xv = (e & 1) ? bfhi(wd) : bflo(wd);
;                     a += w[j][e] * xv;
	v_pk_fma_f32 v[92:93], v[16:17], v[90:91], v[92:93]

; DEV float silu_f(float x) { return x / (1.f + __expf(-x)); }
; DEV void gdn_prep_chunk(const Params& p, int item, unsigned char* lds) {
;     ...
;                 y[e] = silu_f(a); ss += y[e] * y[e];
	v_mul_f32_e32 v118, 0xbfb8aa3b, v92
	v_mul_f32_e32 v119, 0xbfb8aa3b, v93
	v_exp_f32_e32 v118, v118
	v_exp_f32_e32 v119, v119


; DEV float silu_f(float x) { return x / (1.f + __expf(-x)); }
; DEV void gdn_prep_chunk(const Params& p, int item, unsigned char* lds) {
;     ...
;                 y[e] = silu_f(a); ss += y[e] * y[e];
	v_rcp_f32_e32 v125, v124
	s_nop 0
	v_mul_f32_e32 v122, v122, v125
	v_pk_add_f32 v[118:119], v[118:119], 1.0 op_sel_hi:[1,0]
	s_nop 0


; DEV float silu_f(float x) { return x / (1.f + __expf(-x)); }
; DEV void gdn_prep_chunk(const Params& p, int item, unsigned char* lds) {
;     ...
;                 y[e] = silu_f(a); ss += y[e] * y[e];
	s_nop 0


; DEV float silu_f(float x) { return x / (1.f + __expf(-x)); }
; DEV void gdn_prep_chunk(const Params& p, int item, unsigned char* lds) {
;     ...
;                 y[e] = silu_f(a); ss += y[e] * y[e];
	v_rcp_f32_e32 v124, v119
	s_nop 0
	v_mul_f32_e32 v93, v93, v124


; DEV float silu_f(float x) { return x / (1.f + __expf(-x)); }
; DEV void gdn_prep_chunk(const Params& p, int item, unsigned char* lds) {
;     ...
;                 y[e] = silu_f(a); ss += y[e] * y[e];
;             }
;             if (mat < 2) {
;                 ss += __shfl_xor(ss, 1); ss += __shfl_xor(ss, 2); ss += __shfl_xor(ss, 4); ss += __shfl_xor(ss, 8);
	v_rcp_f32_e32 v119, v118
	s_nop 0
	v_mul_f32_e32 v92, v92, v119
	s_and_saveexec_b64 s[36:37], s[6:7]
	s_cbranch_execz .LBB0_476
	v_pk_mul_f32 v[118:119], v[108:109], v[108:109]
	v_pk_mul_f32 v[124:125], v[116:117], v[116:117]
	v_add_f32_e32 v118, v118, v119
	v_add_f32_e32 v118, v118, v124
	v_pk_mul_f32 v[126:127], v[122:123], v[122:123]
	v_add_f32_e32 v118, v125, v118
	v_and_b32_e32 v124, 64, v182
	v_add_f32_e32 v118, v126, v118

; DEV float silu_f(float x) { return x / (1.f + __expf(-x)); }
; DEV void gdn_prep_chunk(const Params& p, int item, unsigned char* lds) {
;     ...
;                 y[e] = silu_f(a); ss += y[e] * y[e];
;             }
;             if (mat < 2) {
;                 ss += __shfl_xor(ss, 1); ss += __shfl_xor(ss, 2); ss += __shfl_xor(ss, 4); ss += __shfl_xor(ss, 8);
	v_add_u32_e32 v124, 64, v124
	v_pk_mul_f32 v[128:129], v[92:93], v[92:93]
	v_add_f32_e32 v118, v127, v118

; DEV float silu_f(float x) { return x / (1.f + __expf(-x)); }
; DEV void gdn_prep_chunk(const Params& p, int item, unsigned char* lds) {
;     ...
;                 y[e] = silu_f(a); ss += y[e] * y[e];
;             }
;             if (mat < 2) {
;                 ss += __shfl_xor(ss, 1); ss += __shfl_xor(ss, 2); ss += __shfl_xor(ss, 4); ss += __shfl_xor(ss, 8);
	v_add_f32_e32 v118, v128, v118
	v_add_f32_e32 v118, v129, v118


; DEV void gdn_prep_chunk(const Params& p, int item, unsigned char* lds) {
;     ...
;                 ss += __shfl_xor(ss, 1); ss += __shfl_xor(ss, 2); ss += __shfl_xor(ss, 4); ss += __shfl_xor(ss, 8);
	s_waitcnt lgkmcnt(0)
	s_nop 1
	v_add_f32_dpp v118, v118, v118 quad_perm:[1,0,3,2] row_mask:0xf bank_mask:0xf


; DEV void gdn_prep_chunk(const Params& p, int item, unsigned char* lds) {
;     ...
;                 ss += __shfl_xor(ss, 1); ss += __shfl_xor(ss, 2); ss += __shfl_xor(ss, 4); ss += __shfl_xor(ss, 8);
	s_nop 1


; DEV void gdn_prep_chunk(const Params& p, int item, unsigned char* lds) {
;     ...
;                 ss += __shfl_xor(ss, 1); ss += __shfl_xor(ss, 2); ss += __shfl_xor(ss, 4); ss += __shfl_xor(ss, 8);
	s_waitcnt lgkmcnt(0)
	s_nop 1
	v_add_f32_dpp v118, v118, v118 quad_perm:[2,3,0,1] row_mask:0xf bank_mask:0xf


; DEV void gdn_prep_chunk(const Params& p, int item, unsigned char* lds) {
;     ...
;                 ss += __shfl_xor(ss, 1); ss += __shfl_xor(ss, 2); ss += __shfl_xor(ss, 4); ss += __shfl_xor(ss, 8);
	s_nop 1


; DEV void gdn_prep_chunk(const Params& p, int item, unsigned char* lds) {
;     ...
;                 ss += __shfl_xor(ss, 1); ss += __shfl_xor(ss, 2); ss += __shfl_xor(ss, 4); ss += __shfl_xor(ss, 8);
	s_waitcnt lgkmcnt(0)
	s_nop 1
	v_add_f32_dpp v118, v118, v118 row_half_mirror row_mask:0xf bank_mask:0xf


; DEV void gdn_prep_chunk(const Params& p, int item, unsigned char* lds) {
;     ...
;                 ss += __shfl_xor(ss, 1); ss += __shfl_xor(ss, 2); ss += __shfl_xor(ss, 4); ss += __shfl_xor(ss, 8);
	s_nop 1


; DEV unsigned cvt_pk_bf16(float lo, float hi) { const f32x2_t v = {lo, hi}; const bf16x2_t b = __builtin_convertvector(v, bf16x2_t); return __builtin_bit_cast(unsigned, b); }
; DEV float bflo(unsigned u) { return __uint_as_float(u << 16); }
; DEV float bfhi(unsigned u) { return __uint_as_float(u & 0xffff0000u); }
; DEV float silu_f(float x) { return x / (1.f + __expf(-x)); }
; DEV void gdn_prep_chunk(const Params& p, int item, unsigned char* lds) {
;     ...
;             for (int e = 0; e < 8; ++e) {
;                 float a = 0.f;
; #pragma unroll
;                 for (int j = 0; j < 4; ++j) {
;                     const uint4 u = raw[r + j];
;                     const unsigned wd = (e < 2 ? u.x : (e < 4 ? u.y : (e < 6 ? u.z : u.w)));
;                     const float xv = (e & 1) ? bfhi(wd) : bflo(wd);
;                     a += w[j][e] * xv;
;                 }
;                 y[e] = silu_f(a); ss += y[e] * y[e];
;     ...
;                 ss += __shfl_xor(ss, 1); ss += __shfl_xor(ss, 2); ss += __shfl_xor(ss, 4); ss += __shfl_xor(ss, 8);
;                 float inv = rsqrtf(ss + EPS); if (mat == 0) inv *= 0.08838834764831845f;
; #pragma unroll
;                 for (int e = 0; e < 8; ++e) y[e] *= inv;
;             }
;             uint4 o; o.x = cvt_pk_bf16(y[0], y[1]); o.y = cvt_pk_bf16(y[2], y[3]); o.z = cvt_pk_bf16(y[4], y[5]); o.w = cvt_pk_bf16(y[6], y[7]);
	s_waitcnt lgkmcnt(0)
	s_nop 1
	v_add_f32_dpp v118, v118, v118 row_mirror row_mask:0xf bank_mask:0xf
	v_add_f32_e32 v118, 0x358637bd, v118
	v_mul_f32_e32 v119, 0x4b800000, v118
	v_cmp_gt_f32_e32 vcc, s56, v118
	s_nop 1
	v_cndmask_b32_e32 v118, v118, v119, vcc
	v_rsq_f32_e32 v118, v118
	s_nop 0
	v_mul_f32_e32 v119, 0x45800000, v118
	v_cndmask_b32_e32 v118, v118, v119, vcc
	v_mul_f32_e32 v119, 0x3db504f3, v118
	v_cndmask_b32_e64 v118, v118, v119, s[4:5]
	v_pk_mul_f32 v[108:109], v[108:109], v[118:119] op_sel_hi:[1,0]
	v_pk_mul_f32 v[116:117], v[116:117], v[118:119] op_sel_hi:[1,0]
	v_pk_mul_f32 v[122:123], v[122:123], v[118:119] op_sel_hi:[1,0]
	v_pk_mul_f32 v[92:93], v[92:93], v[118:119] op_sel_hi:[1,0]
.LBB0_476:
	s_or_b64 exec, exec, s[36:37]
	v_cvt_pk_bf16_f32 v124, v108, v109
	v_pk_fma_f32 v[108:109], v[18:19], v[112:113], 0 op_sel_hi:[1,1,0]
	s_waitcnt vmcnt(13)
	v_lshlrev_b32_e32 v118, 16, v86
	v_pk_fma_f32 v[108:109], v[22:23], v[110:111], v[108:109]
	v_and_b32_e32 v119, 0xffff0000, v86
	v_pk_fma_f32 v[108:109], v[26:27], v[104:105], v[108:109]
	v_cvt_pk_bf16_f32 v127, v92, v93
	v_pk_fma_f32 v[108:109], v[30:31], v[118:119], v[108:109]
	v_mul_u32_u24_e32 v128, 0x110, v133
	v_mul_f32_e32 v86, 0xbfb8aa3b, v108
	v_exp_f32_e32 v112, v86
	v_mul_f32_e32 v86, 0xbfb8aa3b, v109
	v_exp_f32_e32 v113, v86
	v_cvt_pk_bf16_f32 v126, v122, v123
	v_add_u32_e32 v122, 0x110, v128
	v_cvt_pk_bf16_f32 v125, v116, v117
	v_pk_add_f32 v[92:93], v[112:113], 1.0 op_sel_hi:[1,0]
	v_add_u32_e32 v113, v132, v122


; DEV void gdn_prep_chunk(const Params& p, int item, unsigned char* lds) {
;     ...
;             *(uint4*)(dst + (tl0 + r) * QS + cv * 8) = o;
	ds_write_b128 v113, v[124:127]


; DEV float silu_f(float x) { return x / (1.f + __expf(-x)); }
; DEV void gdn_prep_chunk(const Params& p, int item, unsigned char* lds) {
;     ...
;                 y[e] = silu_f(a); ss += y[e] * y[e];
	v_rcp_f32_e32 v86, v93
	s_nop 0
	v_mul_f32_e32 v93, v109, v86


; DEV float bflo(unsigned u) { return __uint_as_float(u << 16); }
; DEV float bfhi(unsigned u) { return __uint_as_float(u & 0xffff0000u); }
; DEV void gdn_prep_chunk(const Params& p, int item, unsigned char* lds) {
;     ...
;             for (int e = 0; e < 8; ++e) {
;                 float a = 0.f;
; #pragma unroll
;                 for (int j = 0; j < 4; ++j) {
;                     const uint4 u = raw[r + j];
;                     const unsigned wd = (e < 2 ? u.x : (e < 4 ? u.y : (e < 6 ? u.z : u.w)));
;                     const float xv = (e & 1) ? bfhi(wd) : bflo(wd);
;                     a += w[j][e] * xv;
	v_lshlrev_b32_e32 v116, 16, v87
	v_and_b32_e32 v117, 0xffff0000, v87
	v_pk_fma_f32 v[86:87], v[20:21], v[114:115], 0 op_sel_hi:[1,1,0]

; DEV float bflo(unsigned u) { return __uint_as_float(u << 16); }
; DEV float bfhi(unsigned u) { return __uint_as_float(u & 0xffff0000u); }
; DEV void gdn_prep_chunk(const Params& p, int item, unsigned char* lds) {
;     ...
;                 for (int j = 0; j < 4; ++j) {
;                     const uint4 u = raw[r + j];
;                     const unsigned wd = (e < 2 ? u.x : (e < 4 ? u.y : (e < 6 ? u.z : u.w)));
;                     const float xv = (e & 1) ? bfhi(wd) : bflo(wd);
;                     a += w[j][e] * xv;
	v_pk_fma_f32 v[86:87], v[24:25], v[94:95], v[86:87]

; DEV float bflo(unsigned u) { return __uint_as_float(u << 16); }
; DEV float bfhi(unsigned u) { return __uint_as_float(u & 0xffff0000u); }
; DEV void gdn_prep_chunk(const Params& p, int item, unsigned char* lds) {
;     ...
;                 for (int j = 0; j < 4; ++j) {
;                     const uint4 u = raw[r + j];
;                     const unsigned wd = (e < 2 ? u.x : (e < 4 ? u.y : (e < 6 ? u.z : u.w)));
;                     const float xv = (e & 1) ? bfhi(wd) : bflo(wd);
;                     a += w[j][e] * xv;
	v_pk_fma_f32 v[86:87], v[28:29], v[102:103], v[86:87]

; DEV float bflo(unsigned u) { return __uint_as_float(u << 16); }
; DEV float bfhi(unsigned u) { return __uint_as_float(u & 0xffff0000u); }
; DEV void gdn_prep_chunk(const Params& p, int item, unsigned char* lds) {
;     ...
;                 for (int j = 0; j < 4; ++j) {
;                     const uint4 u = raw[r + j];
;                     const unsigned wd = (e < 2 ? u.x : (e < 4 ? u.y : (e < 6 ? u.z : u.w)));
;                     const float xv = (e & 1) ? bfhi(wd) : bflo(wd);
;                     a += w[j][e] * xv;
	v_pk_fma_f32 v[86:87], v[32:33], v[116:117], v[86:87]

; DEV float silu_f(float x) { return x / (1.f + __expf(-x)); }
; DEV void gdn_prep_chunk(const Params& p, int item, unsigned char* lds) {
;     ...
;                 y[e] = silu_f(a); ss += y[e] * y[e];
	v_mul_f32_e32 v112, 0xbfb8aa3b, v86
	v_mul_f32_e32 v113, 0xbfb8aa3b, v87
	v_exp_f32_e32 v112, v112
	v_exp_f32_e32 v113, v113


; DEV float bflo(unsigned u) { return __uint_as_float(u << 16); }
; DEV float bfhi(unsigned u) { return __uint_as_float(u & 0xffff0000u); }
; DEV float silu_f(float x) { return x / (1.f + __expf(-x)); }
; DEV void gdn_prep_chunk(const Params& p, int item, unsigned char* lds) {
;     ...
;                 for (int j = 0; j < 4; ++j) {
;                     const uint4 u = raw[r + j];
;                     const unsigned wd = (e < 2 ? u.x : (e < 4 ? u.y : (e < 6 ? u.z : u.w)));
;                     const float xv = (e & 1) ? bfhi(wd) : bflo(wd);
;                     a += w[j][e] * xv;
;     ...
;                 y[e] = silu_f(a); ss += y[e] * y[e];
	v_rcp_f32_e32 v109, v92
	s_nop 0
	v_mul_f32_e32 v92, v108, v109
	v_pk_add_f32 v[112:113], v[112:113], 1.0 op_sel_hi:[1,0]
	v_pk_fma_f32 v[106:107], v[2:3], v[106:107], 0 op_sel_hi:[1,1,0]


; DEV float bflo(unsigned u) { return __uint_as_float(u << 16); }
; DEV float bfhi(unsigned u) { return __uint_as_float(u & 0xffff0000u); }
; DEV void gdn_prep_chunk(const Params& p, int item, unsigned char* lds) {
;     ...
;                 for (int j = 0; j < 4; ++j) {
;                     const uint4 u = raw[r + j];
;                     const unsigned wd = (e < 2 ? u.x : (e < 4 ? u.y : (e < 6 ? u.z : u.w)));
;                     const float xv = (e & 1) ? bfhi(wd) : bflo(wd);
;                     a += w[j][e] * xv;
	v_pk_fma_f32 v[106:107], v[6:7], v[98:99], v[106:107]


; DEV float bflo(unsigned u) { return __uint_as_float(u << 16); }
; DEV float bfhi(unsigned u) { return __uint_as_float(u & 0xffff0000u); }
; DEV float silu_f(float x) { return x / (1.f + __expf(-x)); }
; DEV void gdn_prep_chunk(const Params& p, int item, unsigned char* lds) {
;     ...
;                 for (int j = 0; j < 4; ++j) {
;                     const uint4 u = raw[r + j];
;                     const unsigned wd = (e < 2 ? u.x : (e < 4 ? u.y : (e < 6 ? u.z : u.w)));
;                     const float xv = (e & 1) ? bfhi(wd) : bflo(wd);
;                     a += w[j][e] * xv;
;                 }
;                 y[e] = silu_f(a); ss += y[e] * y[e];
	v_lshlrev_b32_e32 v114, 16, v88
	v_and_b32_e32 v115, 0xffff0000, v88
	v_pk_fma_f32 v[106:107], v[10:11], v[100:101], v[106:107]
	v_rcp_f32_e32 v108, v113
	s_nop 0
	v_mul_f32_e32 v87, v87, v108
	v_pk_fma_f32 v[106:107], v[14:15], v[114:115], v[106:107]

; DEV float silu_f(float x) { return x / (1.f + __expf(-x)); }
; DEV void gdn_prep_chunk(const Params& p, int item, unsigned char* lds) {
;     ...
;                 y[e] = silu_f(a); ss += y[e] * y[e];
	v_mul_f32_e32 v88, 0xbfb8aa3b, v106

; DEV float silu_f(float x) { return x / (1.f + __expf(-x)); }
; DEV void gdn_prep_chunk(const Params& p, int item, unsigned char* lds) {
;     ...
;                 y[e] = silu_f(a); ss += y[e] * y[e];
	v_exp_f32_e32 v108, v88
	v_mul_f32_e32 v88, 0xbfb8aa3b, v107
	v_exp_f32_e32 v109, v88


; DEV float silu_f(float x) { return x / (1.f + __expf(-x)); }
; DEV void gdn_prep_chunk(const Params& p, int item, unsigned char* lds) {
;     ...
;                 y[e] = silu_f(a); ss += y[e] * y[e];
	s_nop 0
	v_pk_add_f32 v[108:109], v[108:109], 1.0 op_sel_hi:[1,0]


; DEV float silu_f(float x) { return x / (1.f + __expf(-x)); }
; DEV void gdn_prep_chunk(const Params& p, int item, unsigned char* lds) {
;     ...
;                 y[e] = silu_f(a); ss += y[e] * y[e];
	v_rcp_f32_e32 v88, v112
	s_nop 0
	v_mul_f32_e32 v86, v86, v88


; DEV float silu_f(float x) { return x / (1.f + __expf(-x)); }
; DEV void gdn_prep_chunk(const Params& p, int item, unsigned char* lds) {
;     ...
;                 y[e] = silu_f(a); ss += y[e] * y[e];
	v_rcp_f32_e32 v88, v109
	s_nop 0
	v_mul_f32_e32 v107, v107, v88


; DEV float bflo(unsigned u) { return __uint_as_float(u << 16); }
; DEV float bfhi(unsigned u) { return __uint_as_float(u & 0xffff0000u); }
; DEV void gdn_prep_chunk(const Params& p, int item, unsigned char* lds) {
;     ...
;             for (int e = 0; e < 8; ++e) {
;                 float a = 0.f;
; #pragma unroll
;                 for (int j = 0; j < 4; ++j) {
;                     const uint4 u = raw[r + j];
;                     const unsigned wd = (e < 2 ? u.x : (e < 4 ? u.y : (e < 6 ? u.z : u.w)));
;                     const float xv = (e & 1) ? bfhi(wd) : bflo(wd);
;                     a += w[j][e] * xv;
	v_lshlrev_b32_e32 v112, 16, v89
	v_and_b32_e32 v113, 0xffff0000, v89
	v_pk_fma_f32 v[88:89], v[4:5], v[120:121], 0 op_sel_hi:[1,1,0]

; DEV float bflo(unsigned u) { return __uint_as_float(u << 16); }
; DEV float bfhi(unsigned u) { return __uint_as_float(u & 0xffff0000u); }
; DEV void gdn_prep_chunk(const Params& p, int item, unsigned char* lds) {
;     ...
;                 for (int j = 0; j < 4; ++j) {
;                     const uint4 u = raw[r + j];
;                     const unsigned wd = (e < 2 ? u.x : (e < 4 ? u.y : (e < 6 ? u.z : u.w)));
;                     const float xv = (e & 1) ? bfhi(wd) : bflo(wd);
;                     a += w[j][e] * xv;
	v_pk_fma_f32 v[88:89], v[8:9], v[96:97], v[88:89]

; DEV float bflo(unsigned u) { return __uint_as_float(u << 16); }
; DEV float bfhi(unsigned u) { return __uint_as_float(u & 0xffff0000u); }
; DEV void gdn_prep_chunk(const Params& p, int item, unsigned char* lds) {
;     ...
;                 for (int j = 0; j < 4; ++j) {
;                     const uint4 u = raw[r + j];
;                     const unsigned wd = (e < 2 ? u.x : (e < 4 ? u.y : (e < 6 ? u.z : u.w)));
;                     const float xv = (e & 1) ? bfhi(wd) : bflo(wd);
;                     a += w[j][e] * xv;
	v_pk_fma_f32 v[88:89], v[12:13], v[90:91], v[88:89]

; DEV float bflo(unsigned u) { return __uint_as_float(u << 16); }
; DEV float bfhi(unsigned u) { return __uint_as_float(u & 0xffff0000u); }
; DEV void gdn_prep_chunk(const Params& p, int item, unsigned char* lds) {
;     ...
;                 for (int j = 0; j < 4; ++j) {
;                     const uint4 u = raw[r + j];
;                     const unsigned wd = (e < 2 ? u.x : (e < 4 ? u.y : (e < 6 ? u.z : u.w)));
;                     const float xv = (e & 1) ? bfhi(wd) : bflo(wd);
;                     a += w[j][e] * xv;
	v_pk_fma_f32 v[88:89], v[16:17], v[112:113], v[88:89]

; DEV float silu_f(float x) { return x / (1.f + __expf(-x)); }
; DEV void gdn_prep_chunk(const Params& p, int item, unsigned char* lds) {
;     ...
;                 y[e] = silu_f(a); ss += y[e] * y[e];
	v_mul_f32_e32 v120, 0xbfb8aa3b, v88
	v_mul_f32_e32 v121, 0xbfb8aa3b, v89
	v_exp_f32_e32 v120, v120
	v_exp_f32_e32 v121, v121


; DEV float silu_f(float x) { return x / (1.f + __expf(-x)); }
; DEV void gdn_prep_chunk(const Params& p, int item, unsigned char* lds) {
;     ...
;                 y[e] = silu_f(a); ss += y[e] * y[e];
	v_rcp_f32_e32 v109, v108
	s_nop 0
	v_mul_f32_e32 v106, v106, v109
	v_pk_add_f32 v[120:121], v[120:121], 1.0 op_sel_hi:[1,0]
	s_nop 0


; DEV float silu_f(float x) { return x / (1.f + __expf(-x)); }
; DEV void gdn_prep_chunk(const Params& p, int item, unsigned char* lds) {
;     ...
;                 y[e] = silu_f(a); ss += y[e] * y[e];
	s_nop 0


; DEV float silu_f(float x) { return x / (1.f + __expf(-x)); }
; DEV void gdn_prep_chunk(const Params& p, int item, unsigned char* lds) {
;     ...
;                 y[e] = silu_f(a); ss += y[e] * y[e];
	v_rcp_f32_e32 v108, v121
	s_nop 0
	v_mul_f32_e32 v89, v89, v108


; DEV float silu_f(float x) { return x / (1.f + __expf(-x)); }
; DEV void gdn_prep_chunk(const Params& p, int item, unsigned char* lds) {
;     ...
;                 y[e] = silu_f(a); ss += y[e] * y[e];
;             }
;             if (mat < 2) {
;                 ss += __shfl_xor(ss, 1); ss += __shfl_xor(ss, 2); ss += __shfl_xor(ss, 4); ss += __shfl_xor(ss, 8);
	v_rcp_f32_e32 v108, v120
	s_nop 0
	v_mul_f32_e32 v88, v88, v108
	s_and_saveexec_b64 s[36:37], s[6:7]
	s_cbranch_execz .LBB0_478
	v_pk_mul_f32 v[108:109], v[92:93], v[92:93]
	v_pk_mul_f32 v[120:121], v[86:87], v[86:87]
	v_add_f32_e32 v108, v108, v109
	v_add_f32_e32 v108, v108, v120
	v_pk_mul_f32 v[124:125], v[106:107], v[106:107]
	v_add_f32_e32 v108, v121, v108
	v_and_b32_e32 v120, 64, v182
	v_add_f32_e32 v108, v124, v108

; DEV float silu_f(float x) { return x / (1.f + __expf(-x)); }
; DEV void gdn_prep_chunk(const Params& p, int item, unsigned char* lds) {
;     ...
;                 y[e] = silu_f(a); ss += y[e] * y[e];
;             }
;             if (mat < 2) {
;                 ss += __shfl_xor(ss, 1); ss += __shfl_xor(ss, 2); ss += __shfl_xor(ss, 4); ss += __shfl_xor(ss, 8);
	v_add_u32_e32 v120, 64, v120
	v_pk_mul_f32 v[126:127], v[88:89], v[88:89]
	v_add_f32_e32 v108, v125, v108

; DEV float silu_f(float x) { return x / (1.f + __expf(-x)); }
; DEV void gdn_prep_chunk(const Params& p, int item, unsigned char* lds) {
;     ...
;                 y[e] = silu_f(a); ss += y[e] * y[e];
;             }
;             if (mat < 2) {
;                 ss += __shfl_xor(ss, 1); ss += __shfl_xor(ss, 2); ss += __shfl_xor(ss, 4); ss += __shfl_xor(ss, 8);
	v_add_f32_e32 v108, v126, v108
	v_add_f32_e32 v108, v127, v108


; DEV void gdn_prep_chunk(const Params& p, int item, unsigned char* lds) {
;     ...
;                 ss += __shfl_xor(ss, 1); ss += __shfl_xor(ss, 2); ss += __shfl_xor(ss, 4); ss += __shfl_xor(ss, 8);
	s_waitcnt lgkmcnt(0)
	s_nop 1
	v_add_f32_dpp v108, v108, v108 quad_perm:[1,0,3,2] row_mask:0xf bank_mask:0xf


; DEV void gdn_prep_chunk(const Params& p, int item, unsigned char* lds) {
;     ...
;                 ss += __shfl_xor(ss, 1); ss += __shfl_xor(ss, 2); ss += __shfl_xor(ss, 4); ss += __shfl_xor(ss, 8);
	s_nop 1


; DEV void gdn_prep_chunk(const Params& p, int item, unsigned char* lds) {
;     ...
;                 ss += __shfl_xor(ss, 1); ss += __shfl_xor(ss, 2); ss += __shfl_xor(ss, 4); ss += __shfl_xor(ss, 8);
	s_waitcnt lgkmcnt(0)
	s_nop 1
	v_add_f32_dpp v108, v108, v108 quad_perm:[2,3,0,1] row_mask:0xf bank_mask:0xf


; DEV void gdn_prep_chunk(const Params& p, int item, unsigned char* lds) {
;     ...
;                 ss += __shfl_xor(ss, 1); ss += __shfl_xor(ss, 2); ss += __shfl_xor(ss, 4); ss += __shfl_xor(ss, 8);
	s_nop 1


; DEV void gdn_prep_chunk(const Params& p, int item, unsigned char* lds) {
;     ...
;                 ss += __shfl_xor(ss, 1); ss += __shfl_xor(ss, 2); ss += __shfl_xor(ss, 4); ss += __shfl_xor(ss, 8);
	s_waitcnt lgkmcnt(0)
	s_nop 1
	v_add_f32_dpp v108, v108, v108 row_half_mirror row_mask:0xf bank_mask:0xf


; DEV void gdn_prep_chunk(const Params& p, int item, unsigned char* lds) {
;     ...
;                 ss += __shfl_xor(ss, 1); ss += __shfl_xor(ss, 2); ss += __shfl_xor(ss, 4); ss += __shfl_xor(ss, 8);
	s_nop 1


; DEV unsigned cvt_pk_bf16(float lo, float hi) { const f32x2_t v = {lo, hi}; const bf16x2_t b = __builtin_convertvector(v, bf16x2_t); return __builtin_bit_cast(unsigned, b); }
; DEV float bflo(unsigned u) { return __uint_as_float(u << 16); }
; DEV float bfhi(unsigned u) { return __uint_as_float(u & 0xffff0000u); }
; DEV float silu_f(float x) { return x / (1.f + __expf(-x)); }
; DEV void gdn_prep_chunk(const Params& p, int item, unsigned char* lds) {
;     ...
;                 for (int j = 0; j < 4; ++j) {
;                     const uint4 u = raw[r + j];
;                     const unsigned wd = (e < 2 ? u.x : (e < 4 ? u.y : (e < 6 ? u.z : u.w)));
;                     const float xv = (e & 1) ? bfhi(wd) : bflo(wd);
;                     a += w[j][e] * xv;
;                 }
;                 y[e] = silu_f(a); ss += y[e] * y[e];
;             }
;             if (mat < 2) {
;                 ss += __shfl_xor(ss, 1); ss += __shfl_xor(ss, 2); ss += __shfl_xor(ss, 4); ss += __shfl_xor(ss, 8);
;                 float inv = rsqrtf(ss + EPS); if (mat == 0) inv *= 0.08838834764831845f;
; #pragma unroll
;                 for (int e = 0; e < 8; ++e) y[e] *= inv;
;             }
;             uint4 o; o.x = cvt_pk_bf16(y[0], y[1]); o.y = cvt_pk_bf16(y[2], y[3]); o.z = cvt_pk_bf16(y[4], y[5]); o.w = cvt_pk_bf16(y[6], y[7]);
	s_waitcnt lgkmcnt(0)
	s_nop 1
	v_add_f32_dpp v108, v108, v108 row_mirror row_mask:0xf bank_mask:0xf
	v_add_f32_e32 v108, 0x358637bd, v108
	v_mul_f32_e32 v109, 0x4b800000, v108
	v_cmp_gt_f32_e32 vcc, s56, v108
	s_nop 1
	v_cndmask_b32_e32 v108, v108, v109, vcc
	v_rsq_f32_e32 v108, v108
	s_nop 0
	v_mul_f32_e32 v109, 0x45800000, v108
	v_cndmask_b32_e32 v108, v108, v109, vcc
	v_mul_f32_e32 v109, 0x3db504f3, v108
	v_cndmask_b32_e64 v108, v108, v109, s[4:5]
	v_pk_mul_f32 v[92:93], v[92:93], v[108:109] op_sel_hi:[1,0]
	v_pk_mul_f32 v[86:87], v[86:87], v[108:109] op_sel_hi:[1,0]
	v_pk_mul_f32 v[106:107], v[106:107], v[108:109] op_sel_hi:[1,0]
	v_pk_mul_f32 v[88:89], v[88:89], v[108:109] op_sel_hi:[1,0]
.LBB0_478:
	s_or_b64 exec, exec, s[36:37]
	v_cvt_pk_bf16_f32 v124, v92, v93
	v_pk_fma_f32 v[92:93], v[18:19], v[110:111], 0 op_sel_hi:[1,1,0]
	s_waitcnt vmcnt(12)
	v_lshlrev_b32_e32 v108, 16, v82
	v_pk_fma_f32 v[92:93], v[22:23], v[104:105], v[92:93]
	v_and_b32_e32 v109, 0xffff0000, v82
	v_pk_fma_f32 v[92:93], v[26:27], v[118:119], v[92:93]
	v_cvt_pk_bf16_f32 v125, v86, v87
	v_pk_fma_f32 v[92:93], v[30:31], v[108:109], v[92:93]
	v_cvt_pk_bf16_f32 v127, v88, v89
	v_mul_f32_e32 v82, 0xbfb8aa3b, v92
	v_exp_f32_e32 v110, v82
	v_mul_f32_e32 v82, 0xbfb8aa3b, v93
	v_exp_f32_e32 v111, v82
	v_cvt_pk_bf16_f32 v126, v106, v107
	v_pk_add_f32 v[86:87], v[110:111], 1.0 op_sel_hi:[1,0]
	s_nop 0


; DEV void gdn_prep_chunk(const Params& p, int item, unsigned char* lds) {
;     ...
;             *(uint4*)(dst + (tl0 + r) * QS + cv * 8) = o;
	v_add_u32_e32 v110, 0x110, v122
	v_add_u32_e32 v89, v132, v110
	ds_write_b128 v89, v[124:127]


; DEV float silu_f(float x) { return x / (1.f + __expf(-x)); }
	v_rcp_f32_e32 v82, v87
	s_nop 0
	v_mul_f32_e32 v87, v93, v82


; DEV float bflo(unsigned u) { return __uint_as_float(u << 16); }
; DEV float bfhi(unsigned u) { return __uint_as_float(u & 0xffff0000u); }
; DEV void gdn_prep_chunk(const Params& p, int item, unsigned char* lds) {
;     ...
;                 for (int j = 0; j < 4; ++j) {
;                     const uint4 u = raw[r + j];
;                     const unsigned wd = (e < 2 ? u.x : (e < 4 ? u.y : (e < 6 ? u.z : u.w)));
;                     const float xv = (e & 1) ? bfhi(wd) : bflo(wd);
;                     a += w[j][e] * xv;
	v_lshlrev_b32_e32 v106, 16, v83
	v_and_b32_e32 v107, 0xffff0000, v83
	v_pk_fma_f32 v[82:83], v[20:21], v[94:95], 0 op_sel_hi:[1,1,0]

; DEV void gdn_prep_chunk(const Params& p, int item, unsigned char* lds) {
;     ...
;                     a += w[j][e] * xv;
	v_pk_fma_f32 v[82:83], v[24:25], v[102:103], v[82:83]

; DEV void gdn_prep_chunk(const Params& p, int item, unsigned char* lds) {
;     ...
;                     a += w[j][e] * xv;
	v_pk_fma_f32 v[82:83], v[28:29], v[116:117], v[82:83]

; DEV void gdn_prep_chunk(const Params& p, int item, unsigned char* lds) {
;     ...
;                     a += w[j][e] * xv;
	v_pk_fma_f32 v[82:83], v[32:33], v[106:107], v[82:83]

; DEV float silu_f(float x) { return x / (1.f + __expf(-x)); }
	v_mul_f32_e32 v88, 0xbfb8aa3b, v82
	v_mul_f32_e32 v89, 0xbfb8aa3b, v83
	v_exp_f32_e32 v88, v88
	v_exp_f32_e32 v89, v89


; DEV float silu_f(float x) { return x / (1.f + __expf(-x)); }
	v_rcp_f32_e32 v93, v86
	s_nop 0
	v_mul_f32_e32 v86, v92, v93
	v_pk_add_f32 v[88:89], v[88:89], 1.0 op_sel_hi:[1,0]
	s_nop 0


; DEV float silu_f(float x) { return x / (1.f + __expf(-x)); }
	s_nop 0


; DEV float bflo(unsigned u) { return __uint_as_float(u << 16); }
; DEV float bfhi(unsigned u) { return __uint_as_float(u & 0xffff0000u); }
; DEV void gdn_prep_chunk(const Params& p, int item, unsigned char* lds) {
;     ...
;                 for (int j = 0; j < 4; ++j) {
;                     const uint4 u = raw[r + j];
;                     const unsigned wd = (e < 2 ? u.x : (e < 4 ? u.y : (e < 6 ? u.z : u.w)));
;                     const float xv = (e & 1) ? bfhi(wd) : bflo(wd);
;                     a += w[j][e] * xv;
	v_pk_fma_f32 v[94:95], v[2:3], v[98:99], 0 op_sel_hi:[1,1,0]

; DEV void gdn_prep_chunk(const Params& p, int item, unsigned char* lds) {
;     ...
;                     a += w[j][e] * xv;
	v_pk_fma_f32 v[94:95], v[6:7], v[100:101], v[94:95]

; DEV float bflo(unsigned u) { return __uint_as_float(u << 16); }
; DEV float bfhi(unsigned u) { return __uint_as_float(u & 0xffff0000u); }
; DEV float silu_f(float x) { return x / (1.f + __expf(-x)); }
; DEV void gdn_prep_chunk(const Params& p, int item, unsigned char* lds) {
;     ...
;                 for (int j = 0; j < 4; ++j) {
;                     const uint4 u = raw[r + j];
;                     const unsigned wd = (e < 2 ? u.x : (e < 4 ? u.y : (e < 6 ? u.z : u.w)));
;                     const float xv = (e & 1) ? bfhi(wd) : bflo(wd);
;                     a += w[j][e] * xv;
;                 }
;                 y[e] = silu_f(a); ss += y[e] * y[e];
	v_rcp_f32_e32 v92, v89
	s_nop 0
	v_mul_f32_e32 v83, v83, v92
	v_lshlrev_b32_e32 v92, 16, v84
	v_and_b32_e32 v93, 0xffff0000, v84
	v_pk_fma_f32 v[94:95], v[10:11], v[114:115], v[94:95]

; DEV void gdn_prep_chunk(const Params& p, int item, unsigned char* lds) {
;     ...
;                     a += w[j][e] * xv;
	v_pk_fma_f32 v[94:95], v[14:15], v[92:93], v[94:95]

; DEV float silu_f(float x) { return x / (1.f + __expf(-x)); }
	v_mul_f32_e32 v84, 0xbfb8aa3b, v94
	v_exp_f32_e32 v98, v84
	v_mul_f32_e32 v84, 0xbfb8aa3b, v95
	v_exp_f32_e32 v99, v84


; DEV float silu_f(float x) { return x / (1.f + __expf(-x)); }
	s_nop 0
	v_pk_add_f32 v[98:99], v[98:99], 1.0 op_sel_hi:[1,0]


; DEV float silu_f(float x) { return x / (1.f + __expf(-x)); }
	v_rcp_f32_e32 v84, v88
	s_nop 0
	v_mul_f32_e32 v82, v82, v84


; DEV float silu_f(float x) { return x / (1.f + __expf(-x)); }
	v_rcp_f32_e32 v84, v99
	s_nop 0
	v_mul_f32_e32 v95, v95, v84


; DEV float bflo(unsigned u) { return __uint_as_float(u << 16); }
; DEV float bfhi(unsigned u) { return __uint_as_float(u & 0xffff0000u); }
; DEV void gdn_prep_chunk(const Params& p, int item, unsigned char* lds) {
;     ...
;                 for (int j = 0; j < 4; ++j) {
;                     const uint4 u = raw[r + j];
;                     const unsigned wd = (e < 2 ? u.x : (e < 4 ? u.y : (e < 6 ? u.z : u.w)));
;                     const float xv = (e & 1) ? bfhi(wd) : bflo(wd);
;                     a += w[j][e] * xv;
	v_lshlrev_b32_e32 v88, 16, v85
	v_and_b32_e32 v89, 0xffff0000, v85
	v_pk_fma_f32 v[84:85], v[4:5], v[96:97], 0 op_sel_hi:[1,1,0]

; DEV void gdn_prep_chunk(const Params& p, int item, unsigned char* lds) {
;     ...
;                     a += w[j][e] * xv;
	v_pk_fma_f32 v[84:85], v[8:9], v[90:91], v[84:85]

; DEV void gdn_prep_chunk(const Params& p, int item, unsigned char* lds) {
;     ...
;                     a += w[j][e] * xv;
	v_pk_fma_f32 v[84:85], v[12:13], v[112:113], v[84:85]

; DEV void gdn_prep_chunk(const Params& p, int item, unsigned char* lds) {
;     ...
;                     a += w[j][e] * xv;
	v_pk_fma_f32 v[84:85], v[16:17], v[88:89], v[84:85]

; DEV float silu_f(float x) { return x / (1.f + __expf(-x)); }
	v_mul_f32_e32 v96, 0xbfb8aa3b, v84
	v_mul_f32_e32 v97, 0xbfb8aa3b, v85
	v_exp_f32_e32 v96, v96
	v_exp_f32_e32 v97, v97


; DEV float silu_f(float x) { return x / (1.f + __expf(-x)); }
	v_rcp_f32_e32 v99, v98
	s_nop 0
	v_mul_f32_e32 v94, v94, v99
	v_pk_add_f32 v[96:97], v[96:97], 1.0 op_sel_hi:[1,0]
	s_nop 0


; DEV float silu_f(float x) { return x / (1.f + __expf(-x)); }
	s_nop 0


; DEV float silu_f(float x) { return x / (1.f + __expf(-x)); }
	v_rcp_f32_e32 v98, v97
	s_nop 0
	v_mul_f32_e32 v85, v85, v98


; DEV float silu_f(float x) { return x / (1.f + __expf(-x)); }
; DEV void gdn_prep_chunk(const Params& p, int item, unsigned char* lds) {
;     ...
;                 y[e] = silu_f(a); ss += y[e] * y[e];
;             }
;             if (mat < 2) {
;                 ss += __shfl_xor(ss, 1); ss += __shfl_xor(ss, 2); ss += __shfl_xor(ss, 4); ss += __shfl_xor(ss, 8);
	v_rcp_f32_e32 v97, v96
	s_nop 0
	v_mul_f32_e32 v84, v84, v97
	s_and_saveexec_b64 s[36:37], s[6:7]
	s_cbranch_execz .LBB0_480
	v_pk_mul_f32 v[96:97], v[86:87], v[86:87]
	v_pk_mul_f32 v[98:99], v[82:83], v[82:83]
	v_add_f32_e32 v96, v96, v97
	v_add_f32_e32 v96, v96, v98
	v_pk_mul_f32 v[120:121], v[94:95], v[94:95]
	v_add_f32_e32 v96, v99, v96
	v_and_b32_e32 v98, 64, v182
	v_add_f32_e32 v96, v120, v96

; DEV float silu_f(float x) { return x / (1.f + __expf(-x)); }
; DEV void gdn_prep_chunk(const Params& p, int item, unsigned char* lds) {
;     ...
;                 y[e] = silu_f(a); ss += y[e] * y[e];
;             }
;             if (mat < 2) {
;                 ss += __shfl_xor(ss, 1); ss += __shfl_xor(ss, 2); ss += __shfl_xor(ss, 4); ss += __shfl_xor(ss, 8);
	v_add_u32_e32 v98, 64, v98
	v_pk_mul_f32 v[122:123], v[84:85], v[84:85]
	v_add_f32_e32 v96, v121, v96

; DEV float silu_f(float x) { return x / (1.f + __expf(-x)); }
; DEV void gdn_prep_chunk(const Params& p, int item, unsigned char* lds) {
;     ...
;                 y[e] = silu_f(a); ss += y[e] * y[e];
;             }
;             if (mat < 2) {
;                 ss += __shfl_xor(ss, 1); ss += __shfl_xor(ss, 2); ss += __shfl_xor(ss, 4); ss += __shfl_xor(ss, 8);
	v_add_f32_e32 v96, v122, v96
	v_add_f32_e32 v96, v123, v96


; DEV void gdn_prep_chunk(const Params& p, int item, unsigned char* lds) {
;     ...
;                 ss += __shfl_xor(ss, 1); ss += __shfl_xor(ss, 2); ss += __shfl_xor(ss, 4); ss += __shfl_xor(ss, 8);
	s_waitcnt lgkmcnt(0)
	s_nop 1
	v_add_f32_dpp v96, v96, v96 quad_perm:[1,0,3,2] row_mask:0xf bank_mask:0xf


; DEV void gdn_prep_chunk(const Params& p, int item, unsigned char* lds) {
;     ...
;                 ss += __shfl_xor(ss, 1); ss += __shfl_xor(ss, 2); ss += __shfl_xor(ss, 4); ss += __shfl_xor(ss, 8);
	s_nop 1


; DEV void gdn_prep_chunk(const Params& p, int item, unsigned char* lds) {
;     ...
;                 ss += __shfl_xor(ss, 1); ss += __shfl_xor(ss, 2); ss += __shfl_xor(ss, 4); ss += __shfl_xor(ss, 8);
	s_waitcnt lgkmcnt(0)
	s_nop 1
	v_add_f32_dpp v96, v96, v96 quad_perm:[2,3,0,1] row_mask:0xf bank_mask:0xf


; DEV void gdn_prep_chunk(const Params& p, int item, unsigned char* lds) {
;     ...
;                 ss += __shfl_xor(ss, 1); ss += __shfl_xor(ss, 2); ss += __shfl_xor(ss, 4); ss += __shfl_xor(ss, 8);
	s_nop 1


; DEV void gdn_prep_chunk(const Params& p, int item, unsigned char* lds) {
;     ...
;                 ss += __shfl_xor(ss, 1); ss += __shfl_xor(ss, 2); ss += __shfl_xor(ss, 4); ss += __shfl_xor(ss, 8);
	s_waitcnt lgkmcnt(0)
	s_nop 1
	v_add_f32_dpp v96, v96, v96 row_half_mirror row_mask:0xf bank_mask:0xf


; DEV void gdn_prep_chunk(const Params& p, int item, unsigned char* lds) {
;     ...
;                 ss += __shfl_xor(ss, 1); ss += __shfl_xor(ss, 2); ss += __shfl_xor(ss, 4); ss += __shfl_xor(ss, 8);
	s_nop 1


; DEV unsigned cvt_pk_bf16(float lo, float hi) { const f32x2_t v = {lo, hi}; const bf16x2_t b = __builtin_convertvector(v, bf16x2_t); return __builtin_bit_cast(unsigned, b); }
; DEV float bflo(unsigned u) { return __uint_as_float(u << 16); }
; DEV float bfhi(unsigned u) { return __uint_as_float(u & 0xffff0000u); }
; DEV float silu_f(float x) { return x / (1.f + __expf(-x)); }
; DEV void gdn_prep_chunk(const Params& p, int item, unsigned char* lds) {
;     ...
;                 for (int j = 0; j < 4; ++j) {
;                     const uint4 u = raw[r + j];
;                     const unsigned wd = (e < 2 ? u.x : (e < 4 ? u.y : (e < 6 ? u.z : u.w)));
;                     const float xv = (e & 1) ? bfhi(wd) : bflo(wd);
;                     a += w[j][e] * xv;
;                 }
;                 y[e] = silu_f(a); ss += y[e] * y[e];
;             }
;             if (mat < 2) {
;                 ss += __shfl_xor(ss, 1); ss += __shfl_xor(ss, 2); ss += __shfl_xor(ss, 4); ss += __shfl_xor(ss, 8);
;                 float inv = rsqrtf(ss + EPS); if (mat == 0) inv *= 0.08838834764831845f;
; #pragma unroll
;                 for (int e = 0; e < 8; ++e) y[e] *= inv;
;             }
;             uint4 o; o.x = cvt_pk_bf16(y[0], y[1]); o.y = cvt_pk_bf16(y[2], y[3]); o.z = cvt_pk_bf16(y[4], y[5]); o.w = cvt_pk_bf16(y[6], y[7]);
	s_waitcnt lgkmcnt(0)
	s_nop 1
	v_add_f32_dpp v96, v96, v96 row_mirror row_mask:0xf bank_mask:0xf
	v_add_f32_e32 v96, 0x358637bd, v96
	v_mul_f32_e32 v97, 0x4b800000, v96
	v_cmp_gt_f32_e32 vcc, s56, v96
	s_nop 1
	v_cndmask_b32_e32 v96, v96, v97, vcc
	v_rsq_f32_e32 v96, v96
	s_nop 0
	v_mul_f32_e32 v97, 0x45800000, v96
	v_cndmask_b32_e32 v96, v96, v97, vcc
	v_mul_f32_e32 v97, 0x3db504f3, v96
	v_cndmask_b32_e64 v96, v96, v97, s[4:5]
	v_pk_mul_f32 v[86:87], v[86:87], v[96:97] op_sel_hi:[1,0]
	v_pk_mul_f32 v[82:83], v[82:83], v[96:97] op_sel_hi:[1,0]
	v_pk_mul_f32 v[94:95], v[94:95], v[96:97] op_sel_hi:[1,0]
	v_pk_mul_f32 v[84:85], v[84:85], v[96:97] op_sel_hi:[1,0]
.LBB0_480:
	s_or_b64 exec, exec, s[36:37]
	v_pk_fma_f32 v[98:99], v[18:19], v[104:105], 0 op_sel_hi:[1,1,0]
	v_cvt_pk_bf16_f32 v96, v86, v87
	v_pk_fma_f32 v[98:99], v[22:23], v[118:119], v[98:99]
	s_waitcnt vmcnt(11)
	v_lshlrev_b32_e32 v86, 16, v78
	v_and_b32_e32 v87, 0xffff0000, v78
	v_pk_fma_f32 v[98:99], v[26:27], v[108:109], v[98:99]
	v_cvt_pk_bf16_f32 v97, v82, v83
	v_pk_fma_f32 v[120:121], v[30:31], v[86:87], v[98:99]
	v_cvt_pk_bf16_f32 v99, v84, v85
	v_mul_f32_e32 v78, 0xbfb8aa3b, v120
	v_exp_f32_e32 v104, v78
	v_mul_f32_e32 v78, 0xbfb8aa3b, v121
	v_exp_f32_e32 v105, v78
	v_cvt_pk_bf16_f32 v98, v94, v95
	v_pk_add_f32 v[82:83], v[104:105], 1.0 op_sel_hi:[1,0]
	s_nop 0


; DEV void gdn_prep_chunk(const Params& p, int item, unsigned char* lds) {
;     ...
;             *(uint4*)(dst + (tl0 + r) * QS + cv * 8) = o;
	v_add_u32_e32 v104, 0x110, v110
	v_add_u32_e32 v85, v132, v104
	ds_write_b128 v85, v[96:99]


; DEV float silu_f(float x) { return x / (1.f + __expf(-x)); }
	v_rcp_f32_e32 v78, v83
	s_nop 0
	v_mul_f32_e32 v95, v121, v78


; DEV float bflo(unsigned u) { return __uint_as_float(u << 16); }
; DEV float bfhi(unsigned u) { return __uint_as_float(u & 0xffff0000u); }
; DEV void gdn_prep_chunk(const Params& p, int item, unsigned char* lds) {
;     ...
;                 for (int j = 0; j < 4; ++j) {
;                     const uint4 u = raw[r + j];
;                     const unsigned wd = (e < 2 ? u.x : (e < 4 ? u.y : (e < 6 ? u.z : u.w)));
;                     const float xv = (e & 1) ? bfhi(wd) : bflo(wd);
;                     a += w[j][e] * xv;
	v_lshlrev_b32_e32 v84, 16, v79
	v_and_b32_e32 v85, 0xffff0000, v79
	v_pk_fma_f32 v[78:79], v[20:21], v[102:103], 0 op_sel_hi:[1,1,0]

; DEV void gdn_prep_chunk(const Params& p, int item, unsigned char* lds) {
;     ...
;                     a += w[j][e] * xv;
	v_pk_fma_f32 v[78:79], v[24:25], v[116:117], v[78:79]

; DEV void gdn_prep_chunk(const Params& p, int item, unsigned char* lds) {
;     ...
;                     a += w[j][e] * xv;
	v_pk_fma_f32 v[78:79], v[28:29], v[106:107], v[78:79]

; DEV void gdn_prep_chunk(const Params& p, int item, unsigned char* lds) {
;     ...
;                     a += w[j][e] * xv;
	v_pk_fma_f32 v[78:79], v[32:33], v[84:85], v[78:79]

; DEV float silu_f(float x) { return x / (1.f + __expf(-x)); }
	v_mul_f32_e32 v96, 0xbfb8aa3b, v78
	v_mul_f32_e32 v97, 0xbfb8aa3b, v79
	v_exp_f32_e32 v96, v96
	v_exp_f32_e32 v97, v97


; DEV float silu_f(float x) { return x / (1.f + __expf(-x)); }
	v_rcp_f32_e32 v83, v82
	s_nop 0
	v_mul_f32_e32 v94, v120, v83
	v_pk_add_f32 v[96:97], v[96:97], 1.0 op_sel_hi:[1,0]
	s_nop 0


; DEV float bflo(unsigned u) { return __uint_as_float(u << 16); }
; DEV float bfhi(unsigned u) { return __uint_as_float(u & 0xffff0000u); }
; DEV void gdn_prep_chunk(const Params& p, int item, unsigned char* lds) {
;     ...
;                 for (int j = 0; j < 4; ++j) {
;                     const uint4 u = raw[r + j];
;                     const unsigned wd = (e < 2 ? u.x : (e < 4 ? u.y : (e < 6 ? u.z : u.w)));
;                     const float xv = (e & 1) ? bfhi(wd) : bflo(wd);
;                     a += w[j][e] * xv;
	v_pk_fma_f32 v[98:99], v[2:3], v[100:101], 0 op_sel_hi:[1,1,0]

; DEV float bflo(unsigned u) { return __uint_as_float(u << 16); }
; DEV float bfhi(unsigned u) { return __uint_as_float(u & 0xffff0000u); }
; DEV float silu_f(float x) { return x / (1.f + __expf(-x)); }
; DEV void gdn_prep_chunk(const Params& p, int item, unsigned char* lds) {
;     ...
;                 for (int j = 0; j < 4; ++j) {
;                     const uint4 u = raw[r + j];
;                     const unsigned wd = (e < 2 ? u.x : (e < 4 ? u.y : (e < 6 ? u.z : u.w)));
;                     const float xv = (e & 1) ? bfhi(wd) : bflo(wd);
;                     a += w[j][e] * xv;
;                 }
;                 y[e] = silu_f(a); ss += y[e] * y[e];
	v_pk_fma_f32 v[98:99], v[6:7], v[114:115], v[98:99]
	v_rcp_f32_e32 v82, v97
	s_nop 0
	v_mul_f32_e32 v97, v79, v82
	v_lshlrev_b32_e32 v82, 16, v80
	v_and_b32_e32 v83, 0xffff0000, v80
	v_pk_fma_f32 v[98:99], v[10:11], v[92:93], v[98:99]

; DEV void gdn_prep_chunk(const Params& p, int item, unsigned char* lds) {
;     ...
;                     a += w[j][e] * xv;
	v_pk_fma_f32 v[98:99], v[14:15], v[82:83], v[98:99]

; DEV float silu_f(float x) { return x / (1.f + __expf(-x)); }
	v_mul_f32_e32 v80, 0xbfb8aa3b, v98
	v_exp_f32_e32 v100, v80
	v_mul_f32_e32 v80, 0xbfb8aa3b, v99
	v_exp_f32_e32 v101, v80


; DEV float silu_f(float x) { return x / (1.f + __expf(-x)); }
	s_nop 0
	v_pk_add_f32 v[100:101], v[100:101], 1.0 op_sel_hi:[1,0]


; DEV float silu_f(float x) { return x / (1.f + __expf(-x)); }
	v_rcp_f32_e32 v79, v96
	s_nop 0
	v_mul_f32_e32 v96, v78, v79


; DEV float silu_f(float x) { return x / (1.f + __expf(-x)); }
	v_rcp_f32_e32 v78, v101
	s_nop 0
	v_mul_f32_e32 v99, v99, v78


; DEV float bflo(unsigned u) { return __uint_as_float(u << 16); }
; DEV float bfhi(unsigned u) { return __uint_as_float(u & 0xffff0000u); }
; DEV void gdn_prep_chunk(const Params& p, int item, unsigned char* lds) {
;     ...
;                 for (int j = 0; j < 4; ++j) {
;                     const uint4 u = raw[r + j];
;                     const unsigned wd = (e < 2 ? u.x : (e < 4 ? u.y : (e < 6 ? u.z : u.w)));
;                     const float xv = (e & 1) ? bfhi(wd) : bflo(wd);
;                     a += w[j][e] * xv;
	v_lshlrev_b32_e32 v78, 16, v81
	v_and_b32_e32 v79, 0xffff0000, v81
	v_pk_fma_f32 v[80:81], v[4:5], v[90:91], 0 op_sel_hi:[1,1,0]

; DEV void gdn_prep_chunk(const Params& p, int item, unsigned char* lds) {
;     ...
;                     a += w[j][e] * xv;
	v_pk_fma_f32 v[80:81], v[8:9], v[112:113], v[80:81]

; DEV void gdn_prep_chunk(const Params& p, int item, unsigned char* lds) {
;     ...
;                     a += w[j][e] * xv;
	v_pk_fma_f32 v[80:81], v[12:13], v[88:89], v[80:81]

; DEV void gdn_prep_chunk(const Params& p, int item, unsigned char* lds) {
;     ...
;                     a += w[j][e] * xv;
	v_pk_fma_f32 v[80:81], v[16:17], v[78:79], v[80:81]

; DEV float silu_f(float x) { return x / (1.f + __expf(-x)); }
	v_mul_f32_e32 v90, 0xbfb8aa3b, v80
	v_mul_f32_e32 v91, 0xbfb8aa3b, v81
	v_exp_f32_e32 v90, v90
	v_exp_f32_e32 v91, v91


; DEV float silu_f(float x) { return x / (1.f + __expf(-x)); }
	v_rcp_f32_e32 v101, v100
	s_nop 0
	v_mul_f32_e32 v98, v98, v101
	v_pk_add_f32 v[90:91], v[90:91], 1.0 op_sel_hi:[1,0]
	s_nop 0


; DEV float silu_f(float x) { return x / (1.f + __expf(-x)); }
	s_nop 0


; DEV float silu_f(float x) { return x / (1.f + __expf(-x)); }
	v_rcp_f32_e32 v100, v91
	s_nop 0
	v_mul_f32_e32 v91, v81, v100


; DEV float silu_f(float x) { return x / (1.f + __expf(-x)); }
; DEV void gdn_prep_chunk(const Params& p, int item, unsigned char* lds) {
;     ...
;                 y[e] = silu_f(a); ss += y[e] * y[e];
;             }
;             if (mat < 2) {
;                 ss += __shfl_xor(ss, 1); ss += __shfl_xor(ss, 2); ss += __shfl_xor(ss, 4); ss += __shfl_xor(ss, 8);
	v_rcp_f32_e32 v81, v90
	s_nop 0
	v_mul_f32_e32 v90, v80, v81
	s_and_saveexec_b64 s[36:37], s[6:7]
	s_cbranch_execz .LBB0_482
	v_pk_mul_f32 v[80:81], v[94:95], v[94:95]
	v_pk_mul_f32 v[100:101], v[96:97], v[96:97]
	v_add_f32_e32 v80, v80, v81
	v_add_f32_e32 v80, v80, v100
	v_pk_mul_f32 v[102:103], v[98:99], v[98:99]
	v_add_f32_e32 v80, v101, v80
	v_and_b32_e32 v100, 64, v182
	v_add_f32_e32 v80, v102, v80

; DEV float silu_f(float x) { return x / (1.f + __expf(-x)); }
; DEV void gdn_prep_chunk(const Params& p, int item, unsigned char* lds) {
;     ...
;                 y[e] = silu_f(a); ss += y[e] * y[e];
;             }
;             if (mat < 2) {
;                 ss += __shfl_xor(ss, 1); ss += __shfl_xor(ss, 2); ss += __shfl_xor(ss, 4); ss += __shfl_xor(ss, 8);
	v_add_u32_e32 v100, 64, v100
	v_pk_mul_f32 v[110:111], v[90:91], v[90:91]
	v_add_f32_e32 v80, v103, v80

; DEV float silu_f(float x) { return x / (1.f + __expf(-x)); }
; DEV void gdn_prep_chunk(const Params& p, int item, unsigned char* lds) {
;     ...
;                 y[e] = silu_f(a); ss += y[e] * y[e];
;             }
;             if (mat < 2) {
;                 ss += __shfl_xor(ss, 1); ss += __shfl_xor(ss, 2); ss += __shfl_xor(ss, 4); ss += __shfl_xor(ss, 8);
	v_add_f32_e32 v80, v110, v80
	v_add_f32_e32 v80, v111, v80


; DEV void gdn_prep_chunk(const Params& p, int item, unsigned char* lds) {
;     ...
;                 ss += __shfl_xor(ss, 1); ss += __shfl_xor(ss, 2); ss += __shfl_xor(ss, 4); ss += __shfl_xor(ss, 8);
	s_waitcnt lgkmcnt(0)
	s_nop 1
	v_add_f32_dpp v80, v80, v80 quad_perm:[1,0,3,2] row_mask:0xf bank_mask:0xf


; DEV void gdn_prep_chunk(const Params& p, int item, unsigned char* lds) {
;     ...
;                 ss += __shfl_xor(ss, 1); ss += __shfl_xor(ss, 2); ss += __shfl_xor(ss, 4); ss += __shfl_xor(ss, 8);
	s_nop 1


; DEV void gdn_prep_chunk(const Params& p, int item, unsigned char* lds) {
;     ...
;                 ss += __shfl_xor(ss, 1); ss += __shfl_xor(ss, 2); ss += __shfl_xor(ss, 4); ss += __shfl_xor(ss, 8);
	s_waitcnt lgkmcnt(0)
	s_nop 1
	v_add_f32_dpp v80, v80, v80 quad_perm:[2,3,0,1] row_mask:0xf bank_mask:0xf


; DEV void gdn_prep_chunk(const Params& p, int item, unsigned char* lds) {
;     ...
;                 ss += __shfl_xor(ss, 1); ss += __shfl_xor(ss, 2); ss += __shfl_xor(ss, 4); ss += __shfl_xor(ss, 8);
	s_nop 1


; DEV void gdn_prep_chunk(const Params& p, int item, unsigned char* lds) {
;     ...
;                 ss += __shfl_xor(ss, 1); ss += __shfl_xor(ss, 2); ss += __shfl_xor(ss, 4); ss += __shfl_xor(ss, 8);
	s_waitcnt lgkmcnt(0)
	s_nop 1
	v_add_f32_dpp v80, v80, v80 row_half_mirror row_mask:0xf bank_mask:0xf


; DEV void gdn_prep_chunk(const Params& p, int item, unsigned char* lds) {
;     ...
;                 ss += __shfl_xor(ss, 1); ss += __shfl_xor(ss, 2); ss += __shfl_xor(ss, 4); ss += __shfl_xor(ss, 8);
	s_nop 1


; DEV unsigned cvt_pk_bf16(float lo, float hi) { const f32x2_t v = {lo, hi}; const bf16x2_t b = __builtin_convertvector(v, bf16x2_t); return __builtin_bit_cast(unsigned, b); }
; DEV float bflo(unsigned u) { return __uint_as_float(u << 16); }
; DEV float bfhi(unsigned u) { return __uint_as_float(u & 0xffff0000u); }
; DEV float silu_f(float x) { return x / (1.f + __expf(-x)); }
; DEV void gdn_prep_chunk(const Params& p, int item, unsigned char* lds) {
;     ...
;             for (int e = 0; e < 8; ++e) {
;                 float a = 0.f;
; #pragma unroll
;                 for (int j = 0; j < 4; ++j) {
;                     const uint4 u = raw[r + j];
;                     const unsigned wd = (e < 2 ? u.x : (e < 4 ? u.y : (e < 6 ? u.z : u.w)));
;                     const float xv = (e & 1) ? bfhi(wd) : bflo(wd);
;                     a += w[j][e] * xv;
;                 }
;                 y[e] = silu_f(a); ss += y[e] * y[e];
;     ...
;                 ss += __shfl_xor(ss, 1); ss += __shfl_xor(ss, 2); ss += __shfl_xor(ss, 4); ss += __shfl_xor(ss, 8);
;                 float inv = rsqrtf(ss + EPS); if (mat == 0) inv *= 0.08838834764831845f;
; #pragma unroll
;                 for (int e = 0; e < 8; ++e) y[e] *= inv;
;             }
;             uint4 o; o.x = cvt_pk_bf16(y[0], y[1]); o.y = cvt_pk_bf16(y[2], y[3]); o.z = cvt_pk_bf16(y[4], y[5]); o.w = cvt_pk_bf16(y[6], y[7]);
;             *(uint4*)(dst + (tl0 + r) * QS + cv * 8) = o;
	s_waitcnt lgkmcnt(0)
	s_nop 1
	v_add_f32_dpp v80, v80, v80 row_mirror row_mask:0xf bank_mask:0xf
	v_add_f32_e32 v80, 0x358637bd, v80
	v_mul_f32_e32 v81, 0x4b800000, v80
	v_cmp_gt_f32_e32 vcc, s56, v80
	s_nop 1
	v_cndmask_b32_e32 v80, v80, v81, vcc
	v_rsq_f32_e32 v80, v80
	s_nop 0
	v_mul_f32_e32 v81, 0x45800000, v80
	v_cndmask_b32_e32 v80, v80, v81, vcc
	v_mul_f32_e32 v81, 0x3db504f3, v80
	v_cndmask_b32_e64 v80, v80, v81, s[4:5]
	v_pk_mul_f32 v[94:95], v[94:95], v[80:81] op_sel_hi:[1,0]
	v_pk_mul_f32 v[96:97], v[96:97], v[80:81] op_sel_hi:[1,0]
	v_pk_mul_f32 v[98:99], v[98:99], v[80:81] op_sel_hi:[1,0]
	v_pk_mul_f32 v[90:91], v[90:91], v[80:81] op_sel_hi:[1,0]
.LBB0_482:
	s_or_b64 exec, exec, s[36:37]
	v_pk_fma_f32 v[100:101], v[18:19], v[118:119], 0 op_sel_hi:[1,1,0]
	s_waitcnt vmcnt(10)
	v_lshlrev_b32_e32 v80, 16, v74
	v_pk_fma_f32 v[100:101], v[22:23], v[108:109], v[100:101]
	v_and_b32_e32 v81, 0xffff0000, v74
	v_pk_fma_f32 v[100:101], v[26:27], v[86:87], v[100:101]
	v_cvt_pk_bf16_f32 v94, v94, v95
	v_pk_fma_f32 v[100:101], v[30:31], v[80:81], v[100:101]
	v_cvt_pk_bf16_f32 v95, v96, v97
	v_mul_f32_e32 v74, 0xbfb8aa3b, v100
	v_exp_f32_e32 v102, v74
	v_mul_f32_e32 v74, 0xbfb8aa3b, v101
	v_exp_f32_e32 v103, v74
	v_cvt_pk_bf16_f32 v97, v90, v91
	v_cvt_pk_bf16_f32 v96, v98, v99
	v_add_u32_e32 v104, 0x110, v104
	v_pk_add_f32 v[90:91], v[102:103], 1.0 op_sel_hi:[1,0]
	v_add_u32_e32 v99, v132, v104


; DEV void gdn_prep_chunk(const Params& p, int item, unsigned char* lds) {
;     ...
;             *(uint4*)(dst + (tl0 + r) * QS + cv * 8) = o;
	ds_write_b128 v99, v[94:97]


; DEV float silu_f(float x) { return x / (1.f + __expf(-x)); }
	v_rcp_f32_e32 v74, v91
	s_nop 0
	v_mul_f32_e32 v97, v101, v74


; DEV float bflo(unsigned u) { return __uint_as_float(u << 16); }
; DEV float bfhi(unsigned u) { return __uint_as_float(u & 0xffff0000u); }
; DEV void gdn_prep_chunk(const Params& p, int item, unsigned char* lds) {
;     ...
;                 for (int j = 0; j < 4; ++j) {
;                     const uint4 u = raw[r + j];
;                     const unsigned wd = (e < 2 ? u.x : (e < 4 ? u.y : (e < 6 ? u.z : u.w)));
;                     const float xv = (e & 1) ? bfhi(wd) : bflo(wd);
;                     a += w[j][e] * xv;
	v_lshlrev_b32_e32 v94, 16, v75
	v_and_b32_e32 v95, 0xffff0000, v75
	v_pk_fma_f32 v[74:75], v[20:21], v[116:117], 0 op_sel_hi:[1,1,0]

; DEV float bflo(unsigned u) { return __uint_as_float(u << 16); }
; DEV float bfhi(unsigned u) { return __uint_as_float(u & 0xffff0000u); }
; DEV void gdn_prep_chunk(const Params& p, int item, unsigned char* lds) {
;     ...
;                 for (int j = 0; j < 4; ++j) {
;                     const uint4 u = raw[r + j];
;                     const unsigned wd = (e < 2 ? u.x : (e < 4 ? u.y : (e < 6 ? u.z : u.w)));
;                     const float xv = (e & 1) ? bfhi(wd) : bflo(wd);
;                     a += w[j][e] * xv;
	v_pk_fma_f32 v[74:75], v[24:25], v[106:107], v[74:75]

; DEV float bflo(unsigned u) { return __uint_as_float(u << 16); }
; DEV float bfhi(unsigned u) { return __uint_as_float(u & 0xffff0000u); }
; DEV void gdn_prep_chunk(const Params& p, int item, unsigned char* lds) {
;     ...
;                 for (int j = 0; j < 4; ++j) {
;                     const uint4 u = raw[r + j];
;                     const unsigned wd = (e < 2 ? u.x : (e < 4 ? u.y : (e < 6 ? u.z : u.w)));
;                     const float xv = (e & 1) ? bfhi(wd) : bflo(wd);
;                     a += w[j][e] * xv;
	v_pk_fma_f32 v[74:75], v[28:29], v[84:85], v[74:75]

; DEV float bflo(unsigned u) { return __uint_as_float(u << 16); }
; DEV float bfhi(unsigned u) { return __uint_as_float(u & 0xffff0000u); }
; DEV void gdn_prep_chunk(const Params& p, int item, unsigned char* lds) {
;     ...
;                 for (int j = 0; j < 4; ++j) {
;                     const uint4 u = raw[r + j];
;                     const unsigned wd = (e < 2 ? u.x : (e < 4 ? u.y : (e < 6 ? u.z : u.w)));
;                     const float xv = (e & 1) ? bfhi(wd) : bflo(wd);
;                     a += w[j][e] * xv;
	v_pk_fma_f32 v[74:75], v[32:33], v[94:95], v[74:75]

; DEV float silu_f(float x) { return x / (1.f + __expf(-x)); }
	v_mul_f32_e32 v98, 0xbfb8aa3b, v74
	v_mul_f32_e32 v99, 0xbfb8aa3b, v75
	v_exp_f32_e32 v98, v98
	v_exp_f32_e32 v99, v99


; DEV float silu_f(float x) { return x / (1.f + __expf(-x)); }
	v_rcp_f32_e32 v91, v90
	s_nop 0
	v_mul_f32_e32 v96, v100, v91
	v_pk_add_f32 v[98:99], v[98:99], 1.0 op_sel_hi:[1,0]
	s_nop 0


; DEV float bflo(unsigned u) { return __uint_as_float(u << 16); }
; DEV float bfhi(unsigned u) { return __uint_as_float(u & 0xffff0000u); }
; DEV void gdn_prep_chunk(const Params& p, int item, unsigned char* lds) {
;     ...
;                 for (int j = 0; j < 4; ++j) {
;                     const uint4 u = raw[r + j];
;                     const unsigned wd = (e < 2 ? u.x : (e < 4 ? u.y : (e < 6 ? u.z : u.w)));
;                     const float xv = (e & 1) ? bfhi(wd) : bflo(wd);
;                     a += w[j][e] * xv;
	v_pk_fma_f32 v[100:101], v[2:3], v[114:115], 0 op_sel_hi:[1,1,0]

; DEV float bflo(unsigned u) { return __uint_as_float(u << 16); }
; DEV float bfhi(unsigned u) { return __uint_as_float(u & 0xffff0000u); }
; DEV void gdn_prep_chunk(const Params& p, int item, unsigned char* lds) {
;     ...
;                 for (int j = 0; j < 4; ++j) {
;                     const uint4 u = raw[r + j];
;                     const unsigned wd = (e < 2 ? u.x : (e < 4 ? u.y : (e < 6 ? u.z : u.w)));
;                     const float xv = (e & 1) ? bfhi(wd) : bflo(wd);
;                     a += w[j][e] * xv;
	v_pk_fma_f32 v[100:101], v[6:7], v[92:93], v[100:101]
	v_rcp_f32_e32 v90, v99
	s_nop 0
	v_mul_f32_e32 v99, v75, v90
	v_lshlrev_b32_e32 v90, 16, v76
	v_and_b32_e32 v91, 0xffff0000, v76
	v_pk_fma_f32 v[100:101], v[10:11], v[82:83], v[100:101]

; DEV float bflo(unsigned u) { return __uint_as_float(u << 16); }
; DEV float bfhi(unsigned u) { return __uint_as_float(u & 0xffff0000u); }
; DEV void gdn_prep_chunk(const Params& p, int item, unsigned char* lds) {
;     ...
;                 for (int j = 0; j < 4; ++j) {
;                     const uint4 u = raw[r + j];
;                     const unsigned wd = (e < 2 ? u.x : (e < 4 ? u.y : (e < 6 ? u.z : u.w)));
;                     const float xv = (e & 1) ? bfhi(wd) : bflo(wd);
;                     a += w[j][e] * xv;
	v_pk_fma_f32 v[100:101], v[14:15], v[90:91], v[100:101]

; DEV float silu_f(float x) { return x / (1.f + __expf(-x)); }
	v_mul_f32_e32 v76, 0xbfb8aa3b, v100
	v_exp_f32_e32 v102, v76
	v_mul_f32_e32 v76, 0xbfb8aa3b, v101
	v_exp_f32_e32 v103, v76


; DEV float silu_f(float x) { return x / (1.f + __expf(-x)); }
	s_nop 0
	v_pk_add_f32 v[102:103], v[102:103], 1.0 op_sel_hi:[1,0]


; DEV float silu_f(float x) { return x / (1.f + __expf(-x)); }
	v_rcp_f32_e32 v75, v98
	s_nop 0
	v_mul_f32_e32 v98, v74, v75


; DEV float silu_f(float x) { return x / (1.f + __expf(-x)); }
	v_rcp_f32_e32 v74, v103
	s_nop 0
	v_mul_f32_e32 v101, v101, v74


; DEV float bflo(unsigned u) { return __uint_as_float(u << 16); }
; DEV float bfhi(unsigned u) { return __uint_as_float(u & 0xffff0000u); }
; DEV void gdn_prep_chunk(const Params& p, int item, unsigned char* lds) {
;     ...
;                 for (int j = 0; j < 4; ++j) {
;                     const uint4 u = raw[r + j];
;                     const unsigned wd = (e < 2 ? u.x : (e < 4 ? u.y : (e < 6 ? u.z : u.w)));
;                     const float xv = (e & 1) ? bfhi(wd) : bflo(wd);
;                     a += w[j][e] * xv;
	v_lshlrev_b32_e32 v74, 16, v77
	v_and_b32_e32 v75, 0xffff0000, v77
	v_pk_fma_f32 v[76:77], v[4:5], v[112:113], 0 op_sel_hi:[1,1,0]

; DEV float bflo(unsigned u) { return __uint_as_float(u << 16); }
; DEV float bfhi(unsigned u) { return __uint_as_float(u & 0xffff0000u); }
; DEV void gdn_prep_chunk(const Params& p, int item, unsigned char* lds) {
;     ...
;                 for (int j = 0; j < 4; ++j) {
;                     const uint4 u = raw[r + j];
;                     const unsigned wd = (e < 2 ? u.x : (e < 4 ? u.y : (e < 6 ? u.z : u.w)));
;                     const float xv = (e & 1) ? bfhi(wd) : bflo(wd);
;                     a += w[j][e] * xv;
	v_pk_fma_f32 v[76:77], v[8:9], v[88:89], v[76:77]

; DEV float bflo(unsigned u) { return __uint_as_float(u << 16); }
; DEV float bfhi(unsigned u) { return __uint_as_float(u & 0xffff0000u); }
; DEV void gdn_prep_chunk(const Params& p, int item, unsigned char* lds) {
;     ...
;                 for (int j = 0; j < 4; ++j) {
;                     const uint4 u = raw[r + j];
;                     const unsigned wd = (e < 2 ? u.x : (e < 4 ? u.y : (e < 6 ? u.z : u.w)));
;                     const float xv = (e & 1) ? bfhi(wd) : bflo(wd);
;                     a += w[j][e] * xv;
	v_pk_fma_f32 v[76:77], v[12:13], v[78:79], v[76:77]

; DEV float bflo(unsigned u) { return __uint_as_float(u << 16); }
; DEV float bfhi(unsigned u) { return __uint_as_float(u & 0xffff0000u); }
; DEV void gdn_prep_chunk(const Params& p, int item, unsigned char* lds) {
;     ...
;                 for (int j = 0; j < 4; ++j) {
;                     const uint4 u = raw[r + j];
;                     const unsigned wd = (e < 2 ? u.x : (e < 4 ? u.y : (e < 6 ? u.z : u.w)));
;                     const float xv = (e & 1) ? bfhi(wd) : bflo(wd);
;                     a += w[j][e] * xv;
	v_pk_fma_f32 v[76:77], v[16:17], v[74:75], v[76:77]

; DEV float silu_f(float x) { return x / (1.f + __expf(-x)); }
	v_mul_f32_e32 v110, 0xbfb8aa3b, v76
	v_mul_f32_e32 v111, 0xbfb8aa3b, v77
	v_exp_f32_e32 v110, v110
	v_exp_f32_e32 v111, v111


; DEV float silu_f(float x) { return x / (1.f + __expf(-x)); }
	v_rcp_f32_e32 v103, v102
	s_nop 0
	v_mul_f32_e32 v100, v100, v103
	v_pk_add_f32 v[110:111], v[110:111], 1.0 op_sel_hi:[1,0]
	s_nop 0


; DEV float silu_f(float x) { return x / (1.f + __expf(-x)); }
	s_nop 0


; DEV float silu_f(float x) { return x / (1.f + __expf(-x)); }
	v_rcp_f32_e32 v102, v111
	s_nop 0
	v_mul_f32_e32 v103, v77, v102


; DEV float silu_f(float x) { return x / (1.f + __expf(-x)); }
; DEV void gdn_prep_chunk(const Params& p, int item, unsigned char* lds) {
;     ...
;                 y[e] = silu_f(a); ss += y[e] * y[e];
;             }
;             if (mat < 2) {
;                 ss += __shfl_xor(ss, 1); ss += __shfl_xor(ss, 2); ss += __shfl_xor(ss, 4); ss += __shfl_xor(ss, 8);
	v_rcp_f32_e32 v77, v110
	s_nop 0
	v_mul_f32_e32 v102, v76, v77
	s_and_saveexec_b64 s[36:37], s[6:7]
	s_cbranch_execz .LBB0_484
	v_pk_mul_f32 v[76:77], v[96:97], v[96:97]
	v_pk_mul_f32 v[110:111], v[98:99], v[98:99]
	v_add_f32_e32 v76, v76, v77
	v_add_f32_e32 v76, v76, v110
	v_pk_mul_f32 v[112:113], v[100:101], v[100:101]
	v_add_f32_e32 v76, v111, v76
	v_and_b32_e32 v105, 64, v182
	v_add_f32_e32 v76, v112, v76

; DEV float silu_f(float x) { return x / (1.f + __expf(-x)); }
; DEV void gdn_prep_chunk(const Params& p, int item, unsigned char* lds) {
;     ...
;                 y[e] = silu_f(a); ss += y[e] * y[e];
;             }
;             if (mat < 2) {
;                 ss += __shfl_xor(ss, 1); ss += __shfl_xor(ss, 2); ss += __shfl_xor(ss, 4); ss += __shfl_xor(ss, 8);
	v_add_u32_e32 v105, 64, v105
	v_pk_mul_f32 v[114:115], v[102:103], v[102:103]
	v_add_f32_e32 v76, v113, v76

; DEV float silu_f(float x) { return x / (1.f + __expf(-x)); }
; DEV void gdn_prep_chunk(const Params& p, int item, unsigned char* lds) {
;     ...
;                 y[e] = silu_f(a); ss += y[e] * y[e];
;             }
;             if (mat < 2) {
;                 ss += __shfl_xor(ss, 1); ss += __shfl_xor(ss, 2); ss += __shfl_xor(ss, 4); ss += __shfl_xor(ss, 8);
	v_add_f32_e32 v76, v114, v76
	v_add_f32_e32 v76, v115, v76


; DEV void gdn_prep_chunk(const Params& p, int item, unsigned char* lds) {
;     ...
;                 ss += __shfl_xor(ss, 1); ss += __shfl_xor(ss, 2); ss += __shfl_xor(ss, 4); ss += __shfl_xor(ss, 8);
	s_waitcnt lgkmcnt(0)
	s_nop 1
	v_add_f32_dpp v76, v76, v76 quad_perm:[1,0,3,2] row_mask:0xf bank_mask:0xf


; DEV void gdn_prep_chunk(const Params& p, int item, unsigned char* lds) {
;     ...
;                 ss += __shfl_xor(ss, 1); ss += __shfl_xor(ss, 2); ss += __shfl_xor(ss, 4); ss += __shfl_xor(ss, 8);
	s_nop 1


; DEV void gdn_prep_chunk(const Params& p, int item, unsigned char* lds) {
;     ...
;                 ss += __shfl_xor(ss, 1); ss += __shfl_xor(ss, 2); ss += __shfl_xor(ss, 4); ss += __shfl_xor(ss, 8);
	s_waitcnt lgkmcnt(0)
	s_nop 1
	v_add_f32_dpp v76, v76, v76 quad_perm:[2,3,0,1] row_mask:0xf bank_mask:0xf


; DEV void gdn_prep_chunk(const Params& p, int item, unsigned char* lds) {
;     ...
;                 ss += __shfl_xor(ss, 1); ss += __shfl_xor(ss, 2); ss += __shfl_xor(ss, 4); ss += __shfl_xor(ss, 8);
	s_nop 1


; DEV void gdn_prep_chunk(const Params& p, int item, unsigned char* lds) {
;     ...
;                 ss += __shfl_xor(ss, 1); ss += __shfl_xor(ss, 2); ss += __shfl_xor(ss, 4); ss += __shfl_xor(ss, 8);
	s_waitcnt lgkmcnt(0)
	s_nop 1
	v_add_f32_dpp v76, v76, v76 row_half_mirror row_mask:0xf bank_mask:0xf


; DEV void gdn_prep_chunk(const Params& p, int item, unsigned char* lds) {
;     ...
;                 ss += __shfl_xor(ss, 1); ss += __shfl_xor(ss, 2); ss += __shfl_xor(ss, 4); ss += __shfl_xor(ss, 8);
	s_nop 1


; DEV unsigned cvt_pk_bf16(float lo, float hi) { const f32x2_t v = {lo, hi}; const bf16x2_t b = __builtin_convertvector(v, bf16x2_t); return __builtin_bit_cast(unsigned, b); }
; DEV float bflo(unsigned u) { return __uint_as_float(u << 16); }
; DEV float bfhi(unsigned u) { return __uint_as_float(u & 0xffff0000u); }
; DEV float silu_f(float x) { return x / (1.f + __expf(-x)); }
; DEV void gdn_prep_chunk(const Params& p, int item, unsigned char* lds) {
;     ...
;             for (int e = 0; e < 8; ++e) {
;                 float a = 0.f;
; #pragma unroll
;                 for (int j = 0; j < 4; ++j) {
;                     const uint4 u = raw[r + j];
;                     const unsigned wd = (e < 2 ? u.x : (e < 4 ? u.y : (e < 6 ? u.z : u.w)));
;                     const float xv = (e & 1) ? bfhi(wd) : bflo(wd);
;                     a += w[j][e] * xv;
;                 }
;                 y[e] = silu_f(a); ss += y[e] * y[e];
;     ...
;                 ss += __shfl_xor(ss, 1); ss += __shfl_xor(ss, 2); ss += __shfl_xor(ss, 4); ss += __shfl_xor(ss, 8);
;                 float inv = rsqrtf(ss + EPS); if (mat == 0) inv *= 0.08838834764831845f;
; #pragma unroll
;                 for (int e = 0; e < 8; ++e) y[e] *= inv;
;             }
;             uint4 o; o.x = cvt_pk_bf16(y[0], y[1]); o.y = cvt_pk_bf16(y[2], y[3]); o.z = cvt_pk_bf16(y[4], y[5]); o.w = cvt_pk_bf16(y[6], y[7]);
;             *(uint4*)(dst + (tl0 + r) * QS + cv * 8) = o;
	s_waitcnt lgkmcnt(0)
	s_nop 1
	v_add_f32_dpp v76, v76, v76 row_mirror row_mask:0xf bank_mask:0xf
	v_add_f32_e32 v76, 0x358637bd, v76
	v_mul_f32_e32 v77, 0x4b800000, v76
	v_cmp_gt_f32_e32 vcc, s56, v76
	s_nop 1
	v_cndmask_b32_e32 v76, v76, v77, vcc
	v_rsq_f32_e32 v76, v76
	s_nop 0
	v_mul_f32_e32 v77, 0x45800000, v76
	v_cndmask_b32_e32 v76, v76, v77, vcc
	v_mul_f32_e32 v77, 0x3db504f3, v76
	v_cndmask_b32_e64 v76, v76, v77, s[4:5]
	v_pk_mul_f32 v[96:97], v[96:97], v[76:77] op_sel_hi:[1,0]
	v_pk_mul_f32 v[98:99], v[98:99], v[76:77] op_sel_hi:[1,0]
	v_pk_mul_f32 v[100:101], v[100:101], v[76:77] op_sel_hi:[1,0]
	v_pk_mul_f32 v[102:103], v[102:103], v[76:77] op_sel_hi:[1,0]
.LBB0_484:
	s_or_b64 exec, exec, s[36:37]
	v_pk_fma_f32 v[108:109], v[18:19], v[108:109], 0 op_sel_hi:[1,1,0]
	s_waitcnt vmcnt(9)
	v_lshlrev_b32_e32 v76, 16, v70
	v_pk_fma_f32 v[108:109], v[22:23], v[86:87], v[108:109]
	v_and_b32_e32 v77, 0xffff0000, v70
	v_pk_fma_f32 v[108:109], v[26:27], v[80:81], v[108:109]
	v_cvt_pk_bf16_f32 v96, v96, v97
	v_pk_fma_f32 v[108:109], v[30:31], v[76:77], v[108:109]
	v_cvt_pk_bf16_f32 v97, v98, v99
	v_mul_f32_e32 v70, 0xbfb8aa3b, v108
	v_exp_f32_e32 v110, v70
	v_mul_f32_e32 v70, 0xbfb8aa3b, v109
	v_exp_f32_e32 v111, v70
	v_cvt_pk_bf16_f32 v98, v100, v101
	v_cvt_pk_bf16_f32 v99, v102, v103
	v_add_u32_e32 v104, 0x110, v104
	v_pk_add_f32 v[100:101], v[110:111], 1.0 op_sel_hi:[1,0]
	v_add_u32_e32 v103, v132, v104


; DEV void gdn_prep_chunk(const Params& p, int item, unsigned char* lds) {
;     ...
;             *(uint4*)(dst + (tl0 + r) * QS + cv * 8) = o;
	ds_write_b128 v103, v[96:99]


; DEV float silu_f(float x) { return x / (1.f + __expf(-x)); }
	v_rcp_f32_e32 v70, v101
	s_nop 0
	v_mul_f32_e32 v101, v109, v70


; DEV float bflo(unsigned u) { return __uint_as_float(u << 16); }
; DEV float bfhi(unsigned u) { return __uint_as_float(u & 0xffff0000u); }
; DEV void gdn_prep_chunk(const Params& p, int item, unsigned char* lds) {
;     ...
;                 for (int j = 0; j < 4; ++j) {
;                     const uint4 u = raw[r + j];
;                     const unsigned wd = (e < 2 ? u.x : (e < 4 ? u.y : (e < 6 ? u.z : u.w)));
;                     const float xv = (e & 1) ? bfhi(wd) : bflo(wd);
;                     a += w[j][e] * xv;
	v_lshlrev_b32_e32 v98, 16, v71
	v_and_b32_e32 v99, 0xffff0000, v71
	v_pk_fma_f32 v[70:71], v[20:21], v[106:107], 0 op_sel_hi:[1,1,0]

; DEV float bflo(unsigned u) { return __uint_as_float(u << 16); }
; DEV float bfhi(unsigned u) { return __uint_as_float(u & 0xffff0000u); }
; DEV void gdn_prep_chunk(const Params& p, int item, unsigned char* lds) {
;     ...
;                 for (int j = 0; j < 4; ++j) {
;                     const uint4 u = raw[r + j];
;                     const unsigned wd = (e < 2 ? u.x : (e < 4 ? u.y : (e < 6 ? u.z : u.w)));
;                     const float xv = (e & 1) ? bfhi(wd) : bflo(wd);
;                     a += w[j][e] * xv;
	v_pk_fma_f32 v[70:71], v[24:25], v[84:85], v[70:71]

; DEV float bflo(unsigned u) { return __uint_as_float(u << 16); }
; DEV float bfhi(unsigned u) { return __uint_as_float(u & 0xffff0000u); }
; DEV void gdn_prep_chunk(const Params& p, int item, unsigned char* lds) {
;     ...
;                 for (int j = 0; j < 4; ++j) {
;                     const uint4 u = raw[r + j];
;                     const unsigned wd = (e < 2 ? u.x : (e < 4 ? u.y : (e < 6 ? u.z : u.w)));
;                     const float xv = (e & 1) ? bfhi(wd) : bflo(wd);
;                     a += w[j][e] * xv;
	v_pk_fma_f32 v[70:71], v[28:29], v[94:95], v[70:71]

; DEV float bflo(unsigned u) { return __uint_as_float(u << 16); }
; DEV float bfhi(unsigned u) { return __uint_as_float(u & 0xffff0000u); }
; DEV void gdn_prep_chunk(const Params& p, int item, unsigned char* lds) {
;     ...
;                 for (int j = 0; j < 4; ++j) {
;                     const uint4 u = raw[r + j];
;                     const unsigned wd = (e < 2 ? u.x : (e < 4 ? u.y : (e < 6 ? u.z : u.w)));
;                     const float xv = (e & 1) ? bfhi(wd) : bflo(wd);
;                     a += w[j][e] * xv;
	v_pk_fma_f32 v[70:71], v[32:33], v[98:99], v[70:71]

; DEV float silu_f(float x) { return x / (1.f + __expf(-x)); }
	v_mul_f32_e32 v96, 0xbfb8aa3b, v70
	v_mul_f32_e32 v97, 0xbfb8aa3b, v71
	v_exp_f32_e32 v96, v96
	v_exp_f32_e32 v97, v97


; DEV float bflo(unsigned u) { return __uint_as_float(u << 16); }
; DEV float bfhi(unsigned u) { return __uint_as_float(u & 0xffff0000u); }
; DEV float silu_f(float x) { return x / (1.f + __expf(-x)); }
; DEV void gdn_prep_chunk(const Params& p, int item, unsigned char* lds) {
;     ...
;                 for (int j = 0; j < 4; ++j) {
;                     const uint4 u = raw[r + j];
;                     const unsigned wd = (e < 2 ? u.x : (e < 4 ? u.y : (e < 6 ? u.z : u.w)));
;                     const float xv = (e & 1) ? bfhi(wd) : bflo(wd);
;                     a += w[j][e] * xv;
	v_rcp_f32_e32 v105, v100
	s_nop 0
	v_mul_f32_e32 v100, v108, v105
	v_pk_add_f32 v[102:103], v[96:97], 1.0 op_sel_hi:[1,0]
	v_pk_fma_f32 v[92:93], v[2:3], v[92:93], 0 op_sel_hi:[1,1,0]


; DEV float bflo(unsigned u) { return __uint_as_float(u << 16); }
; DEV float bfhi(unsigned u) { return __uint_as_float(u & 0xffff0000u); }
; DEV void gdn_prep_chunk(const Params& p, int item, unsigned char* lds) {
;     ...
;                 for (int j = 0; j < 4; ++j) {
;                     const uint4 u = raw[r + j];
;                     const unsigned wd = (e < 2 ? u.x : (e < 4 ? u.y : (e < 6 ? u.z : u.w)));
;                     const float xv = (e & 1) ? bfhi(wd) : bflo(wd);
;                     a += w[j][e] * xv;
	v_pk_fma_f32 v[92:93], v[6:7], v[82:83], v[92:93]


; DEV float bflo(unsigned u) { return __uint_as_float(u << 16); }
; DEV float bfhi(unsigned u) { return __uint_as_float(u & 0xffff0000u); }
; DEV void gdn_prep_chunk(const Params& p, int item, unsigned char* lds) {
;     ...
;                 for (int j = 0; j < 4; ++j) {
;                     const uint4 u = raw[r + j];
;                     const unsigned wd = (e < 2 ? u.x : (e < 4 ? u.y : (e < 6 ? u.z : u.w)));
;                     const float xv = (e & 1) ? bfhi(wd) : bflo(wd);
;                     a += w[j][e] * xv;
	v_rcp_f32_e32 v96, v103
	s_nop 0
	v_mul_f32_e32 v103, v71, v96
	v_lshlrev_b32_e32 v96, 16, v72
	v_and_b32_e32 v97, 0xffff0000, v72
	v_pk_fma_f32 v[92:93], v[10:11], v[90:91], v[92:93]

; DEV float bflo(unsigned u) { return __uint_as_float(u << 16); }
; DEV float bfhi(unsigned u) { return __uint_as_float(u & 0xffff0000u); }
; DEV void gdn_prep_chunk(const Params& p, int item, unsigned char* lds) {
;     ...
;                 for (int j = 0; j < 4; ++j) {
;                     const uint4 u = raw[r + j];
;                     const unsigned wd = (e < 2 ? u.x : (e < 4 ? u.y : (e < 6 ? u.z : u.w)));
;                     const float xv = (e & 1) ? bfhi(wd) : bflo(wd);
;                     a += w[j][e] * xv;
	v_pk_fma_f32 v[92:93], v[14:15], v[96:97], v[92:93]

; DEV float silu_f(float x) { return x / (1.f + __expf(-x)); }
	v_mul_f32_e32 v72, 0xbfb8aa3b, v92
	v_exp_f32_e32 v106, v72
	v_mul_f32_e32 v72, 0xbfb8aa3b, v93
	v_exp_f32_e32 v107, v72


; DEV float silu_f(float x) { return x / (1.f + __expf(-x)); }
	s_nop 0
	v_pk_add_f32 v[106:107], v[106:107], 1.0 op_sel_hi:[1,0]


; DEV float silu_f(float x) { return x / (1.f + __expf(-x)); }
	v_rcp_f32_e32 v71, v102
	s_nop 0
	v_mul_f32_e32 v102, v70, v71


; DEV float silu_f(float x) { return x / (1.f + __expf(-x)); }
; DEV void gdn_prep_chunk(const Params& p, int item, unsigned char* lds) {
;     ...
;                 y[e] = silu_f(a); ss += y[e] * y[e];
	v_rcp_f32_e32 v70, v107
	s_nop 0
	v_mul_f32_e32 v93, v93, v70


; DEV float bflo(unsigned u) { return __uint_as_float(u << 16); }
; DEV float bfhi(unsigned u) { return __uint_as_float(u & 0xffff0000u); }
; DEV void gdn_prep_chunk(const Params& p, int item, unsigned char* lds) {
;     ...
;                 for (int j = 0; j < 4; ++j) {
;                     const uint4 u = raw[r + j];
;                     const unsigned wd = (e < 2 ? u.x : (e < 4 ? u.y : (e < 6 ? u.z : u.w)));
;                     const float xv = (e & 1) ? bfhi(wd) : bflo(wd);
;                     a += w[j][e] * xv;
	v_lshlrev_b32_e32 v70, 16, v73
	v_and_b32_e32 v71, 0xffff0000, v73
	v_pk_fma_f32 v[72:73], v[4:5], v[88:89], 0 op_sel_hi:[1,1,0]

; DEV float bflo(unsigned u) { return __uint_as_float(u << 16); }
; DEV float bfhi(unsigned u) { return __uint_as_float(u & 0xffff0000u); }
; DEV void gdn_prep_chunk(const Params& p, int item, unsigned char* lds) {
;     ...
;                 for (int j = 0; j < 4; ++j) {
;                     const uint4 u = raw[r + j];
;                     const unsigned wd = (e < 2 ? u.x : (e < 4 ? u.y : (e < 6 ? u.z : u.w)));
;                     const float xv = (e & 1) ? bfhi(wd) : bflo(wd);
;                     a += w[j][e] * xv;
	v_pk_fma_f32 v[72:73], v[8:9], v[78:79], v[72:73]

; DEV float bflo(unsigned u) { return __uint_as_float(u << 16); }
; DEV float bfhi(unsigned u) { return __uint_as_float(u & 0xffff0000u); }
; DEV void gdn_prep_chunk(const Params& p, int item, unsigned char* lds) {
;     ...
;                 for (int j = 0; j < 4; ++j) {
;                     const uint4 u = raw[r + j];
;                     const unsigned wd = (e < 2 ? u.x : (e < 4 ? u.y : (e < 6 ? u.z : u.w)));
;                     const float xv = (e & 1) ? bfhi(wd) : bflo(wd);
;                     a += w[j][e] * xv;
	v_pk_fma_f32 v[72:73], v[12:13], v[74:75], v[72:73]

; DEV float bflo(unsigned u) { return __uint_as_float(u << 16); }
; DEV float bfhi(unsigned u) { return __uint_as_float(u & 0xffff0000u); }
; DEV void gdn_prep_chunk(const Params& p, int item, unsigned char* lds) {
;     ...
;                 for (int j = 0; j < 4; ++j) {
;                     const uint4 u = raw[r + j];
;                     const unsigned wd = (e < 2 ? u.x : (e < 4 ? u.y : (e < 6 ? u.z : u.w)));
;                     const float xv = (e & 1) ? bfhi(wd) : bflo(wd);
;                     a += w[j][e] * xv;
	v_pk_fma_f32 v[72:73], v[16:17], v[70:71], v[72:73]

; DEV float silu_f(float x) { return x / (1.f + __expf(-x)); }
; DEV void gdn_prep_chunk(const Params& p, int item, unsigned char* lds) {
;     ...
;                 y[e] = silu_f(a); ss += y[e] * y[e];
	v_mul_f32_e32 v88, 0xbfb8aa3b, v72
	v_mul_f32_e32 v89, 0xbfb8aa3b, v73
	v_exp_f32_e32 v88, v88
	v_exp_f32_e32 v89, v89


; DEV float silu_f(float x) { return x / (1.f + __expf(-x)); }
; DEV void gdn_prep_chunk(const Params& p, int item, unsigned char* lds) {
;     ...
;                 y[e] = silu_f(a); ss += y[e] * y[e];
	v_rcp_f32_e32 v105, v106
	s_nop 0
	v_mul_f32_e32 v92, v92, v105
	v_pk_add_f32 v[88:89], v[88:89], 1.0 op_sel_hi:[1,0]
	s_nop 0


; DEV float silu_f(float x) { return x / (1.f + __expf(-x)); }
; DEV void gdn_prep_chunk(const Params& p, int item, unsigned char* lds) {
;     ...
;                 y[e] = silu_f(a); ss += y[e] * y[e];
	s_nop 0


; DEV float silu_f(float x) { return x / (1.f + __expf(-x)); }
; DEV void gdn_prep_chunk(const Params& p, int item, unsigned char* lds) {
;     ...
;                 y[e] = silu_f(a); ss += y[e] * y[e];
	v_rcp_f32_e32 v105, v89
	s_nop 0
	v_mul_f32_e32 v89, v73, v105


; DEV float silu_f(float x) { return x / (1.f + __expf(-x)); }
; DEV void gdn_prep_chunk(const Params& p, int item, unsigned char* lds) {
;     ...
;                 y[e] = silu_f(a); ss += y[e] * y[e];
;             }
;             if (mat < 2) {
;                 ss += __shfl_xor(ss, 1); ss += __shfl_xor(ss, 2); ss += __shfl_xor(ss, 4); ss += __shfl_xor(ss, 8);
	v_rcp_f32_e32 v73, v88
	s_nop 0
	v_mul_f32_e32 v88, v72, v73
	s_and_saveexec_b64 s[36:37], s[6:7]
	s_cbranch_execz .LBB0_486
	v_pk_mul_f32 v[72:73], v[100:101], v[100:101]
	v_pk_mul_f32 v[106:107], v[102:103], v[102:103]
	v_add_f32_e32 v72, v72, v73
	v_add_f32_e32 v72, v72, v106
	v_pk_mul_f32 v[108:109], v[92:93], v[92:93]
	v_add_f32_e32 v72, v107, v72
	v_and_b32_e32 v105, 64, v182
	v_add_f32_e32 v72, v108, v72

; DEV void gdn_prep_chunk(const Params& p, int item, unsigned char* lds) {
;     ...
;             if (mat < 2) {
;                 ss += __shfl_xor(ss, 1); ss += __shfl_xor(ss, 2); ss += __shfl_xor(ss, 4); ss += __shfl_xor(ss, 8);
	v_add_u32_e32 v105, 64, v105
	v_pk_mul_f32 v[110:111], v[88:89], v[88:89]
	v_add_f32_e32 v72, v109, v72

; DEV void gdn_prep_chunk(const Params& p, int item, unsigned char* lds) {
;     ...
;             if (mat < 2) {
;                 ss += __shfl_xor(ss, 1); ss += __shfl_xor(ss, 2); ss += __shfl_xor(ss, 4); ss += __shfl_xor(ss, 8);
	v_add_f32_e32 v72, v110, v72
	v_add_f32_e32 v72, v111, v72


; DEV void gdn_prep_chunk(const Params& p, int item, unsigned char* lds) {
;     ...
;                 ss += __shfl_xor(ss, 1); ss += __shfl_xor(ss, 2); ss += __shfl_xor(ss, 4); ss += __shfl_xor(ss, 8);
	s_waitcnt lgkmcnt(0)
	s_nop 1
	v_add_f32_dpp v72, v72, v72 quad_perm:[1,0,3,2] row_mask:0xf bank_mask:0xf


; DEV void gdn_prep_chunk(const Params& p, int item, unsigned char* lds) {
;     ...
;                 ss += __shfl_xor(ss, 1); ss += __shfl_xor(ss, 2); ss += __shfl_xor(ss, 4); ss += __shfl_xor(ss, 8);
	s_nop 1


; DEV void gdn_prep_chunk(const Params& p, int item, unsigned char* lds) {
;     ...
;                 ss += __shfl_xor(ss, 1); ss += __shfl_xor(ss, 2); ss += __shfl_xor(ss, 4); ss += __shfl_xor(ss, 8);
	s_waitcnt lgkmcnt(0)
	s_nop 1
	v_add_f32_dpp v72, v72, v72 quad_perm:[2,3,0,1] row_mask:0xf bank_mask:0xf


; DEV void gdn_prep_chunk(const Params& p, int item, unsigned char* lds) {
;     ...
;                 ss += __shfl_xor(ss, 1); ss += __shfl_xor(ss, 2); ss += __shfl_xor(ss, 4); ss += __shfl_xor(ss, 8);
	s_nop 1


; DEV void gdn_prep_chunk(const Params& p, int item, unsigned char* lds) {
;     ...
;                 ss += __shfl_xor(ss, 1); ss += __shfl_xor(ss, 2); ss += __shfl_xor(ss, 4); ss += __shfl_xor(ss, 8);
	s_waitcnt lgkmcnt(0)
	s_nop 1
	v_add_f32_dpp v72, v72, v72 row_half_mirror row_mask:0xf bank_mask:0xf


; DEV void gdn_prep_chunk(const Params& p, int item, unsigned char* lds) {
;     ...
;                 ss += __shfl_xor(ss, 1); ss += __shfl_xor(ss, 2); ss += __shfl_xor(ss, 4); ss += __shfl_xor(ss, 8);
	s_nop 1


; DEV unsigned cvt_pk_bf16(float lo, float hi) { const f32x2_t v = {lo, hi}; const bf16x2_t b = __builtin_convertvector(v, bf16x2_t); return __builtin_bit_cast(unsigned, b); }
; DEV float bflo(unsigned u) { return __uint_as_float(u << 16); }
; DEV float bfhi(unsigned u) { return __uint_as_float(u & 0xffff0000u); }
; DEV float silu_f(float x) { return x / (1.f + __expf(-x)); }
; DEV void gdn_prep_chunk(const Params& p, int item, unsigned char* lds) {
;     ...
;                 for (int j = 0; j < 4; ++j) {
;                     const uint4 u = raw[r + j];
;                     const unsigned wd = (e < 2 ? u.x : (e < 4 ? u.y : (e < 6 ? u.z : u.w)));
;                     const float xv = (e & 1) ? bfhi(wd) : bflo(wd);
;                     a += w[j][e] * xv;
;                 }
;                 y[e] = silu_f(a); ss += y[e] * y[e];
;     ...
;                 ss += __shfl_xor(ss, 1); ss += __shfl_xor(ss, 2); ss += __shfl_xor(ss, 4); ss += __shfl_xor(ss, 8);
;                 float inv = rsqrtf(ss + EPS); if (mat == 0) inv *= 0.08838834764831845f;
; #pragma unroll
;                 for (int e = 0; e < 8; ++e) y[e] *= inv;
;             }
;             uint4 o; o.x = cvt_pk_bf16(y[0], y[1]); o.y = cvt_pk_bf16(y[2], y[3]); o.z = cvt_pk_bf16(y[4], y[5]); o.w = cvt_pk_bf16(y[6], y[7]);
;             *(uint4*)(dst + (tl0 + r) * QS + cv * 8) = o;
	s_waitcnt lgkmcnt(0)
	s_nop 1
	v_add_f32_dpp v72, v72, v72 row_mirror row_mask:0xf bank_mask:0xf
	v_add_f32_e32 v72, 0x358637bd, v72
	v_mul_f32_e32 v73, 0x4b800000, v72
	v_cmp_gt_f32_e32 vcc, s56, v72
	s_nop 1
	v_cndmask_b32_e32 v72, v72, v73, vcc
	v_rsq_f32_e32 v72, v72
	s_nop 0
	v_mul_f32_e32 v73, 0x45800000, v72
	v_cndmask_b32_e32 v72, v72, v73, vcc
	v_mul_f32_e32 v73, 0x3db504f3, v72
	v_cndmask_b32_e64 v72, v72, v73, s[4:5]
	v_pk_mul_f32 v[100:101], v[100:101], v[72:73] op_sel_hi:[1,0]
	v_pk_mul_f32 v[102:103], v[102:103], v[72:73] op_sel_hi:[1,0]
	v_pk_mul_f32 v[92:93], v[92:93], v[72:73] op_sel_hi:[1,0]
	v_pk_mul_f32 v[88:89], v[88:89], v[72:73] op_sel_hi:[1,0]
.LBB0_486:
	s_or_b64 exec, exec, s[36:37]
	v_pk_fma_f32 v[86:87], v[18:19], v[86:87], 0 op_sel_hi:[1,1,0]
	s_waitcnt vmcnt(8)
	v_lshlrev_b32_e32 v72, 16, v66
	v_pk_fma_f32 v[86:87], v[22:23], v[80:81], v[86:87]
	v_and_b32_e32 v73, 0xffff0000, v66
	v_pk_fma_f32 v[86:87], v[26:27], v[76:77], v[86:87]
	v_cvt_pk_bf16_f32 v100, v100, v101
	v_pk_fma_f32 v[86:87], v[30:31], v[72:73], v[86:87]
	v_cvt_pk_bf16_f32 v101, v102, v103
	v_mul_f32_e32 v66, 0xbfb8aa3b, v86
	v_exp_f32_e32 v106, v66
	v_mul_f32_e32 v66, 0xbfb8aa3b, v87
	v_exp_f32_e32 v107, v66
	v_cvt_pk_bf16_f32 v103, v88, v89
	v_cvt_pk_bf16_f32 v102, v92, v93
	v_add_u32_e32 v93, 0x110, v104
	v_pk_add_f32 v[88:89], v[106:107], 1.0 op_sel_hi:[1,0]
	v_add_u32_e32 v104, v132, v93


; DEV float bflo(unsigned u) { return __uint_as_float(u << 16); }
; DEV float bfhi(unsigned u) { return __uint_as_float(u & 0xffff0000u); }
; DEV void gdn_prep_chunk(const Params& p, int item, unsigned char* lds) {
;     ...
;                 for (int j = 0; j < 4; ++j) {
;                     const uint4 u = raw[r + j];
;                     const unsigned wd = (e < 2 ? u.x : (e < 4 ? u.y : (e < 6 ? u.z : u.w)));
;                     const float xv = (e & 1) ? bfhi(wd) : bflo(wd);
;                     a += w[j][e] * xv;
;     ...
;             *(uint4*)(dst + (tl0 + r) * QS + cv * 8) = o;
	ds_write_b128 v104, v[100:103]
	v_pk_fma_f32 v[82:83], v[2:3], v[82:83], 0 op_sel_hi:[1,1,0]


; DEV float bflo(unsigned u) { return __uint_as_float(u << 16); }
; DEV float bfhi(unsigned u) { return __uint_as_float(u & 0xffff0000u); }
; DEV float silu_f(float x) { return x / (1.f + __expf(-x)); }
; DEV void gdn_prep_chunk(const Params& p, int item, unsigned char* lds) {
;     ...
;                     const float xv = (e & 1) ? bfhi(wd) : bflo(wd);
;     ...
;                 y[e] = silu_f(a); ss += y[e] * y[e];
	v_rcp_f32_e32 v66, v89
	s_nop 0
	v_mul_f32_e32 v103, v87, v66
	v_lshlrev_b32_e32 v100, 16, v67


; DEV float bflo(unsigned u) { return __uint_as_float(u << 16); }
; DEV float bfhi(unsigned u) { return __uint_as_float(u & 0xffff0000u); }
; DEV void gdn_prep_chunk(const Params& p, int item, unsigned char* lds) {
;     ...
;                 for (int j = 0; j < 4; ++j) {
;                     const uint4 u = raw[r + j];
;                     const unsigned wd = (e < 2 ? u.x : (e < 4 ? u.y : (e < 6 ? u.z : u.w)));
;                     const float xv = (e & 1) ? bfhi(wd) : bflo(wd);
;                     a += w[j][e] * xv;
	v_and_b32_e32 v101, 0xffff0000, v67
	v_pk_fma_f32 v[66:67], v[20:21], v[84:85], 0 op_sel_hi:[1,1,0]

; DEV float bflo(unsigned u) { return __uint_as_float(u << 16); }
; DEV float bfhi(unsigned u) { return __uint_as_float(u & 0xffff0000u); }
; DEV void gdn_prep_chunk(const Params& p, int item, unsigned char* lds) {
;     ...
;                 for (int j = 0; j < 4; ++j) {
;                     const uint4 u = raw[r + j];
;                     const unsigned wd = (e < 2 ? u.x : (e < 4 ? u.y : (e < 6 ? u.z : u.w)));
;                     const float xv = (e & 1) ? bfhi(wd) : bflo(wd);
;                     a += w[j][e] * xv;
	v_pk_fma_f32 v[66:67], v[24:25], v[94:95], v[66:67]

; DEV float bflo(unsigned u) { return __uint_as_float(u << 16); }
; DEV float bfhi(unsigned u) { return __uint_as_float(u & 0xffff0000u); }
; DEV void gdn_prep_chunk(const Params& p, int item, unsigned char* lds) {
;     ...
;                 for (int j = 0; j < 4; ++j) {
;                     const uint4 u = raw[r + j];
;                     const unsigned wd = (e < 2 ? u.x : (e < 4 ? u.y : (e < 6 ? u.z : u.w)));
;                     const float xv = (e & 1) ? bfhi(wd) : bflo(wd);
;                     a += w[j][e] * xv;
	v_pk_fma_f32 v[66:67], v[28:29], v[98:99], v[66:67]

; DEV float bflo(unsigned u) { return __uint_as_float(u << 16); }
; DEV float bfhi(unsigned u) { return __uint_as_float(u & 0xffff0000u); }
; DEV void gdn_prep_chunk(const Params& p, int item, unsigned char* lds) {
;     ...
;                 for (int j = 0; j < 4; ++j) {
;                     const uint4 u = raw[r + j];
;                     const unsigned wd = (e < 2 ? u.x : (e < 4 ? u.y : (e < 6 ? u.z : u.w)));
;                     const float xv = (e & 1) ? bfhi(wd) : bflo(wd);
;                     a += w[j][e] * xv;
	v_pk_fma_f32 v[66:67], v[32:33], v[100:101], v[66:67]

; DEV float silu_f(float x) { return x / (1.f + __expf(-x)); }
; DEV void gdn_prep_chunk(const Params& p, int item, unsigned char* lds) {
;     ...
;                 y[e] = silu_f(a); ss += y[e] * y[e];
	v_mul_f32_e32 v84, 0xbfb8aa3b, v66
	v_mul_f32_e32 v85, 0xbfb8aa3b, v67
	v_exp_f32_e32 v84, v84
	v_exp_f32_e32 v85, v85


; DEV float bflo(unsigned u) { return __uint_as_float(u << 16); }
; DEV float bfhi(unsigned u) { return __uint_as_float(u & 0xffff0000u); }
; DEV float silu_f(float x) { return x / (1.f + __expf(-x)); }
; DEV void gdn_prep_chunk(const Params& p, int item, unsigned char* lds) {
;     ...
;                 for (int j = 0; j < 4; ++j) {
;                     const uint4 u = raw[r + j];
;                     const unsigned wd = (e < 2 ? u.x : (e < 4 ? u.y : (e < 6 ? u.z : u.w)));
;                     const float xv = (e & 1) ? bfhi(wd) : bflo(wd);
;                     a += w[j][e] * xv;
;     ...
;                 y[e] = silu_f(a); ss += y[e] * y[e];
	v_rcp_f32_e32 v87, v88
	s_nop 0
	v_mul_f32_e32 v102, v86, v87
	v_pk_add_f32 v[84:85], v[84:85], 1.0 op_sel_hi:[1,0]
	v_pk_fma_f32 v[82:83], v[6:7], v[90:91], v[82:83]


; DEV float bflo(unsigned u) { return __uint_as_float(u << 16); }
; DEV float bfhi(unsigned u) { return __uint_as_float(u & 0xffff0000u); }
; DEV void gdn_prep_chunk(const Params& p, int item, unsigned char* lds) {
;     ...
;                 for (int j = 0; j < 4; ++j) {
;                     const uint4 u = raw[r + j];
;                     const unsigned wd = (e < 2 ? u.x : (e < 4 ? u.y : (e < 6 ? u.z : u.w)));
;                     const float xv = (e & 1) ? bfhi(wd) : bflo(wd);
;                     a += w[j][e] * xv;
	v_pk_fma_f32 v[82:83], v[10:11], v[96:97], v[82:83]


; DEV float bflo(unsigned u) { return __uint_as_float(u << 16); }
; DEV float bfhi(unsigned u) { return __uint_as_float(u & 0xffff0000u); }
; DEV float silu_f(float x) { return x / (1.f + __expf(-x)); }
; DEV void gdn_prep_chunk(const Params& p, int item, unsigned char* lds) {
;     ...
;                 for (int j = 0; j < 4; ++j) {
;                     const uint4 u = raw[r + j];
;                     const unsigned wd = (e < 2 ? u.x : (e < 4 ? u.y : (e < 6 ? u.z : u.w)));
;                     const float xv = (e & 1) ? bfhi(wd) : bflo(wd);
;                     a += w[j][e] * xv;
;                 }
;                 y[e] = silu_f(a); ss += y[e] * y[e];
	v_lshlrev_b32_e32 v92, 16, v68
	v_and_b32_e32 v93, 0xffff0000, v68
	v_pk_fma_f32 v[82:83], v[14:15], v[92:93], v[82:83]
	v_rcp_f32_e32 v86, v85
	s_nop 0
	v_mul_f32_e32 v67, v67, v86
	v_mul_f32_e32 v68, 0xbfb8aa3b, v82
	v_exp_f32_e32 v86, v68
	v_mul_f32_e32 v68, 0xbfb8aa3b, v83

; DEV float silu_f(float x) { return x / (1.f + __expf(-x)); }
; DEV void gdn_prep_chunk(const Params& p, int item, unsigned char* lds) {
;     ...
;                 y[e] = silu_f(a); ss += y[e] * y[e];
	v_exp_f32_e32 v87, v68


; DEV float silu_f(float x) { return x / (1.f + __expf(-x)); }
; DEV void gdn_prep_chunk(const Params& p, int item, unsigned char* lds) {
;     ...
;                 y[e] = silu_f(a); ss += y[e] * y[e];
	s_nop 0
	v_pk_add_f32 v[86:87], v[86:87], 1.0 op_sel_hi:[1,0]


; DEV float silu_f(float x) { return x / (1.f + __expf(-x)); }
; DEV void gdn_prep_chunk(const Params& p, int item, unsigned char* lds) {
;     ...
;                 y[e] = silu_f(a); ss += y[e] * y[e];
	v_rcp_f32_e32 v68, v84
	s_nop 0
	v_mul_f32_e32 v66, v66, v68


; DEV float bflo(unsigned u) { return __uint_as_float(u << 16); }
; DEV float bfhi(unsigned u) { return __uint_as_float(u & 0xffff0000u); }
; DEV float silu_f(float x) { return x / (1.f + __expf(-x)); }
; DEV void gdn_prep_chunk(const Params& p, int item, unsigned char* lds) {
;     ...
;                     const float xv = (e & 1) ? bfhi(wd) : bflo(wd);
;     ...
;                 y[e] = silu_f(a); ss += y[e] * y[e];
	v_rcp_f32_e32 v68, v87
	s_nop 0
	v_mul_f32_e32 v83, v83, v68
	v_lshlrev_b32_e32 v88, 16, v69


; DEV float bflo(unsigned u) { return __uint_as_float(u << 16); }
; DEV float bfhi(unsigned u) { return __uint_as_float(u & 0xffff0000u); }
; DEV void gdn_prep_chunk(const Params& p, int item, unsigned char* lds) {
;     ...
;                 for (int j = 0; j < 4; ++j) {
;                     const uint4 u = raw[r + j];
;                     const unsigned wd = (e < 2 ? u.x : (e < 4 ? u.y : (e < 6 ? u.z : u.w)));
;                     const float xv = (e & 1) ? bfhi(wd) : bflo(wd);
;                     a += w[j][e] * xv;
	v_and_b32_e32 v89, 0xffff0000, v69
	v_pk_fma_f32 v[68:69], v[4:5], v[78:79], 0 op_sel_hi:[1,1,0]

; DEV float bflo(unsigned u) { return __uint_as_float(u << 16); }
; DEV float bfhi(unsigned u) { return __uint_as_float(u & 0xffff0000u); }
; DEV void gdn_prep_chunk(const Params& p, int item, unsigned char* lds) {
;     ...
;                 for (int j = 0; j < 4; ++j) {
;                     const uint4 u = raw[r + j];
;                     const unsigned wd = (e < 2 ? u.x : (e < 4 ? u.y : (e < 6 ? u.z : u.w)));
;                     const float xv = (e & 1) ? bfhi(wd) : bflo(wd);
;                     a += w[j][e] * xv;
	v_pk_fma_f32 v[68:69], v[8:9], v[74:75], v[68:69]

; DEV float bflo(unsigned u) { return __uint_as_float(u << 16); }
; DEV float bfhi(unsigned u) { return __uint_as_float(u & 0xffff0000u); }
; DEV void gdn_prep_chunk(const Params& p, int item, unsigned char* lds) {
;     ...
;                 for (int j = 0; j < 4; ++j) {
;                     const uint4 u = raw[r + j];
;                     const unsigned wd = (e < 2 ? u.x : (e < 4 ? u.y : (e < 6 ? u.z : u.w)));
;                     const float xv = (e & 1) ? bfhi(wd) : bflo(wd);
;                     a += w[j][e] * xv;
	v_pk_fma_f32 v[68:69], v[12:13], v[70:71], v[68:69]

; DEV float bflo(unsigned u) { return __uint_as_float(u << 16); }
; DEV float bfhi(unsigned u) { return __uint_as_float(u & 0xffff0000u); }
; DEV void gdn_prep_chunk(const Params& p, int item, unsigned char* lds) {
;     ...
;                 for (int j = 0; j < 4; ++j) {
;                     const uint4 u = raw[r + j];
;                     const unsigned wd = (e < 2 ? u.x : (e < 4 ? u.y : (e < 6 ? u.z : u.w)));
;                     const float xv = (e & 1) ? bfhi(wd) : bflo(wd);
;                     a += w[j][e] * xv;
	v_pk_fma_f32 v[68:69], v[16:17], v[88:89], v[68:69]

; DEV float silu_f(float x) { return x / (1.f + __expf(-x)); }
; DEV void gdn_prep_chunk(const Params& p, int item, unsigned char* lds) {
;     ...
;                 y[e] = silu_f(a); ss += y[e] * y[e];
	v_mul_f32_e32 v78, 0xbfb8aa3b, v68
	v_mul_f32_e32 v79, 0xbfb8aa3b, v69
	v_exp_f32_e32 v78, v78
	v_exp_f32_e32 v79, v79


; DEV float silu_f(float x) { return x / (1.f + __expf(-x)); }
; DEV void gdn_prep_chunk(const Params& p, int item, unsigned char* lds) {
;     ...
;                 y[e] = silu_f(a); ss += y[e] * y[e];
	v_rcp_f32_e32 v84, v86
	s_nop 0
	v_mul_f32_e32 v82, v82, v84
	v_pk_add_f32 v[78:79], v[78:79], 1.0 op_sel_hi:[1,0]
	s_nop 0


; DEV float silu_f(float x) { return x / (1.f + __expf(-x)); }
; DEV void gdn_prep_chunk(const Params& p, int item, unsigned char* lds) {
;     ...
;                 y[e] = silu_f(a); ss += y[e] * y[e];
	s_nop 0


; DEV float silu_f(float x) { return x / (1.f + __expf(-x)); }
; DEV void gdn_prep_chunk(const Params& p, int item, unsigned char* lds) {
;     ...
;                 y[e] = silu_f(a); ss += y[e] * y[e];
	v_rcp_f32_e32 v84, v79
	s_nop 0
	v_mul_f32_e32 v69, v69, v84


; DEV float silu_f(float x) { return x / (1.f + __expf(-x)); }
; DEV void gdn_prep_chunk(const Params& p, int item, unsigned char* lds) {
;     ...
;                 y[e] = silu_f(a); ss += y[e] * y[e];
;             }
;             if (mat < 2) {
;                 ss += __shfl_xor(ss, 1); ss += __shfl_xor(ss, 2); ss += __shfl_xor(ss, 4); ss += __shfl_xor(ss, 8);
	v_rcp_f32_e32 v79, v78
	s_nop 0
	v_mul_f32_e32 v68, v68, v79
	s_and_saveexec_b64 s[36:37], s[6:7]
	s_cbranch_execz .LBB0_488
	v_pk_mul_f32 v[78:79], v[102:103], v[102:103]
	v_pk_mul_f32 v[84:85], v[66:67], v[66:67]
	v_add_f32_e32 v78, v78, v79
	v_add_f32_e32 v78, v78, v84
	v_pk_mul_f32 v[86:87], v[82:83], v[82:83]
	v_add_f32_e32 v78, v85, v78
	v_and_b32_e32 v84, 64, v182
	v_add_f32_e32 v78, v86, v78

; DEV void gdn_prep_chunk(const Params& p, int item, unsigned char* lds) {
;     ...
;             if (mat < 2) {
;                 ss += __shfl_xor(ss, 1); ss += __shfl_xor(ss, 2); ss += __shfl_xor(ss, 4); ss += __shfl_xor(ss, 8);
	v_add_u32_e32 v84, 64, v84
	v_pk_mul_f32 v[106:107], v[68:69], v[68:69]
	v_add_f32_e32 v78, v87, v78

; DEV void gdn_prep_chunk(const Params& p, int item, unsigned char* lds) {
;     ...
;             if (mat < 2) {
;                 ss += __shfl_xor(ss, 1); ss += __shfl_xor(ss, 2); ss += __shfl_xor(ss, 4); ss += __shfl_xor(ss, 8);
	v_add_f32_e32 v78, v106, v78
	v_add_f32_e32 v78, v107, v78


; DEV void gdn_prep_chunk(const Params& p, int item, unsigned char* lds) {
;     ...
;                 ss += __shfl_xor(ss, 1); ss += __shfl_xor(ss, 2); ss += __shfl_xor(ss, 4); ss += __shfl_xor(ss, 8);
	s_waitcnt lgkmcnt(0)
	s_nop 1
	v_add_f32_dpp v78, v78, v78 quad_perm:[1,0,3,2] row_mask:0xf bank_mask:0xf


; DEV void gdn_prep_chunk(const Params& p, int item, unsigned char* lds) {
;     ...
;                 ss += __shfl_xor(ss, 1); ss += __shfl_xor(ss, 2); ss += __shfl_xor(ss, 4); ss += __shfl_xor(ss, 8);
	s_nop 1


; DEV void gdn_prep_chunk(const Params& p, int item, unsigned char* lds) {
;     ...
;                 ss += __shfl_xor(ss, 1); ss += __shfl_xor(ss, 2); ss += __shfl_xor(ss, 4); ss += __shfl_xor(ss, 8);
	s_waitcnt lgkmcnt(0)
	s_nop 1
	v_add_f32_dpp v78, v78, v78 quad_perm:[2,3,0,1] row_mask:0xf bank_mask:0xf


; DEV void gdn_prep_chunk(const Params& p, int item, unsigned char* lds) {
;     ...
;                 ss += __shfl_xor(ss, 1); ss += __shfl_xor(ss, 2); ss += __shfl_xor(ss, 4); ss += __shfl_xor(ss, 8);
	s_nop 1


; DEV void gdn_prep_chunk(const Params& p, int item, unsigned char* lds) {
;     ...
;                 ss += __shfl_xor(ss, 1); ss += __shfl_xor(ss, 2); ss += __shfl_xor(ss, 4); ss += __shfl_xor(ss, 8);
	s_waitcnt lgkmcnt(0)
	s_nop 1
	v_add_f32_dpp v78, v78, v78 row_half_mirror row_mask:0xf bank_mask:0xf


; DEV void gdn_prep_chunk(const Params& p, int item, unsigned char* lds) {
;     ...
;                 ss += __shfl_xor(ss, 1); ss += __shfl_xor(ss, 2); ss += __shfl_xor(ss, 4); ss += __shfl_xor(ss, 8);
	s_nop 1


; DEV unsigned cvt_pk_bf16(float lo, float hi) { const f32x2_t v = {lo, hi}; const bf16x2_t b = __builtin_convertvector(v, bf16x2_t); return __builtin_bit_cast(unsigned, b); }
; DEV float bflo(unsigned u) { return __uint_as_float(u << 16); }
; DEV float bfhi(unsigned u) { return __uint_as_float(u & 0xffff0000u); }
; DEV float silu_f(float x) { return x / (1.f + __expf(-x)); }
; DEV void gdn_prep_chunk(const Params& p, int item, unsigned char* lds) {
;     ...
;                 for (int j = 0; j < 4; ++j) {
;                     const uint4 u = raw[r + j];
;                     const unsigned wd = (e < 2 ? u.x : (e < 4 ? u.y : (e < 6 ? u.z : u.w)));
;                     const float xv = (e & 1) ? bfhi(wd) : bflo(wd);
;                     a += w[j][e] * xv;
;                 }
;                 y[e] = silu_f(a); ss += y[e] * y[e];
;     ...
;                 ss += __shfl_xor(ss, 1); ss += __shfl_xor(ss, 2); ss += __shfl_xor(ss, 4); ss += __shfl_xor(ss, 8);
;                 float inv = rsqrtf(ss + EPS); if (mat == 0) inv *= 0.08838834764831845f;
; #pragma unroll
;                 for (int e = 0; e < 8; ++e) y[e] *= inv;
;             }
;             uint4 o; o.x = cvt_pk_bf16(y[0], y[1]); o.y = cvt_pk_bf16(y[2], y[3]); o.z = cvt_pk_bf16(y[4], y[5]); o.w = cvt_pk_bf16(y[6], y[7]);
;             *(uint4*)(dst + (tl0 + r) * QS + cv * 8) = o;
	s_waitcnt lgkmcnt(0)
	s_nop 1
	v_add_f32_dpp v78, v78, v78 row_mirror row_mask:0xf bank_mask:0xf
	v_add_f32_e32 v78, 0x358637bd, v78
	v_mul_f32_e32 v79, 0x4b800000, v78
	v_cmp_gt_f32_e32 vcc, s56, v78
	s_nop 1
	v_cndmask_b32_e32 v78, v78, v79, vcc
	v_rsq_f32_e32 v78, v78
	s_nop 0
	v_mul_f32_e32 v79, 0x45800000, v78
	v_cndmask_b32_e32 v78, v78, v79, vcc
	v_mul_f32_e32 v79, 0x3db504f3, v78
	v_cndmask_b32_e64 v78, v78, v79, s[4:5]
	v_pk_mul_f32 v[102:103], v[102:103], v[78:79] op_sel_hi:[1,0]
	v_pk_mul_f32 v[66:67], v[66:67], v[78:79] op_sel_hi:[1,0]
	v_pk_mul_f32 v[82:83], v[82:83], v[78:79] op_sel_hi:[1,0]
	v_pk_mul_f32 v[68:69], v[68:69], v[78:79] op_sel_hi:[1,0]
.LBB0_488:
	s_or_b64 exec, exec, s[36:37]
	v_pk_fma_f32 v[78:79], v[18:19], v[80:81], 0 op_sel_hi:[1,1,0]
	s_waitcnt vmcnt(7)
	v_lshlrev_b32_e32 v86, 16, v62
	v_pk_fma_f32 v[78:79], v[22:23], v[76:77], v[78:79]
	v_and_b32_e32 v87, 0xffff0000, v62
	v_pk_fma_f32 v[78:79], v[26:27], v[72:73], v[78:79]
	v_and_b32_e32 v85, 0xffff0000, v63
	v_pk_fma_f32 v[106:107], v[30:31], v[86:87], v[78:79]
	v_cvt_pk_bf16_f32 v79, v66, v67
	v_mul_f32_e32 v62, 0xbfb8aa3b, v106
	v_exp_f32_e32 v80, v62
	v_mul_f32_e32 v62, 0xbfb8aa3b, v107
	v_exp_f32_e32 v81, v62
	v_cvt_pk_bf16_f32 v78, v102, v103
	v_pk_add_f32 v[66:67], v[80:81], 1.0 op_sel_hi:[1,0]
	s_nop 0


; DEV unsigned cvt_pk_bf16(float lo, float hi) { const f32x2_t v = {lo, hi}; const bf16x2_t b = __builtin_convertvector(v, bf16x2_t); return __builtin_bit_cast(unsigned, b); }
; DEV void gdn_prep_chunk(const Params& p, int item, unsigned char* lds) {
;     ...
;             uint4 o; o.x = cvt_pk_bf16(y[0], y[1]); o.y = cvt_pk_bf16(y[2], y[3]); o.z = cvt_pk_bf16(y[4], y[5]); o.w = cvt_pk_bf16(y[6], y[7]);
;             *(uint4*)(dst + (tl0 + r) * QS + cv * 8) = o;
	v_cvt_pk_bf16_f32 v81, v68, v69
	v_cvt_pk_bf16_f32 v80, v82, v83
	ds_write_b128 v104, v[78:81] offset:272


; DEV float silu_f(float x) { return x / (1.f + __expf(-x)); }
; DEV void gdn_prep_chunk(const Params& p, int item, unsigned char* lds) {
;     ...
;                 y[e] = silu_f(a); ss += y[e] * y[e];
	v_rcp_f32_e32 v62, v67
	s_nop 0
	v_mul_f32_e32 v67, v107, v62


; DEV float bflo(unsigned u) { return __uint_as_float(u << 16); }
; DEV float bfhi(unsigned u) { return __uint_as_float(u & 0xffff0000u); }
; DEV void gdn_prep_chunk(const Params& p, int item, unsigned char* lds) {
;     ...
;                 for (int j = 0; j < 4; ++j) {
;                     const uint4 u = raw[r + j];
;                     const unsigned wd = (e < 2 ? u.x : (e < 4 ? u.y : (e < 6 ? u.z : u.w)));
;                     const float xv = (e & 1) ? bfhi(wd) : bflo(wd);
;                     a += w[j][e] * xv;
	v_lshlrev_b32_e32 v84, 16, v63
	v_pk_fma_f32 v[62:63], v[20:21], v[94:95], 0 op_sel_hi:[1,1,0]

; DEV float bflo(unsigned u) { return __uint_as_float(u << 16); }
; DEV float bfhi(unsigned u) { return __uint_as_float(u & 0xffff0000u); }
; DEV void gdn_prep_chunk(const Params& p, int item, unsigned char* lds) {
;     ...
;                 for (int j = 0; j < 4; ++j) {
;                     const uint4 u = raw[r + j];
;                     const unsigned wd = (e < 2 ? u.x : (e < 4 ? u.y : (e < 6 ? u.z : u.w)));
;                     const float xv = (e & 1) ? bfhi(wd) : bflo(wd);
;                     a += w[j][e] * xv;
	v_pk_fma_f32 v[62:63], v[24:25], v[98:99], v[62:63]

; DEV float bflo(unsigned u) { return __uint_as_float(u << 16); }
; DEV float bfhi(unsigned u) { return __uint_as_float(u & 0xffff0000u); }
; DEV void gdn_prep_chunk(const Params& p, int item, unsigned char* lds) {
;     ...
;                 for (int j = 0; j < 4; ++j) {
;                     const uint4 u = raw[r + j];
;                     const unsigned wd = (e < 2 ? u.x : (e < 4 ? u.y : (e < 6 ? u.z : u.w)));
;                     const float xv = (e & 1) ? bfhi(wd) : bflo(wd);
;                     a += w[j][e] * xv;
	v_pk_fma_f32 v[62:63], v[28:29], v[100:101], v[62:63]

; DEV float bflo(unsigned u) { return __uint_as_float(u << 16); }
; DEV float bfhi(unsigned u) { return __uint_as_float(u & 0xffff0000u); }
; DEV void gdn_prep_chunk(const Params& p, int item, unsigned char* lds) {
;     ...
;                 for (int j = 0; j < 4; ++j) {
;                     const uint4 u = raw[r + j];
;                     const unsigned wd = (e < 2 ? u.x : (e < 4 ? u.y : (e < 6 ? u.z : u.w)));
;                     const float xv = (e & 1) ? bfhi(wd) : bflo(wd);
;                     a += w[j][e] * xv;
	v_pk_fma_f32 v[62:63], v[32:33], v[84:85], v[62:63]

; DEV float silu_f(float x) { return x / (1.f + __expf(-x)); }
; DEV void gdn_prep_chunk(const Params& p, int item, unsigned char* lds) {
;     ...
;                 y[e] = silu_f(a); ss += y[e] * y[e];
	v_mul_f32_e32 v68, 0xbfb8aa3b, v62
	v_mul_f32_e32 v69, 0xbfb8aa3b, v63
	v_exp_f32_e32 v68, v68
	v_exp_f32_e32 v69, v69


; DEV float bflo(unsigned u) { return __uint_as_float(u << 16); }
; DEV float bfhi(unsigned u) { return __uint_as_float(u & 0xffff0000u); }
; DEV float silu_f(float x) { return x / (1.f + __expf(-x)); }
; DEV void gdn_prep_chunk(const Params& p, int item, unsigned char* lds) {
;     ...
;                     const float xv = (e & 1) ? bfhi(wd) : bflo(wd);
;     ...
;                 y[e] = silu_f(a); ss += y[e] * y[e];
	v_rcp_f32_e32 v78, v66
	s_nop 0
	v_mul_f32_e32 v66, v106, v78
	v_pk_add_f32 v[68:69], v[68:69], 1.0 op_sel_hi:[1,0]
	v_and_b32_e32 v83, 0xffff0000, v64


; DEV float bflo(unsigned u) { return __uint_as_float(u << 16); }
; DEV float bfhi(unsigned u) { return __uint_as_float(u & 0xffff0000u); }
; DEV float silu_f(float x) { return x / (1.f + __expf(-x)); }
; DEV void gdn_prep_chunk(const Params& p, int item, unsigned char* lds) {
;     ...
;                 for (int j = 0; j < 4; ++j) {
;                     const uint4 u = raw[r + j];
;                     const unsigned wd = (e < 2 ? u.x : (e < 4 ? u.y : (e < 6 ? u.z : u.w)));
;                     const float xv = (e & 1) ? bfhi(wd) : bflo(wd);
;                     a += w[j][e] * xv;
;     ...
;                 y[e] = silu_f(a); ss += y[e] * y[e];
	v_rcp_f32_e32 v78, v69
	s_nop 0
	v_mul_f32_e32 v63, v63, v78
	v_pk_fma_f32 v[78:79], v[2:3], v[90:91], 0 op_sel_hi:[1,1,0]
	v_lshlrev_b32_e32 v82, 16, v64
	v_pk_fma_f32 v[78:79], v[6:7], v[96:97], v[78:79]

; DEV float bflo(unsigned u) { return __uint_as_float(u << 16); }
; DEV float bfhi(unsigned u) { return __uint_as_float(u & 0xffff0000u); }
; DEV void gdn_prep_chunk(const Params& p, int item, unsigned char* lds) {
;     ...
;                 for (int j = 0; j < 4; ++j) {
;                     const uint4 u = raw[r + j];
;                     const unsigned wd = (e < 2 ? u.x : (e < 4 ? u.y : (e < 6 ? u.z : u.w)));
;                     const float xv = (e & 1) ? bfhi(wd) : bflo(wd);
;                     a += w[j][e] * xv;
	v_pk_fma_f32 v[78:79], v[10:11], v[92:93], v[78:79]

; DEV float bflo(unsigned u) { return __uint_as_float(u << 16); }
; DEV float bfhi(unsigned u) { return __uint_as_float(u & 0xffff0000u); }
; DEV void gdn_prep_chunk(const Params& p, int item, unsigned char* lds) {
;     ...
;                 for (int j = 0; j < 4; ++j) {
;                     const uint4 u = raw[r + j];
;                     const unsigned wd = (e < 2 ? u.x : (e < 4 ? u.y : (e < 6 ? u.z : u.w)));
;                     const float xv = (e & 1) ? bfhi(wd) : bflo(wd);
;                     a += w[j][e] * xv;
	v_pk_fma_f32 v[78:79], v[14:15], v[82:83], v[78:79]

; DEV float silu_f(float x) { return x / (1.f + __expf(-x)); }
; DEV void gdn_prep_chunk(const Params& p, int item, unsigned char* lds) {
;     ...
;                 y[e] = silu_f(a); ss += y[e] * y[e];
	v_mul_f32_e32 v64, 0xbfb8aa3b, v78
	v_exp_f32_e32 v80, v64
	v_mul_f32_e32 v64, 0xbfb8aa3b, v79
	v_exp_f32_e32 v81, v64


; DEV float silu_f(float x) { return x / (1.f + __expf(-x)); }
; DEV void gdn_prep_chunk(const Params& p, int item, unsigned char* lds) {
;     ...
;                 y[e] = silu_f(a); ss += y[e] * y[e];
	s_nop 0
	v_pk_add_f32 v[90:91], v[80:81], 1.0 op_sel_hi:[1,0]


; DEV float silu_f(float x) { return x / (1.f + __expf(-x)); }
; DEV void gdn_prep_chunk(const Params& p, int item, unsigned char* lds) {
;     ...
;                 y[e] = silu_f(a); ss += y[e] * y[e];
	v_rcp_f32_e32 v64, v68
	s_nop 0
	v_mul_f32_e32 v62, v62, v64


; DEV float silu_f(float x) { return x / (1.f + __expf(-x)); }
; DEV void gdn_prep_chunk(const Params& p, int item, unsigned char* lds) {
;     ...
;                 y[e] = silu_f(a); ss += y[e] * y[e];
	v_rcp_f32_e32 v64, v91
	s_nop 0
	v_mul_f32_e32 v69, v79, v64


; DEV float bflo(unsigned u) { return __uint_as_float(u << 16); }
; DEV float bfhi(unsigned u) { return __uint_as_float(u & 0xffff0000u); }
; DEV void gdn_prep_chunk(const Params& p, int item, unsigned char* lds) {
;     ...
;                     const uint4 u = raw[r + j];
;                     const unsigned wd = (e < 2 ? u.x : (e < 4 ? u.y : (e < 6 ? u.z : u.w)));
;                     const float xv = (e & 1) ? bfhi(wd) : bflo(wd);
;                     a += w[j][e] * xv;
	v_lshlrev_b32_e32 v80, 16, v65
	v_and_b32_e32 v81, 0xffff0000, v65
	v_pk_fma_f32 v[64:65], v[4:5], v[74:75], 0 op_sel_hi:[1,1,0]

; DEV float bflo(unsigned u) { return __uint_as_float(u << 16); }
; DEV float bfhi(unsigned u) { return __uint_as_float(u & 0xffff0000u); }
; DEV void gdn_prep_chunk(const Params& p, int item, unsigned char* lds) {
;     ...
;                 for (int j = 0; j < 4; ++j) {
;                     const uint4 u = raw[r + j];
;                     const unsigned wd = (e < 2 ? u.x : (e < 4 ? u.y : (e < 6 ? u.z : u.w)));
;                     const float xv = (e & 1) ? bfhi(wd) : bflo(wd);
;                     a += w[j][e] * xv;
	v_pk_fma_f32 v[64:65], v[8:9], v[70:71], v[64:65]

; DEV float bflo(unsigned u) { return __uint_as_float(u << 16); }
; DEV float bfhi(unsigned u) { return __uint_as_float(u & 0xffff0000u); }
; DEV void gdn_prep_chunk(const Params& p, int item, unsigned char* lds) {
;     ...
;                 for (int j = 0; j < 4; ++j) {
;                     const uint4 u = raw[r + j];
;                     const unsigned wd = (e < 2 ? u.x : (e < 4 ? u.y : (e < 6 ? u.z : u.w)));
;                     const float xv = (e & 1) ? bfhi(wd) : bflo(wd);
;                     a += w[j][e] * xv;
	v_pk_fma_f32 v[64:65], v[12:13], v[88:89], v[64:65]

; DEV float bflo(unsigned u) { return __uint_as_float(u << 16); }
; DEV float bfhi(unsigned u) { return __uint_as_float(u & 0xffff0000u); }
; DEV void gdn_prep_chunk(const Params& p, int item, unsigned char* lds) {
;     ...
;                 for (int j = 0; j < 4; ++j) {
;                     const uint4 u = raw[r + j];
;                     const unsigned wd = (e < 2 ? u.x : (e < 4 ? u.y : (e < 6 ? u.z : u.w)));
;                     const float xv = (e & 1) ? bfhi(wd) : bflo(wd);
;                     a += w[j][e] * xv;
	v_pk_fma_f32 v[64:65], v[16:17], v[80:81], v[64:65]

; DEV float silu_f(float x) { return x / (1.f + __expf(-x)); }
; DEV void gdn_prep_chunk(const Params& p, int item, unsigned char* lds) {
;     ...
;                 y[e] = silu_f(a); ss += y[e] * y[e];
	v_mul_f32_e32 v74, 0xbfb8aa3b, v64
	v_mul_f32_e32 v75, 0xbfb8aa3b, v65
	v_exp_f32_e32 v74, v74
	v_exp_f32_e32 v75, v75


; DEV float silu_f(float x) { return x / (1.f + __expf(-x)); }
; DEV void gdn_prep_chunk(const Params& p, int item, unsigned char* lds) {
;     ...
;                 y[e] = silu_f(a); ss += y[e] * y[e];
	v_rcp_f32_e32 v68, v90
	s_nop 0
	v_mul_f32_e32 v68, v78, v68
	v_pk_add_f32 v[74:75], v[74:75], 1.0 op_sel_hi:[1,0]
	s_nop 0


; DEV float silu_f(float x) { return x / (1.f + __expf(-x)); }
; DEV void gdn_prep_chunk(const Params& p, int item, unsigned char* lds) {
;     ...
;                 y[e] = silu_f(a); ss += y[e] * y[e];
	s_nop 0


; DEV float silu_f(float x) { return x / (1.f + __expf(-x)); }
; DEV void gdn_prep_chunk(const Params& p, int item, unsigned char* lds) {
;     ...
;                 y[e] = silu_f(a); ss += y[e] * y[e];
	v_rcp_f32_e32 v78, v75
	s_nop 0
	v_mul_f32_e32 v65, v65, v78


; DEV float silu_f(float x) { return x / (1.f + __expf(-x)); }
; DEV void gdn_prep_chunk(const Params& p, int item, unsigned char* lds) {
;     ...
;                 y[e] = silu_f(a); ss += y[e] * y[e];
;             }
;             if (mat < 2) {
;                 ss += __shfl_xor(ss, 1); ss += __shfl_xor(ss, 2); ss += __shfl_xor(ss, 4); ss += __shfl_xor(ss, 8);
	v_rcp_f32_e32 v75, v74
	s_nop 0
	v_mul_f32_e32 v64, v64, v75
	s_and_saveexec_b64 s[36:37], s[6:7]
	s_cbranch_execz .LBB0_490
	v_pk_mul_f32 v[74:75], v[66:67], v[66:67]
	v_pk_mul_f32 v[78:79], v[62:63], v[62:63]
	v_add_f32_e32 v74, v74, v75
	v_add_f32_e32 v74, v74, v78
	v_pk_mul_f32 v[90:91], v[68:69], v[68:69]
	v_add_f32_e32 v74, v79, v74
	v_and_b32_e32 v78, 64, v182
	v_add_f32_e32 v74, v90, v74

; DEV float silu_f(float x) { return x / (1.f + __expf(-x)); }
; DEV void gdn_prep_chunk(const Params& p, int item, unsigned char* lds) {
;     ...
;                 y[e] = silu_f(a); ss += y[e] * y[e];
;             }
;             if (mat < 2) {
;                 ss += __shfl_xor(ss, 1); ss += __shfl_xor(ss, 2); ss += __shfl_xor(ss, 4); ss += __shfl_xor(ss, 8);
	v_add_u32_e32 v78, 64, v78
	v_pk_mul_f32 v[94:95], v[64:65], v[64:65]
	v_add_f32_e32 v74, v91, v74

; DEV float silu_f(float x) { return x / (1.f + __expf(-x)); }
; DEV void gdn_prep_chunk(const Params& p, int item, unsigned char* lds) {
;     ...
;                 y[e] = silu_f(a); ss += y[e] * y[e];
;             }
;             if (mat < 2) {
;                 ss += __shfl_xor(ss, 1); ss += __shfl_xor(ss, 2); ss += __shfl_xor(ss, 4); ss += __shfl_xor(ss, 8);
	v_add_f32_e32 v74, v94, v74
	v_add_f32_e32 v74, v95, v74


; DEV void gdn_prep_chunk(const Params& p, int item, unsigned char* lds) {
;     ...
;                 ss += __shfl_xor(ss, 1); ss += __shfl_xor(ss, 2); ss += __shfl_xor(ss, 4); ss += __shfl_xor(ss, 8);
	s_waitcnt lgkmcnt(0)
	s_nop 1
	v_add_f32_dpp v74, v74, v74 quad_perm:[1,0,3,2] row_mask:0xf bank_mask:0xf


; DEV void gdn_prep_chunk(const Params& p, int item, unsigned char* lds) {
;     ...
;                 ss += __shfl_xor(ss, 1); ss += __shfl_xor(ss, 2); ss += __shfl_xor(ss, 4); ss += __shfl_xor(ss, 8);
	s_nop 1


; DEV void gdn_prep_chunk(const Params& p, int item, unsigned char* lds) {
;     ...
;                 ss += __shfl_xor(ss, 1); ss += __shfl_xor(ss, 2); ss += __shfl_xor(ss, 4); ss += __shfl_xor(ss, 8);
	s_waitcnt lgkmcnt(0)
	s_nop 1
	v_add_f32_dpp v74, v74, v74 quad_perm:[2,3,0,1] row_mask:0xf bank_mask:0xf


; DEV void gdn_prep_chunk(const Params& p, int item, unsigned char* lds) {
;     ...
;                 ss += __shfl_xor(ss, 1); ss += __shfl_xor(ss, 2); ss += __shfl_xor(ss, 4); ss += __shfl_xor(ss, 8);
	s_nop 1


; DEV void gdn_prep_chunk(const Params& p, int item, unsigned char* lds) {
;     ...
;                 ss += __shfl_xor(ss, 1); ss += __shfl_xor(ss, 2); ss += __shfl_xor(ss, 4); ss += __shfl_xor(ss, 8);
	s_waitcnt lgkmcnt(0)
	s_nop 1
	v_add_f32_dpp v74, v74, v74 row_half_mirror row_mask:0xf bank_mask:0xf


; DEV void gdn_prep_chunk(const Params& p, int item, unsigned char* lds) {
;     ...
;                 ss += __shfl_xor(ss, 1); ss += __shfl_xor(ss, 2); ss += __shfl_xor(ss, 4); ss += __shfl_xor(ss, 8);
	s_nop 1


; DEV unsigned cvt_pk_bf16(float lo, float hi) { const f32x2_t v = {lo, hi}; const bf16x2_t b = __builtin_convertvector(v, bf16x2_t); return __builtin_bit_cast(unsigned, b); }
; DEV float bflo(unsigned u) { return __uint_as_float(u << 16); }
; DEV float bfhi(unsigned u) { return __uint_as_float(u & 0xffff0000u); }
; DEV float silu_f(float x) { return x / (1.f + __expf(-x)); }
; DEV void gdn_prep_chunk(const Params& p, int item, unsigned char* lds) {
;     ...
;                 for (int j = 0; j < 4; ++j) {
;                     const uint4 u = raw[r + j];
;                     const unsigned wd = (e < 2 ? u.x : (e < 4 ? u.y : (e < 6 ? u.z : u.w)));
;                     const float xv = (e & 1) ? bfhi(wd) : bflo(wd);
;                     a += w[j][e] * xv;
;                 }
;                 y[e] = silu_f(a); ss += y[e] * y[e];
;     ...
;                 ss += __shfl_xor(ss, 1); ss += __shfl_xor(ss, 2); ss += __shfl_xor(ss, 4); ss += __shfl_xor(ss, 8);
;                 float inv = rsqrtf(ss + EPS); if (mat == 0) inv *= 0.08838834764831845f;
; #pragma unroll
;                 for (int e = 0; e < 8; ++e) y[e] *= inv;
;             }
;             uint4 o; o.x = cvt_pk_bf16(y[0], y[1]); o.y = cvt_pk_bf16(y[2], y[3]); o.z = cvt_pk_bf16(y[4], y[5]); o.w = cvt_pk_bf16(y[6], y[7]);
;             *(uint4*)(dst + (tl0 + r) * QS + cv * 8) = o;
	s_waitcnt lgkmcnt(0)
	s_nop 1
	v_add_f32_dpp v74, v74, v74 row_mirror row_mask:0xf bank_mask:0xf
	v_add_f32_e32 v74, 0x358637bd, v74
	v_mul_f32_e32 v75, 0x4b800000, v74
	v_cmp_gt_f32_e32 vcc, s56, v74
	s_nop 1
	v_cndmask_b32_e32 v74, v74, v75, vcc
	v_rsq_f32_e32 v74, v74
	s_nop 0
	v_mul_f32_e32 v75, 0x45800000, v74
	v_cndmask_b32_e32 v74, v74, v75, vcc
	v_mul_f32_e32 v75, 0x3db504f3, v74
	v_cndmask_b32_e64 v74, v74, v75, s[4:5]
	v_pk_mul_f32 v[66:67], v[66:67], v[74:75] op_sel_hi:[1,0]
	v_pk_mul_f32 v[62:63], v[62:63], v[74:75] op_sel_hi:[1,0]
	v_pk_mul_f32 v[68:69], v[68:69], v[74:75] op_sel_hi:[1,0]
	v_pk_mul_f32 v[64:65], v[64:65], v[74:75] op_sel_hi:[1,0]
.LBB0_490:
	s_or_b64 exec, exec, s[36:37]
	v_pk_fma_f32 v[74:75], v[18:19], v[76:77], 0 op_sel_hi:[1,1,0]
	s_waitcnt vmcnt(6)
	v_lshlrev_b32_e32 v78, 16, v58
	v_pk_fma_f32 v[74:75], v[22:23], v[72:73], v[74:75]
	v_and_b32_e32 v79, 0xffff0000, v58
	v_pk_fma_f32 v[74:75], v[26:27], v[86:87], v[74:75]
	v_cvt_pk_bf16_f32 v66, v66, v67
	v_pk_fma_f32 v[74:75], v[30:31], v[78:79], v[74:75]
	v_cvt_pk_bf16_f32 v67, v62, v63
	v_mul_f32_e32 v58, 0xbfb8aa3b, v74
	v_exp_f32_e32 v76, v58
	v_mul_f32_e32 v58, 0xbfb8aa3b, v75
	v_exp_f32_e32 v77, v58
	v_cvt_pk_bf16_f32 v68, v68, v69
	v_cvt_pk_bf16_f32 v69, v64, v65
	ds_write_b128 v104, v[66:69] offset:544
	v_pk_add_f32 v[62:63], v[76:77], 1.0 op_sel_hi:[1,0]
	v_and_b32_e32 v77, 0xffff0000, v59


; DEV float silu_f(float x) { return x / (1.f + __expf(-x)); }
; DEV void gdn_prep_chunk(const Params& p, int item, unsigned char* lds) {
;     ...
;                 y[e] = silu_f(a); ss += y[e] * y[e];
	s_nop 0


; DEV float silu_f(float x) { return x / (1.f + __expf(-x)); }
; DEV void gdn_prep_chunk(const Params& p, int item, unsigned char* lds) {
;     ...
;                 y[e] = silu_f(a); ss += y[e] * y[e];
	v_rcp_f32_e32 v58, v63
	s_nop 0
	v_mul_f32_e32 v63, v75, v58


; DEV float bflo(unsigned u) { return __uint_as_float(u << 16); }
; DEV float bfhi(unsigned u) { return __uint_as_float(u & 0xffff0000u); }
; DEV void gdn_prep_chunk(const Params& p, int item, unsigned char* lds) {
;     ...
;                     const uint4 u = raw[r + j];
;                     const unsigned wd = (e < 2 ? u.x : (e < 4 ? u.y : (e < 6 ? u.z : u.w)));
;                     const float xv = (e & 1) ? bfhi(wd) : bflo(wd);
;                     a += w[j][e] * xv;
	v_lshlrev_b32_e32 v76, 16, v59
	v_pk_fma_f32 v[58:59], v[20:21], v[98:99], 0 op_sel_hi:[1,1,0]

; DEV float bflo(unsigned u) { return __uint_as_float(u << 16); }
; DEV float bfhi(unsigned u) { return __uint_as_float(u & 0xffff0000u); }
; DEV void gdn_prep_chunk(const Params& p, int item, unsigned char* lds) {
;     ...
;                 for (int j = 0; j < 4; ++j) {
;                     const uint4 u = raw[r + j];
;                     const unsigned wd = (e < 2 ? u.x : (e < 4 ? u.y : (e < 6 ? u.z : u.w)));
;                     const float xv = (e & 1) ? bfhi(wd) : bflo(wd);
;                     a += w[j][e] * xv;
	v_pk_fma_f32 v[58:59], v[24:25], v[100:101], v[58:59]

; DEV float bflo(unsigned u) { return __uint_as_float(u << 16); }
; DEV float bfhi(unsigned u) { return __uint_as_float(u & 0xffff0000u); }
; DEV void gdn_prep_chunk(const Params& p, int item, unsigned char* lds) {
;     ...
;                 for (int j = 0; j < 4; ++j) {
;                     const uint4 u = raw[r + j];
;                     const unsigned wd = (e < 2 ? u.x : (e < 4 ? u.y : (e < 6 ? u.z : u.w)));
;                     const float xv = (e & 1) ? bfhi(wd) : bflo(wd);
;                     a += w[j][e] * xv;
	v_pk_fma_f32 v[58:59], v[28:29], v[84:85], v[58:59]

; DEV float bflo(unsigned u) { return __uint_as_float(u << 16); }
; DEV float bfhi(unsigned u) { return __uint_as_float(u & 0xffff0000u); }
; DEV void gdn_prep_chunk(const Params& p, int item, unsigned char* lds) {
;     ...
;                 for (int j = 0; j < 4; ++j) {
;                     const uint4 u = raw[r + j];
;                     const unsigned wd = (e < 2 ? u.x : (e < 4 ? u.y : (e < 6 ? u.z : u.w)));
;                     const float xv = (e & 1) ? bfhi(wd) : bflo(wd);
;                     a += w[j][e] * xv;
	v_pk_fma_f32 v[58:59], v[32:33], v[76:77], v[58:59]

; DEV float silu_f(float x) { return x / (1.f + __expf(-x)); }
; DEV void gdn_prep_chunk(const Params& p, int item, unsigned char* lds) {
;     ...
;                 y[e] = silu_f(a); ss += y[e] * y[e];
	v_mul_f32_e32 v64, 0xbfb8aa3b, v58
	v_mul_f32_e32 v65, 0xbfb8aa3b, v59
	v_exp_f32_e32 v64, v64
	v_exp_f32_e32 v65, v65


; DEV float silu_f(float x) { return x / (1.f + __expf(-x)); }
; DEV void gdn_prep_chunk(const Params& p, int item, unsigned char* lds) {
;     ...
;                 y[e] = silu_f(a); ss += y[e] * y[e];
	v_rcp_f32_e32 v66, v62
	s_nop 0
	v_mul_f32_e32 v62, v74, v66
	v_pk_add_f32 v[64:65], v[64:65], 1.0 op_sel_hi:[1,0]
	v_lshlrev_b32_e32 v74, 16, v60


; DEV float bflo(unsigned u) { return __uint_as_float(u << 16); }
; DEV float bfhi(unsigned u) { return __uint_as_float(u & 0xffff0000u); }
; DEV float silu_f(float x) { return x / (1.f + __expf(-x)); }
; DEV void gdn_prep_chunk(const Params& p, int item, unsigned char* lds) {
;     ...
;                 for (int j = 0; j < 4; ++j) {
;                     const uint4 u = raw[r + j];
;                     const unsigned wd = (e < 2 ? u.x : (e < 4 ? u.y : (e < 6 ? u.z : u.w)));
;                     const float xv = (e & 1) ? bfhi(wd) : bflo(wd);
;                     a += w[j][e] * xv;
;     ...
;                 y[e] = silu_f(a); ss += y[e] * y[e];
	v_rcp_f32_e32 v66, v65
	s_nop 0
	v_mul_f32_e32 v59, v59, v66
	v_pk_fma_f32 v[66:67], v[2:3], v[96:97], 0 op_sel_hi:[1,1,0]
	v_and_b32_e32 v75, 0xffff0000, v60
	v_pk_fma_f32 v[66:67], v[6:7], v[92:93], v[66:67]

; DEV float bflo(unsigned u) { return __uint_as_float(u << 16); }
; DEV float bfhi(unsigned u) { return __uint_as_float(u & 0xffff0000u); }
; DEV void gdn_prep_chunk(const Params& p, int item, unsigned char* lds) {
;     ...
;                 for (int j = 0; j < 4; ++j) {
;                     const uint4 u = raw[r + j];
;                     const unsigned wd = (e < 2 ? u.x : (e < 4 ? u.y : (e < 6 ? u.z : u.w)));
;                     const float xv = (e & 1) ? bfhi(wd) : bflo(wd);
;                     a += w[j][e] * xv;
	v_pk_fma_f32 v[66:67], v[10:11], v[82:83], v[66:67]

; DEV float bflo(unsigned u) { return __uint_as_float(u << 16); }
; DEV float bfhi(unsigned u) { return __uint_as_float(u & 0xffff0000u); }
; DEV void gdn_prep_chunk(const Params& p, int item, unsigned char* lds) {
;     ...
;                 for (int j = 0; j < 4; ++j) {
;                     const uint4 u = raw[r + j];
;                     const unsigned wd = (e < 2 ? u.x : (e < 4 ? u.y : (e < 6 ? u.z : u.w)));
;                     const float xv = (e & 1) ? bfhi(wd) : bflo(wd);
;                     a += w[j][e] * xv;
	v_pk_fma_f32 v[66:67], v[14:15], v[74:75], v[66:67]

; DEV float silu_f(float x) { return x / (1.f + __expf(-x)); }
; DEV void gdn_prep_chunk(const Params& p, int item, unsigned char* lds) {
;     ...
;                 y[e] = silu_f(a); ss += y[e] * y[e];
	v_mul_f32_e32 v60, 0xbfb8aa3b, v66
	v_exp_f32_e32 v68, v60
	v_mul_f32_e32 v60, 0xbfb8aa3b, v67
	v_exp_f32_e32 v69, v60


; DEV float silu_f(float x) { return x / (1.f + __expf(-x)); }
; DEV void gdn_prep_chunk(const Params& p, int item, unsigned char* lds) {
;     ...
;                 y[e] = silu_f(a); ss += y[e] * y[e];
	s_nop 0
	v_pk_add_f32 v[90:91], v[68:69], 1.0 op_sel_hi:[1,0]


; DEV float silu_f(float x) { return x / (1.f + __expf(-x)); }
; DEV void gdn_prep_chunk(const Params& p, int item, unsigned char* lds) {
;     ...
;                 y[e] = silu_f(a); ss += y[e] * y[e];
	v_rcp_f32_e32 v60, v64
	s_nop 0
	v_mul_f32_e32 v58, v58, v60


; DEV float silu_f(float x) { return x / (1.f + __expf(-x)); }
; DEV void gdn_prep_chunk(const Params& p, int item, unsigned char* lds) {
;     ...
;                 y[e] = silu_f(a); ss += y[e] * y[e];
	v_rcp_f32_e32 v60, v91
	s_nop 0
	v_mul_f32_e32 v65, v67, v60


; DEV float bflo(unsigned u) { return __uint_as_float(u << 16); }
; DEV float bfhi(unsigned u) { return __uint_as_float(u & 0xffff0000u); }
; DEV void gdn_prep_chunk(const Params& p, int item, unsigned char* lds) {
;     ...
;                     const uint4 u = raw[r + j];
;                     const unsigned wd = (e < 2 ? u.x : (e < 4 ? u.y : (e < 6 ? u.z : u.w)));
;                     const float xv = (e & 1) ? bfhi(wd) : bflo(wd);
;                     a += w[j][e] * xv;
	v_lshlrev_b32_e32 v68, 16, v61
	v_and_b32_e32 v69, 0xffff0000, v61
	v_pk_fma_f32 v[60:61], v[4:5], v[70:71], 0 op_sel_hi:[1,1,0]

; DEV float bflo(unsigned u) { return __uint_as_float(u << 16); }
; DEV float bfhi(unsigned u) { return __uint_as_float(u & 0xffff0000u); }
; DEV void gdn_prep_chunk(const Params& p, int item, unsigned char* lds) {
;     ...
;                 for (int j = 0; j < 4; ++j) {
;                     const uint4 u = raw[r + j];
;                     const unsigned wd = (e < 2 ? u.x : (e < 4 ? u.y : (e < 6 ? u.z : u.w)));
;                     const float xv = (e & 1) ? bfhi(wd) : bflo(wd);
;                     a += w[j][e] * xv;
	v_pk_fma_f32 v[60:61], v[8:9], v[88:89], v[60:61]

; DEV float bflo(unsigned u) { return __uint_as_float(u << 16); }
; DEV float bfhi(unsigned u) { return __uint_as_float(u & 0xffff0000u); }
; DEV void gdn_prep_chunk(const Params& p, int item, unsigned char* lds) {
;     ...
;                 for (int j = 0; j < 4; ++j) {
;                     const uint4 u = raw[r + j];
;                     const unsigned wd = (e < 2 ? u.x : (e < 4 ? u.y : (e < 6 ? u.z : u.w)));
;                     const float xv = (e & 1) ? bfhi(wd) : bflo(wd);
;                     a += w[j][e] * xv;
	v_pk_fma_f32 v[60:61], v[12:13], v[80:81], v[60:61]

; DEV float bflo(unsigned u) { return __uint_as_float(u << 16); }
; DEV float bfhi(unsigned u) { return __uint_as_float(u & 0xffff0000u); }
; DEV void gdn_prep_chunk(const Params& p, int item, unsigned char* lds) {
;     ...
;                 for (int j = 0; j < 4; ++j) {
;                     const uint4 u = raw[r + j];
;                     const unsigned wd = (e < 2 ? u.x : (e < 4 ? u.y : (e < 6 ? u.z : u.w)));
;                     const float xv = (e & 1) ? bfhi(wd) : bflo(wd);
;                     a += w[j][e] * xv;
	v_pk_fma_f32 v[60:61], v[16:17], v[68:69], v[60:61]

; DEV float silu_f(float x) { return x / (1.f + __expf(-x)); }
; DEV void gdn_prep_chunk(const Params& p, int item, unsigned char* lds) {
;     ...
;                 y[e] = silu_f(a); ss += y[e] * y[e];
	v_mul_f32_e32 v70, 0xbfb8aa3b, v60
	v_mul_f32_e32 v71, 0xbfb8aa3b, v61
	v_exp_f32_e32 v70, v70
	v_exp_f32_e32 v71, v71


; DEV float silu_f(float x) { return x / (1.f + __expf(-x)); }
; DEV void gdn_prep_chunk(const Params& p, int item, unsigned char* lds) {
;     ...
;                 y[e] = silu_f(a); ss += y[e] * y[e];
	v_rcp_f32_e32 v64, v90
	s_nop 0
	v_mul_f32_e32 v64, v66, v64
	v_pk_add_f32 v[70:71], v[70:71], 1.0 op_sel_hi:[1,0]
	s_nop 0


; DEV float silu_f(float x) { return x / (1.f + __expf(-x)); }
; DEV void gdn_prep_chunk(const Params& p, int item, unsigned char* lds) {
;     ...
;                 y[e] = silu_f(a); ss += y[e] * y[e];
	s_nop 0


; DEV float silu_f(float x) { return x / (1.f + __expf(-x)); }
; DEV void gdn_prep_chunk(const Params& p, int item, unsigned char* lds) {
;     ...
;                 y[e] = silu_f(a); ss += y[e] * y[e];
	v_rcp_f32_e32 v66, v71
	s_nop 0
	v_mul_f32_e32 v61, v61, v66


; DEV float silu_f(float x) { return x / (1.f + __expf(-x)); }
; DEV void gdn_prep_chunk(const Params& p, int item, unsigned char* lds) {
;     ...
;                 y[e] = silu_f(a); ss += y[e] * y[e];
;             }
;             if (mat < 2) {
;                 ss += __shfl_xor(ss, 1); ss += __shfl_xor(ss, 2); ss += __shfl_xor(ss, 4); ss += __shfl_xor(ss, 8);
	v_rcp_f32_e32 v66, v70
	s_nop 0
	v_mul_f32_e32 v60, v60, v66
	s_and_saveexec_b64 s[36:37], s[6:7]
	s_cbranch_execz .LBB0_492
	v_pk_mul_f32 v[66:67], v[62:63], v[62:63]
	v_pk_mul_f32 v[70:71], v[58:59], v[58:59]
	v_add_f32_e32 v66, v66, v67
	v_add_f32_e32 v66, v66, v70
	v_pk_mul_f32 v[90:91], v[64:65], v[64:65]
	v_add_f32_e32 v66, v71, v66
	v_and_b32_e32 v70, 64, v182
	v_add_f32_e32 v66, v90, v66

; DEV float silu_f(float x) { return x / (1.f + __expf(-x)); }
; DEV void gdn_prep_chunk(const Params& p, int item, unsigned char* lds) {
;     ...
;                 y[e] = silu_f(a); ss += y[e] * y[e];
;             }
;             if (mat < 2) {
;                 ss += __shfl_xor(ss, 1); ss += __shfl_xor(ss, 2); ss += __shfl_xor(ss, 4); ss += __shfl_xor(ss, 8);
	v_add_u32_e32 v70, 64, v70
	v_pk_mul_f32 v[94:95], v[60:61], v[60:61]
	v_add_f32_e32 v66, v91, v66

; DEV float silu_f(float x) { return x / (1.f + __expf(-x)); }
; DEV void gdn_prep_chunk(const Params& p, int item, unsigned char* lds) {
;     ...
;                 y[e] = silu_f(a); ss += y[e] * y[e];
;             }
;             if (mat < 2) {
;                 ss += __shfl_xor(ss, 1); ss += __shfl_xor(ss, 2); ss += __shfl_xor(ss, 4); ss += __shfl_xor(ss, 8);
	v_add_f32_e32 v66, v94, v66
	v_add_f32_e32 v66, v95, v66


; DEV void gdn_prep_chunk(const Params& p, int item, unsigned char* lds) {
;     ...
;                 ss += __shfl_xor(ss, 1); ss += __shfl_xor(ss, 2); ss += __shfl_xor(ss, 4); ss += __shfl_xor(ss, 8);
	s_waitcnt lgkmcnt(0)
	s_nop 1
	v_add_f32_dpp v66, v66, v66 quad_perm:[1,0,3,2] row_mask:0xf bank_mask:0xf


; DEV void gdn_prep_chunk(const Params& p, int item, unsigned char* lds) {
;     ...
;                 ss += __shfl_xor(ss, 1); ss += __shfl_xor(ss, 2); ss += __shfl_xor(ss, 4); ss += __shfl_xor(ss, 8);
	s_nop 1


; DEV void gdn_prep_chunk(const Params& p, int item, unsigned char* lds) {
;     ...
;                 ss += __shfl_xor(ss, 1); ss += __shfl_xor(ss, 2); ss += __shfl_xor(ss, 4); ss += __shfl_xor(ss, 8);
	s_waitcnt lgkmcnt(0)
	s_nop 1
	v_add_f32_dpp v66, v66, v66 quad_perm:[2,3,0,1] row_mask:0xf bank_mask:0xf


; DEV void gdn_prep_chunk(const Params& p, int item, unsigned char* lds) {
;     ...
;                 ss += __shfl_xor(ss, 1); ss += __shfl_xor(ss, 2); ss += __shfl_xor(ss, 4); ss += __shfl_xor(ss, 8);
	s_nop 1


; DEV void gdn_prep_chunk(const Params& p, int item, unsigned char* lds) {
;     ...
;                 ss += __shfl_xor(ss, 1); ss += __shfl_xor(ss, 2); ss += __shfl_xor(ss, 4); ss += __shfl_xor(ss, 8);
	s_waitcnt lgkmcnt(0)
	s_nop 1
	v_add_f32_dpp v66, v66, v66 row_half_mirror row_mask:0xf bank_mask:0xf


; DEV void gdn_prep_chunk(const Params& p, int item, unsigned char* lds) {
;     ...
;                 ss += __shfl_xor(ss, 1); ss += __shfl_xor(ss, 2); ss += __shfl_xor(ss, 4); ss += __shfl_xor(ss, 8);
	s_nop 1


; DEV unsigned cvt_pk_bf16(float lo, float hi) { const f32x2_t v = {lo, hi}; const bf16x2_t b = __builtin_convertvector(v, bf16x2_t); return __builtin_bit_cast(unsigned, b); }
; DEV float bflo(unsigned u) { return __uint_as_float(u << 16); }
; DEV float bfhi(unsigned u) { return __uint_as_float(u & 0xffff0000u); }
; DEV float silu_f(float x) { return x / (1.f + __expf(-x)); }
; DEV void gdn_prep_chunk(const Params& p, int item, unsigned char* lds) {
;     ...
;                 for (int j = 0; j < 4; ++j) {
;                     const uint4 u = raw[r + j];
;                     const unsigned wd = (e < 2 ? u.x : (e < 4 ? u.y : (e < 6 ? u.z : u.w)));
;                     const float xv = (e & 1) ? bfhi(wd) : bflo(wd);
;                     a += w[j][e] * xv;
;                 }
;                 y[e] = silu_f(a); ss += y[e] * y[e];
;     ...
;                 ss += __shfl_xor(ss, 1); ss += __shfl_xor(ss, 2); ss += __shfl_xor(ss, 4); ss += __shfl_xor(ss, 8);
;                 float inv = rsqrtf(ss + EPS); if (mat == 0) inv *= 0.08838834764831845f;
; #pragma unroll
;                 for (int e = 0; e < 8; ++e) y[e] *= inv;
;             }
;             uint4 o; o.x = cvt_pk_bf16(y[0], y[1]); o.y = cvt_pk_bf16(y[2], y[3]); o.z = cvt_pk_bf16(y[4], y[5]); o.w = cvt_pk_bf16(y[6], y[7]);
;             *(uint4*)(dst + (tl0 + r) * QS + cv * 8) = o;
	s_waitcnt lgkmcnt(0)
	s_nop 1
	v_add_f32_dpp v66, v66, v66 row_mirror row_mask:0xf bank_mask:0xf
	v_add_f32_e32 v66, 0x358637bd, v66
	v_mul_f32_e32 v67, 0x4b800000, v66
	v_cmp_gt_f32_e32 vcc, s56, v66
	s_nop 1
	v_cndmask_b32_e32 v66, v66, v67, vcc
	v_rsq_f32_e32 v66, v66
	s_nop 0
	v_mul_f32_e32 v67, 0x45800000, v66
	v_cndmask_b32_e32 v66, v66, v67, vcc
	v_mul_f32_e32 v67, 0x3db504f3, v66
	v_cndmask_b32_e64 v66, v66, v67, s[4:5]
	v_pk_mul_f32 v[62:63], v[62:63], v[66:67] op_sel_hi:[1,0]
	v_pk_mul_f32 v[58:59], v[58:59], v[66:67] op_sel_hi:[1,0]
	v_pk_mul_f32 v[64:65], v[64:65], v[66:67] op_sel_hi:[1,0]
	v_pk_mul_f32 v[60:61], v[60:61], v[66:67] op_sel_hi:[1,0]
.LBB0_492:
	s_or_b64 exec, exec, s[36:37]
	v_pk_fma_f32 v[70:71], v[18:19], v[72:73], 0 op_sel_hi:[1,1,0]
	s_waitcnt vmcnt(5)
	v_lshlrev_b32_e32 v66, 16, v54
	v_pk_fma_f32 v[70:71], v[22:23], v[86:87], v[70:71]
	v_and_b32_e32 v67, 0xffff0000, v54
	v_pk_fma_f32 v[70:71], v[26:27], v[78:79], v[70:71]
	v_cvt_pk_bf16_f32 v62, v62, v63
	v_pk_fma_f32 v[70:71], v[30:31], v[66:67], v[70:71]
	v_cvt_pk_bf16_f32 v63, v58, v59
	v_mul_f32_e32 v54, 0xbfb8aa3b, v70
	v_exp_f32_e32 v72, v54
	v_mul_f32_e32 v54, 0xbfb8aa3b, v71
	v_exp_f32_e32 v73, v54
	v_cvt_pk_bf16_f32 v64, v64, v65
	v_cvt_pk_bf16_f32 v65, v60, v61
	ds_write_b128 v104, v[62:65] offset:816
	v_pk_add_f32 v[58:59], v[72:73], 1.0 op_sel_hi:[1,0]
	v_lshlrev_b32_e32 v64, 16, v55


; DEV float bflo(unsigned u) { return __uint_as_float(u << 16); }
; DEV float bfhi(unsigned u) { return __uint_as_float(u & 0xffff0000u); }
; DEV void gdn_prep_chunk(const Params& p, int item, unsigned char* lds) {
;     ...
;                     const uint4 u = raw[r + j];
;                     const unsigned wd = (e < 2 ? u.x : (e < 4 ? u.y : (e < 6 ? u.z : u.w)));
;                     const float xv = (e & 1) ? bfhi(wd) : bflo(wd);
	v_and_b32_e32 v65, 0xffff0000, v55


; DEV float silu_f(float x) { return x / (1.f + __expf(-x)); }
; DEV void gdn_prep_chunk(const Params& p, int item, unsigned char* lds) {
;     ...
;                 y[e] = silu_f(a); ss += y[e] * y[e];
	v_rcp_f32_e32 v54, v59
	s_nop 0
	v_mul_f32_e32 v71, v71, v54


; DEV float bflo(unsigned u) { return __uint_as_float(u << 16); }
; DEV float bfhi(unsigned u) { return __uint_as_float(u & 0xffff0000u); }
; DEV void gdn_prep_chunk(const Params& p, int item, unsigned char* lds) {
;     ...
;                 for (int j = 0; j < 4; ++j) {
;                     const uint4 u = raw[r + j];
;                     const unsigned wd = (e < 2 ? u.x : (e < 4 ? u.y : (e < 6 ? u.z : u.w)));
;                     const float xv = (e & 1) ? bfhi(wd) : bflo(wd);
;                     a += w[j][e] * xv;
	v_pk_fma_f32 v[54:55], v[20:21], v[100:101], 0 op_sel_hi:[1,1,0]

; DEV float bflo(unsigned u) { return __uint_as_float(u << 16); }
; DEV float bfhi(unsigned u) { return __uint_as_float(u & 0xffff0000u); }
; DEV void gdn_prep_chunk(const Params& p, int item, unsigned char* lds) {
;     ...
;             for (int e = 0; e < 8; ++e) {
;                 float a = 0.f;
; #pragma unroll
;                 for (int j = 0; j < 4; ++j) {
;                     const uint4 u = raw[r + j];
;                     const unsigned wd = (e < 2 ? u.x : (e < 4 ? u.y : (e < 6 ? u.z : u.w)));
;                     const float xv = (e & 1) ? bfhi(wd) : bflo(wd);
;                     a += w[j][e] * xv;
;                 }
	v_pk_fma_f32 v[54:55], v[24:25], v[84:85], v[54:55]

; DEV float bflo(unsigned u) { return __uint_as_float(u << 16); }
; DEV float bfhi(unsigned u) { return __uint_as_float(u & 0xffff0000u); }
; DEV void gdn_prep_chunk(const Params& p, int item, unsigned char* lds) {
;     ...
;             for (int e = 0; e < 8; ++e) {
;                 float a = 0.f;
; #pragma unroll
;                 for (int j = 0; j < 4; ++j) {
;                     const uint4 u = raw[r + j];
;                     const unsigned wd = (e < 2 ? u.x : (e < 4 ? u.y : (e < 6 ? u.z : u.w)));
;                     const float xv = (e & 1) ? bfhi(wd) : bflo(wd);
;                     a += w[j][e] * xv;
;                 }
	v_pk_fma_f32 v[54:55], v[28:29], v[76:77], v[54:55]

; DEV float bflo(unsigned u) { return __uint_as_float(u << 16); }
; DEV float bfhi(unsigned u) { return __uint_as_float(u & 0xffff0000u); }
; DEV void gdn_prep_chunk(const Params& p, int item, unsigned char* lds) {
;     ...
;             for (int e = 0; e < 8; ++e) {
;                 float a = 0.f;
; #pragma unroll
;                 for (int j = 0; j < 4; ++j) {
;                     const uint4 u = raw[r + j];
;                     const unsigned wd = (e < 2 ? u.x : (e < 4 ? u.y : (e < 6 ? u.z : u.w)));
;                     const float xv = (e & 1) ? bfhi(wd) : bflo(wd);
;                     a += w[j][e] * xv;
;                 }
	v_pk_fma_f32 v[54:55], v[32:33], v[64:65], v[54:55]

; DEV float silu_f(float x) { return x / (1.f + __expf(-x)); }
; DEV void gdn_prep_chunk(const Params& p, int item, unsigned char* lds) {
;     ...
;                 y[e] = silu_f(a); ss += y[e] * y[e];
	v_mul_f32_e32 v60, 0xbfb8aa3b, v54
	v_mul_f32_e32 v61, 0xbfb8aa3b, v55
	v_exp_f32_e32 v60, v60
	v_exp_f32_e32 v61, v61


; DEV float silu_f(float x) { return x / (1.f + __expf(-x)); }
; DEV void gdn_prep_chunk(const Params& p, int item, unsigned char* lds) {
;     ...
;                 y[e] = silu_f(a); ss += y[e] * y[e];
	v_rcp_f32_e32 v59, v58
	s_nop 0
	v_mul_f32_e32 v70, v70, v59
	v_pk_add_f32 v[60:61], v[60:61], 1.0 op_sel_hi:[1,0]
	s_nop 0


; DEV float silu_f(float x) { return x / (1.f + __expf(-x)); }
; DEV void gdn_prep_chunk(const Params& p, int item, unsigned char* lds) {
;     ...
;                 y[e] = silu_f(a); ss += y[e] * y[e];
	v_rcp_f32_e32 v58, v61
	s_nop 0
	v_mul_f32_e32 v55, v55, v58


; DEV float bflo(unsigned u) { return __uint_as_float(u << 16); }
; DEV float bfhi(unsigned u) { return __uint_as_float(u & 0xffff0000u); }
; DEV void gdn_prep_chunk(const Params& p, int item, unsigned char* lds) {
;     ...
;             for (int e = 0; e < 8; ++e) {
;                 float a = 0.f;
; #pragma unroll
;                 for (int j = 0; j < 4; ++j) {
;                     const uint4 u = raw[r + j];
;                     const unsigned wd = (e < 2 ? u.x : (e < 4 ? u.y : (e < 6 ? u.z : u.w)));
;                     const float xv = (e & 1) ? bfhi(wd) : bflo(wd);
;                     a += w[j][e] * xv;
;                 }
	v_pk_fma_f32 v[58:59], v[2:3], v[92:93], 0 op_sel_hi:[1,1,0]
	v_lshlrev_b32_e32 v62, 16, v56
	v_pk_fma_f32 v[58:59], v[6:7], v[82:83], v[58:59]
	v_and_b32_e32 v63, 0xffff0000, v56
	v_pk_fma_f32 v[58:59], v[10:11], v[74:75], v[58:59]

; DEV float bflo(unsigned u) { return __uint_as_float(u << 16); }
; DEV float bfhi(unsigned u) { return __uint_as_float(u & 0xffff0000u); }
; DEV void gdn_prep_chunk(const Params& p, int item, unsigned char* lds) {
;     ...
;             for (int e = 0; e < 8; ++e) {
;                 float a = 0.f;
; #pragma unroll
;                 for (int j = 0; j < 4; ++j) {
;                     const uint4 u = raw[r + j];
;                     const unsigned wd = (e < 2 ? u.x : (e < 4 ? u.y : (e < 6 ? u.z : u.w)));
;                     const float xv = (e & 1) ? bfhi(wd) : bflo(wd);
;                     a += w[j][e] * xv;
;                 }
	v_pk_fma_f32 v[58:59], v[14:15], v[62:63], v[58:59]

; DEV float silu_f(float x) { return x / (1.f + __expf(-x)); }
; DEV void gdn_prep_chunk(const Params& p, int item, unsigned char* lds) {
;     ...
;                 y[e] = silu_f(a); ss += y[e] * y[e];
	v_mul_f32_e32 v56, 0xbfb8aa3b, v58
	v_exp_f32_e32 v72, v56
	v_mul_f32_e32 v56, 0xbfb8aa3b, v59
	v_exp_f32_e32 v73, v56


; DEV float silu_f(float x) { return x / (1.f + __expf(-x)); }
; DEV void gdn_prep_chunk(const Params& p, int item, unsigned char* lds) {
;     ...
;                 y[e] = silu_f(a); ss += y[e] * y[e];
	s_nop 0
	v_pk_add_f32 v[72:73], v[72:73], 1.0 op_sel_hi:[1,0]


; DEV float silu_f(float x) { return x / (1.f + __expf(-x)); }
; DEV void gdn_prep_chunk(const Params& p, int item, unsigned char* lds) {
;     ...
;                 y[e] = silu_f(a); ss += y[e] * y[e];
	v_rcp_f32_e32 v56, v60
	s_nop 0
	v_mul_f32_e32 v54, v54, v56


; DEV float silu_f(float x) { return x / (1.f + __expf(-x)); }
; DEV void gdn_prep_chunk(const Params& p, int item, unsigned char* lds) {
;     ...
;                 y[e] = silu_f(a); ss += y[e] * y[e];
	v_rcp_f32_e32 v56, v73
	s_nop 0
	v_mul_f32_e32 v73, v59, v56


; DEV float bflo(unsigned u) { return __uint_as_float(u << 16); }
; DEV float bfhi(unsigned u) { return __uint_as_float(u & 0xffff0000u); }
; DEV void gdn_prep_chunk(const Params& p, int item, unsigned char* lds) {
;     ...
;             for (int e = 0; e < 8; ++e) {
;                 float a = 0.f;
; #pragma unroll
;                 for (int j = 0; j < 4; ++j) {
;                     const uint4 u = raw[r + j];
;                     const unsigned wd = (e < 2 ? u.x : (e < 4 ? u.y : (e < 6 ? u.z : u.w)));
;                     const float xv = (e & 1) ? bfhi(wd) : bflo(wd);
;                     a += w[j][e] * xv;
;                 }
	v_lshlrev_b32_e32 v60, 16, v57
	v_and_b32_e32 v61, 0xffff0000, v57
	v_pk_fma_f32 v[56:57], v[4:5], v[88:89], 0 op_sel_hi:[1,1,0]

; DEV float bflo(unsigned u) { return __uint_as_float(u << 16); }
; DEV float bfhi(unsigned u) { return __uint_as_float(u & 0xffff0000u); }
; DEV void gdn_prep_chunk(const Params& p, int item, unsigned char* lds) {
;     ...
;             for (int e = 0; e < 8; ++e) {
;                 float a = 0.f;
; #pragma unroll
;                 for (int j = 0; j < 4; ++j) {
;                     const uint4 u = raw[r + j];
;                     const unsigned wd = (e < 2 ? u.x : (e < 4 ? u.y : (e < 6 ? u.z : u.w)));
;                     const float xv = (e & 1) ? bfhi(wd) : bflo(wd);
;                     a += w[j][e] * xv;
;                 }
	v_pk_fma_f32 v[56:57], v[8:9], v[80:81], v[56:57]

; DEV float bflo(unsigned u) { return __uint_as_float(u << 16); }
; DEV float bfhi(unsigned u) { return __uint_as_float(u & 0xffff0000u); }
; DEV void gdn_prep_chunk(const Params& p, int item, unsigned char* lds) {
;     ...
;             for (int e = 0; e < 8; ++e) {
;                 float a = 0.f;
; #pragma unroll
;                 for (int j = 0; j < 4; ++j) {
;                     const uint4 u = raw[r + j];
;                     const unsigned wd = (e < 2 ? u.x : (e < 4 ? u.y : (e < 6 ? u.z : u.w)));
;                     const float xv = (e & 1) ? bfhi(wd) : bflo(wd);
;                     a += w[j][e] * xv;
;                 }
	v_pk_fma_f32 v[56:57], v[12:13], v[68:69], v[56:57]

; DEV float bflo(unsigned u) { return __uint_as_float(u << 16); }
; DEV float bfhi(unsigned u) { return __uint_as_float(u & 0xffff0000u); }
; DEV void gdn_prep_chunk(const Params& p, int item, unsigned char* lds) {
;     ...
;             for (int e = 0; e < 8; ++e) {
;                 float a = 0.f;
; #pragma unroll
;                 for (int j = 0; j < 4; ++j) {
;                     const uint4 u = raw[r + j];
;                     const unsigned wd = (e < 2 ? u.x : (e < 4 ? u.y : (e < 6 ? u.z : u.w)));
;                     const float xv = (e & 1) ? bfhi(wd) : bflo(wd);
;                     a += w[j][e] * xv;
;                 }
	v_pk_fma_f32 v[56:57], v[16:17], v[60:61], v[56:57]

; DEV float silu_f(float x) { return x / (1.f + __expf(-x)); }
; DEV void gdn_prep_chunk(const Params& p, int item, unsigned char* lds) {
;     ...
;                 y[e] = silu_f(a); ss += y[e] * y[e];
	v_mul_f32_e32 v88, 0xbfb8aa3b, v56
	v_mul_f32_e32 v89, 0xbfb8aa3b, v57
	v_exp_f32_e32 v88, v88
	v_exp_f32_e32 v89, v89


; DEV float silu_f(float x) { return x / (1.f + __expf(-x)); }
; DEV void gdn_prep_chunk(const Params& p, int item, unsigned char* lds) {
;     ...
;                 y[e] = silu_f(a); ss += y[e] * y[e];
	v_rcp_f32_e32 v59, v72
	s_nop 0
	v_mul_f32_e32 v72, v58, v59
	v_pk_add_f32 v[88:89], v[88:89], 1.0 op_sel_hi:[1,0]
	s_nop 0


; DEV float silu_f(float x) { return x / (1.f + __expf(-x)); }
; DEV void gdn_prep_chunk(const Params& p, int item, unsigned char* lds) {
;     ...
;                 y[e] = silu_f(a); ss += y[e] * y[e];
	s_nop 0


; DEV float silu_f(float x) { return x / (1.f + __expf(-x)); }
; DEV void gdn_prep_chunk(const Params& p, int item, unsigned char* lds) {
;     ...
;                 y[e] = silu_f(a); ss += y[e] * y[e];
	v_rcp_f32_e32 v58, v89
	s_nop 0
	v_mul_f32_e32 v57, v57, v58


; DEV float silu_f(float x) { return x / (1.f + __expf(-x)); }
; DEV void gdn_prep_chunk(const Params& p, int item, unsigned char* lds) {
;     ...
;                 y[e] = silu_f(a); ss += y[e] * y[e];
;             }
;             if (mat < 2) {
;                 ss += __shfl_xor(ss, 1); ss += __shfl_xor(ss, 2); ss += __shfl_xor(ss, 4); ss += __shfl_xor(ss, 8);
	v_rcp_f32_e32 v58, v88
	s_nop 0
	v_mul_f32_e32 v56, v56, v58
	s_and_saveexec_b64 s[36:37], s[6:7]
	s_cbranch_execz .LBB0_494
	v_pk_mul_f32 v[58:59], v[70:71], v[70:71]
	v_pk_mul_f32 v[88:89], v[54:55], v[54:55]
	v_add_f32_e32 v58, v58, v59
	v_add_f32_e32 v58, v58, v88
	v_pk_mul_f32 v[90:91], v[72:73], v[72:73]
	v_add_f32_e32 v58, v89, v58
	v_and_b32_e32 v88, 64, v182
	v_add_f32_e32 v58, v90, v58

; DEV float silu_f(float x) { return x / (1.f + __expf(-x)); }
; DEV void gdn_prep_chunk(const Params& p, int item, unsigned char* lds) {
;     ...
;                 y[e] = silu_f(a); ss += y[e] * y[e];
;             }
;             if (mat < 2) {
;                 ss += __shfl_xor(ss, 1); ss += __shfl_xor(ss, 2); ss += __shfl_xor(ss, 4); ss += __shfl_xor(ss, 8);
	v_add_u32_e32 v88, 64, v88
	v_pk_mul_f32 v[92:93], v[56:57], v[56:57]
	v_add_f32_e32 v58, v91, v58

; DEV float silu_f(float x) { return x / (1.f + __expf(-x)); }
; DEV void gdn_prep_chunk(const Params& p, int item, unsigned char* lds) {
;     ...
;                 y[e] = silu_f(a); ss += y[e] * y[e];
;             }
;             if (mat < 2) {
;                 ss += __shfl_xor(ss, 1); ss += __shfl_xor(ss, 2); ss += __shfl_xor(ss, 4); ss += __shfl_xor(ss, 8);
	v_add_f32_e32 v58, v92, v58
	v_add_f32_e32 v58, v93, v58


; DEV void gdn_prep_chunk(const Params& p, int item, unsigned char* lds) {
;     ...
;                 ss += __shfl_xor(ss, 1); ss += __shfl_xor(ss, 2); ss += __shfl_xor(ss, 4); ss += __shfl_xor(ss, 8);
	s_waitcnt lgkmcnt(0)
	s_nop 1
	v_add_f32_dpp v58, v58, v58 quad_perm:[1,0,3,2] row_mask:0xf bank_mask:0xf


; DEV void gdn_prep_chunk(const Params& p, int item, unsigned char* lds) {
;     ...
;                 ss += __shfl_xor(ss, 1); ss += __shfl_xor(ss, 2); ss += __shfl_xor(ss, 4); ss += __shfl_xor(ss, 8);
	s_nop 1


; DEV void gdn_prep_chunk(const Params& p, int item, unsigned char* lds) {
;     ...
;                 ss += __shfl_xor(ss, 1); ss += __shfl_xor(ss, 2); ss += __shfl_xor(ss, 4); ss += __shfl_xor(ss, 8);
	s_waitcnt lgkmcnt(0)
	s_nop 1
	v_add_f32_dpp v58, v58, v58 quad_perm:[2,3,0,1] row_mask:0xf bank_mask:0xf


; DEV void gdn_prep_chunk(const Params& p, int item, unsigned char* lds) {
;     ...
;                 ss += __shfl_xor(ss, 1); ss += __shfl_xor(ss, 2); ss += __shfl_xor(ss, 4); ss += __shfl_xor(ss, 8);
	s_nop 1


; DEV void gdn_prep_chunk(const Params& p, int item, unsigned char* lds) {
;     ...
;                 ss += __shfl_xor(ss, 1); ss += __shfl_xor(ss, 2); ss += __shfl_xor(ss, 4); ss += __shfl_xor(ss, 8);
	s_waitcnt lgkmcnt(0)
	s_nop 1
	v_add_f32_dpp v58, v58, v58 row_half_mirror row_mask:0xf bank_mask:0xf


; DEV void gdn_prep_chunk(const Params& p, int item, unsigned char* lds) {
;     ...
;                 ss += __shfl_xor(ss, 1); ss += __shfl_xor(ss, 2); ss += __shfl_xor(ss, 4); ss += __shfl_xor(ss, 8);
	s_nop 1


; DEV unsigned cvt_pk_bf16(float lo, float hi) { const f32x2_t v = {lo, hi}; const bf16x2_t b = __builtin_convertvector(v, bf16x2_t); return __builtin_bit_cast(unsigned, b); }
; DEV void gdn_prep_chunk(const Params& p, int item, unsigned char* lds) {
;     ...
;                 ss += __shfl_xor(ss, 1); ss += __shfl_xor(ss, 2); ss += __shfl_xor(ss, 4); ss += __shfl_xor(ss, 8);
;                 float inv = rsqrtf(ss + EPS); if (mat == 0) inv *= 0.08838834764831845f;
; #pragma unroll
;                 for (int e = 0; e < 8; ++e) y[e] *= inv;
;             }
;             uint4 o; o.x = cvt_pk_bf16(y[0], y[1]); o.y = cvt_pk_bf16(y[2], y[3]); o.z = cvt_pk_bf16(y[4], y[5]); o.w = cvt_pk_bf16(y[6], y[7]);
;             *(uint4*)(dst + (tl0 + r) * QS + cv * 8) = o;
	s_waitcnt lgkmcnt(0)
	s_nop 1
	v_add_f32_dpp v58, v58, v58 row_mirror row_mask:0xf bank_mask:0xf
	v_add_f32_e32 v58, 0x358637bd, v58
	v_mul_f32_e32 v59, 0x4b800000, v58
	v_cmp_gt_f32_e32 vcc, s56, v58
	s_nop 1
	v_cndmask_b32_e32 v58, v58, v59, vcc
	v_rsq_f32_e32 v58, v58
	s_nop 0
	v_mul_f32_e32 v59, 0x45800000, v58
	v_cndmask_b32_e32 v58, v58, v59, vcc
	v_mul_f32_e32 v59, 0x3db504f3, v58
	v_cndmask_b32_e64 v58, v58, v59, s[4:5]
	v_pk_mul_f32 v[70:71], v[70:71], v[58:59] op_sel_hi:[1,0]
	v_pk_mul_f32 v[54:55], v[54:55], v[58:59] op_sel_hi:[1,0]
	v_pk_mul_f32 v[72:73], v[72:73], v[58:59] op_sel_hi:[1,0]
	v_pk_mul_f32 v[56:57], v[56:57], v[58:59] op_sel_hi:[1,0]
.LBB0_494:
	s_or_b64 exec, exec, s[36:37]
	v_pk_fma_f32 v[86:87], v[18:19], v[86:87], 0 op_sel_hi:[1,1,0]
	s_waitcnt vmcnt(4)
	v_lshlrev_b32_e32 v58, 16, v50
	v_pk_fma_f32 v[86:87], v[22:23], v[78:79], v[86:87]
	v_and_b32_e32 v59, 0xffff0000, v50
	v_pk_fma_f32 v[86:87], v[26:27], v[66:67], v[86:87]
	v_cvt_pk_bf16_f32 v70, v70, v71
	v_pk_fma_f32 v[86:87], v[30:31], v[58:59], v[86:87]
	v_cvt_pk_bf16_f32 v71, v54, v55
	v_mul_f32_e32 v50, 0xbfb8aa3b, v86
	v_exp_f32_e32 v88, v50
	v_mul_f32_e32 v50, 0xbfb8aa3b, v87
	v_exp_f32_e32 v89, v50
	v_cvt_pk_bf16_f32 v72, v72, v73
	v_cvt_pk_bf16_f32 v73, v56, v57
	ds_write_b128 v104, v[70:73] offset:1088
	v_pk_add_f32 v[54:55], v[88:89], 1.0 op_sel_hi:[1,0]
	v_pk_fma_f32 v[82:83], v[2:3], v[82:83], 0 op_sel_hi:[1,1,0]


; DEV float bflo(unsigned u) { return __uint_as_float(u << 16); }
; DEV float bfhi(unsigned u) { return __uint_as_float(u & 0xffff0000u); }
; DEV void gdn_prep_chunk(const Params& p, int item, unsigned char* lds) {
;     ...
;             for (int e = 0; e < 8; ++e) {
;                 float a = 0.f;
; #pragma unroll
;                 for (int j = 0; j < 4; ++j) {
;                     const uint4 u = raw[r + j];
;                     const unsigned wd = (e < 2 ? u.x : (e < 4 ? u.y : (e < 6 ? u.z : u.w)));
;                     const float xv = (e & 1) ? bfhi(wd) : bflo(wd);
;                     a += w[j][e] * xv;
;                 }
	v_pk_fma_f32 v[82:83], v[6:7], v[74:75], v[82:83]


; DEV float silu_f(float x) { return x / (1.f + __expf(-x)); }
; DEV void gdn_prep_chunk(const Params& p, int item, unsigned char* lds) {
;     ...
;                 y[e] = silu_f(a); ss += y[e] * y[e];
	v_rcp_f32_e32 v50, v55
	s_nop 0
	v_mul_f32_e32 v71, v87, v50


; DEV float bflo(unsigned u) { return __uint_as_float(u << 16); }
; DEV float bfhi(unsigned u) { return __uint_as_float(u & 0xffff0000u); }
; DEV void gdn_prep_chunk(const Params& p, int item, unsigned char* lds) {
;     ...
;             for (int e = 0; e < 8; ++e) {
;                 float a = 0.f;
; #pragma unroll
;                 for (int j = 0; j < 4; ++j) {
;                     const uint4 u = raw[r + j];
;                     const unsigned wd = (e < 2 ? u.x : (e < 4 ? u.y : (e < 6 ? u.z : u.w)));
;                     const float xv = (e & 1) ? bfhi(wd) : bflo(wd);
;                     a += w[j][e] * xv;
;                 }
	v_lshlrev_b32_e32 v56, 16, v51
	v_and_b32_e32 v57, 0xffff0000, v51
	v_pk_fma_f32 v[50:51], v[20:21], v[84:85], 0 op_sel_hi:[1,1,0]

; DEV float bflo(unsigned u) { return __uint_as_float(u << 16); }
; DEV float bfhi(unsigned u) { return __uint_as_float(u & 0xffff0000u); }
; DEV void gdn_prep_chunk(const Params& p, int item, unsigned char* lds) {
;     ...
;             for (int e = 0; e < 8; ++e) {
;                 float a = 0.f;
; #pragma unroll
;                 for (int j = 0; j < 4; ++j) {
;                     const uint4 u = raw[r + j];
;                     const unsigned wd = (e < 2 ? u.x : (e < 4 ? u.y : (e < 6 ? u.z : u.w)));
;                     const float xv = (e & 1) ? bfhi(wd) : bflo(wd);
;                     a += w[j][e] * xv;
;                 }
	v_pk_fma_f32 v[50:51], v[24:25], v[76:77], v[50:51]

; DEV float bflo(unsigned u) { return __uint_as_float(u << 16); }
; DEV float bfhi(unsigned u) { return __uint_as_float(u & 0xffff0000u); }
; DEV void gdn_prep_chunk(const Params& p, int item, unsigned char* lds) {
;     ...
;             for (int e = 0; e < 8; ++e) {
;                 float a = 0.f;
; #pragma unroll
;                 for (int j = 0; j < 4; ++j) {
;                     const uint4 u = raw[r + j];
;                     const unsigned wd = (e < 2 ? u.x : (e < 4 ? u.y : (e < 6 ? u.z : u.w)));
;                     const float xv = (e & 1) ? bfhi(wd) : bflo(wd);
;                     a += w[j][e] * xv;
;                 }
	v_pk_fma_f32 v[50:51], v[28:29], v[64:65], v[50:51]

; DEV float bflo(unsigned u) { return __uint_as_float(u << 16); }
; DEV float bfhi(unsigned u) { return __uint_as_float(u & 0xffff0000u); }
; DEV void gdn_prep_chunk(const Params& p, int item, unsigned char* lds) {
;     ...
;             for (int e = 0; e < 8; ++e) {
;                 float a = 0.f;
; #pragma unroll
;                 for (int j = 0; j < 4; ++j) {
;                     const uint4 u = raw[r + j];
;                     const unsigned wd = (e < 2 ? u.x : (e < 4 ? u.y : (e < 6 ? u.z : u.w)));
;                     const float xv = (e & 1) ? bfhi(wd) : bflo(wd);
;                     a += w[j][e] * xv;
;                 }
	v_pk_fma_f32 v[50:51], v[32:33], v[56:57], v[50:51]

; DEV float silu_f(float x) { return x / (1.f + __expf(-x)); }
; DEV void gdn_prep_chunk(const Params& p, int item, unsigned char* lds) {
;     ...
;                 y[e] = silu_f(a); ss += y[e] * y[e];
	v_mul_f32_e32 v72, 0xbfb8aa3b, v50
	v_mul_f32_e32 v73, 0xbfb8aa3b, v51
	v_exp_f32_e32 v72, v72
	v_exp_f32_e32 v73, v73


; DEV float bflo(unsigned u) { return __uint_as_float(u << 16); }
; DEV float bfhi(unsigned u) { return __uint_as_float(u & 0xffff0000u); }
; DEV float silu_f(float x) { return x / (1.f + __expf(-x)); }
; DEV void gdn_prep_chunk(const Params& p, int item, unsigned char* lds) {
;     ...
;             for (int e = 0; e < 8; ++e) {
;                 float a = 0.f;
; #pragma unroll
;                 for (int j = 0; j < 4; ++j) {
;                     const uint4 u = raw[r + j];
;                     const unsigned wd = (e < 2 ? u.x : (e < 4 ? u.y : (e < 6 ? u.z : u.w)));
;                     const float xv = (e & 1) ? bfhi(wd) : bflo(wd);
;                     a += w[j][e] * xv;
;                 }
;                 y[e] = silu_f(a); ss += y[e] * y[e];
	v_rcp_f32_e32 v55, v54
	s_nop 0
	v_mul_f32_e32 v70, v86, v55
	v_pk_add_f32 v[72:73], v[72:73], 1.0 op_sel_hi:[1,0]
	v_pk_fma_f32 v[82:83], v[10:11], v[62:63], v[82:83]


; DEV float silu_f(float x) { return x / (1.f + __expf(-x)); }
; DEV void gdn_prep_chunk(const Params& p, int item, unsigned char* lds) {
;     ...
;                 y[e] = silu_f(a); ss += y[e] * y[e];
	s_nop 0


; DEV float bflo(unsigned u) { return __uint_as_float(u << 16); }
; DEV float bfhi(unsigned u) { return __uint_as_float(u & 0xffff0000u); }
; DEV float silu_f(float x) { return x / (1.f + __expf(-x)); }
; DEV void gdn_prep_chunk(const Params& p, int item, unsigned char* lds) {
;     ...
;             for (int e = 0; e < 8; ++e) {
;                 float a = 0.f;
; #pragma unroll
;                 for (int j = 0; j < 4; ++j) {
;                     const uint4 u = raw[r + j];
;                     const unsigned wd = (e < 2 ? u.x : (e < 4 ? u.y : (e < 6 ? u.z : u.w)));
;                     const float xv = (e & 1) ? bfhi(wd) : bflo(wd);
;                     a += w[j][e] * xv;
;                 }
;                 y[e] = silu_f(a); ss += y[e] * y[e];
	v_rcp_f32_e32 v54, v73
	s_nop 0
	v_mul_f32_e32 v85, v51, v54
	v_lshlrev_b32_e32 v54, 16, v52
	v_and_b32_e32 v55, 0xffff0000, v52

; DEV float bflo(unsigned u) { return __uint_as_float(u << 16); }
; DEV float bfhi(unsigned u) { return __uint_as_float(u & 0xffff0000u); }
; DEV void gdn_prep_chunk(const Params& p, int item, unsigned char* lds) {
;     ...
;             for (int e = 0; e < 8; ++e) {
;                 float a = 0.f;
; #pragma unroll
;                 for (int j = 0; j < 4; ++j) {
;                     const uint4 u = raw[r + j];
;                     const unsigned wd = (e < 2 ? u.x : (e < 4 ? u.y : (e < 6 ? u.z : u.w)));
;                     const float xv = (e & 1) ? bfhi(wd) : bflo(wd);
;                     a += w[j][e] * xv;
;                 }
	v_pk_fma_f32 v[82:83], v[14:15], v[54:55], v[82:83]

; DEV float silu_f(float x) { return x / (1.f + __expf(-x)); }
; DEV void gdn_prep_chunk(const Params& p, int item, unsigned char* lds) {
;     ...
;                 y[e] = silu_f(a); ss += y[e] * y[e];
	v_mul_f32_e32 v52, 0xbfb8aa3b, v82
	v_exp_f32_e32 v86, v52
	v_mul_f32_e32 v52, 0xbfb8aa3b, v83
	v_exp_f32_e32 v87, v52


; DEV float silu_f(float x) { return x / (1.f + __expf(-x)); }
; DEV void gdn_prep_chunk(const Params& p, int item, unsigned char* lds) {
;     ...
;                 y[e] = silu_f(a); ss += y[e] * y[e];
	s_nop 0
	v_pk_add_f32 v[86:87], v[86:87], 1.0 op_sel_hi:[1,0]


; DEV float silu_f(float x) { return x / (1.f + __expf(-x)); }
; DEV void gdn_prep_chunk(const Params& p, int item, unsigned char* lds) {
;     ...
;                 y[e] = silu_f(a); ss += y[e] * y[e];
	v_rcp_f32_e32 v51, v72
	s_nop 0
	v_mul_f32_e32 v84, v50, v51


; DEV float silu_f(float x) { return x / (1.f + __expf(-x)); }
; DEV void gdn_prep_chunk(const Params& p, int item, unsigned char* lds) {
;     ...
;                 y[e] = silu_f(a); ss += y[e] * y[e];
	v_rcp_f32_e32 v50, v87
	s_nop 0
	v_mul_f32_e32 v83, v83, v50


; DEV float bflo(unsigned u) { return __uint_as_float(u << 16); }
; DEV float bfhi(unsigned u) { return __uint_as_float(u & 0xffff0000u); }
; DEV void gdn_prep_chunk(const Params& p, int item, unsigned char* lds) {
;     ...
;             for (int e = 0; e < 8; ++e) {
;                 float a = 0.f;
; #pragma unroll
;                 for (int j = 0; j < 4; ++j) {
;                     const uint4 u = raw[r + j];
;                     const unsigned wd = (e < 2 ? u.x : (e < 4 ? u.y : (e < 6 ? u.z : u.w)));
;                     const float xv = (e & 1) ? bfhi(wd) : bflo(wd);
;                     a += w[j][e] * xv;
;                 }
	v_lshlrev_b32_e32 v50, 16, v53
	v_and_b32_e32 v51, 0xffff0000, v53
	v_pk_fma_f32 v[52:53], v[4:5], v[80:81], 0 op_sel_hi:[1,1,0]

; DEV float bflo(unsigned u) { return __uint_as_float(u << 16); }
; DEV float bfhi(unsigned u) { return __uint_as_float(u & 0xffff0000u); }
; DEV void gdn_prep_chunk(const Params& p, int item, unsigned char* lds) {
;     ...
;             for (int e = 0; e < 8; ++e) {
;                 float a = 0.f;
; #pragma unroll
;                 for (int j = 0; j < 4; ++j) {
;                     const uint4 u = raw[r + j];
;                     const unsigned wd = (e < 2 ? u.x : (e < 4 ? u.y : (e < 6 ? u.z : u.w)));
;                     const float xv = (e & 1) ? bfhi(wd) : bflo(wd);
;                     a += w[j][e] * xv;
;                 }
	v_pk_fma_f32 v[52:53], v[8:9], v[68:69], v[52:53]

; DEV float bflo(unsigned u) { return __uint_as_float(u << 16); }
; DEV float bfhi(unsigned u) { return __uint_as_float(u & 0xffff0000u); }
; DEV void gdn_prep_chunk(const Params& p, int item, unsigned char* lds) {
;     ...
;             for (int e = 0; e < 8; ++e) {
;                 float a = 0.f;
; #pragma unroll
;                 for (int j = 0; j < 4; ++j) {
;                     const uint4 u = raw[r + j];
;                     const unsigned wd = (e < 2 ? u.x : (e < 4 ? u.y : (e < 6 ? u.z : u.w)));
;                     const float xv = (e & 1) ? bfhi(wd) : bflo(wd);
;                     a += w[j][e] * xv;
;                 }
	v_pk_fma_f32 v[52:53], v[12:13], v[60:61], v[52:53]

; DEV float bflo(unsigned u) { return __uint_as_float(u << 16); }
; DEV float bfhi(unsigned u) { return __uint_as_float(u & 0xffff0000u); }
; DEV void gdn_prep_chunk(const Params& p, int item, unsigned char* lds) {
;     ...
;             for (int e = 0; e < 8; ++e) {
;                 float a = 0.f;
; #pragma unroll
;                 for (int j = 0; j < 4; ++j) {
;                     const uint4 u = raw[r + j];
;                     const unsigned wd = (e < 2 ? u.x : (e < 4 ? u.y : (e < 6 ? u.z : u.w)));
;                     const float xv = (e & 1) ? bfhi(wd) : bflo(wd);
;                     a += w[j][e] * xv;
;                 }
	v_pk_fma_f32 v[52:53], v[16:17], v[50:51], v[52:53]

; DEV float silu_f(float x) { return x / (1.f + __expf(-x)); }
; DEV void gdn_prep_chunk(const Params& p, int item, unsigned char* lds) {
;     ...
;                 y[e] = silu_f(a); ss += y[e] * y[e];
	v_mul_f32_e32 v72, 0xbfb8aa3b, v52
	v_mul_f32_e32 v73, 0xbfb8aa3b, v53
	v_exp_f32_e32 v72, v72
	v_exp_f32_e32 v73, v73


; DEV float silu_f(float x) { return x / (1.f + __expf(-x)); }
; DEV void gdn_prep_chunk(const Params& p, int item, unsigned char* lds) {
;     ...
;                 y[e] = silu_f(a); ss += y[e] * y[e];
	v_rcp_f32_e32 v80, v86
	s_nop 0
	v_mul_f32_e32 v82, v82, v80
	v_pk_add_f32 v[72:73], v[72:73], 1.0 op_sel_hi:[1,0]
	s_nop 0


; DEV float silu_f(float x) { return x / (1.f + __expf(-x)); }
; DEV void gdn_prep_chunk(const Params& p, int item, unsigned char* lds) {
;     ...
;                 y[e] = silu_f(a); ss += y[e] * y[e];
	s_nop 0


; DEV float silu_f(float x) { return x / (1.f + __expf(-x)); }
; DEV void gdn_prep_chunk(const Params& p, int item, unsigned char* lds) {
;     ...
;                 y[e] = silu_f(a); ss += y[e] * y[e];
	v_rcp_f32_e32 v80, v73
	s_nop 0
	v_mul_f32_e32 v53, v53, v80


; DEV float silu_f(float x) { return x / (1.f + __expf(-x)); }
; DEV void gdn_prep_chunk(const Params& p, int item, unsigned char* lds) {
;     ...
;                 y[e] = silu_f(a); ss += y[e] * y[e];
;             }
;             if (mat < 2) {
;                 ss += __shfl_xor(ss, 1); ss += __shfl_xor(ss, 2); ss += __shfl_xor(ss, 4); ss += __shfl_xor(ss, 8);
	v_rcp_f32_e32 v73, v72
	s_nop 0
	v_mul_f32_e32 v52, v52, v73
	s_and_saveexec_b64 s[36:37], s[6:7]
	s_cbranch_execz .LBB0_496
	v_pk_mul_f32 v[72:73], v[70:71], v[70:71]
	v_pk_mul_f32 v[80:81], v[84:85], v[84:85]
	v_add_f32_e32 v72, v72, v73
	v_add_f32_e32 v72, v72, v80
	v_pk_mul_f32 v[86:87], v[82:83], v[82:83]
	v_add_f32_e32 v72, v81, v72
	v_and_b32_e32 v80, 64, v182
	v_add_f32_e32 v72, v86, v72

; DEV float silu_f(float x) { return x / (1.f + __expf(-x)); }
; DEV void gdn_prep_chunk(const Params& p, int item, unsigned char* lds) {
;     ...
;                 y[e] = silu_f(a); ss += y[e] * y[e];
;             }
;             if (mat < 2) {
;                 ss += __shfl_xor(ss, 1); ss += __shfl_xor(ss, 2); ss += __shfl_xor(ss, 4); ss += __shfl_xor(ss, 8);
	v_add_u32_e32 v80, 64, v80
	v_pk_mul_f32 v[88:89], v[52:53], v[52:53]
	v_add_f32_e32 v72, v87, v72

; DEV float silu_f(float x) { return x / (1.f + __expf(-x)); }
; DEV void gdn_prep_chunk(const Params& p, int item, unsigned char* lds) {
;     ...
;                 y[e] = silu_f(a); ss += y[e] * y[e];
;             }
;             if (mat < 2) {
;                 ss += __shfl_xor(ss, 1); ss += __shfl_xor(ss, 2); ss += __shfl_xor(ss, 4); ss += __shfl_xor(ss, 8);
	v_add_f32_e32 v72, v88, v72
	v_add_f32_e32 v72, v89, v72


; DEV void gdn_prep_chunk(const Params& p, int item, unsigned char* lds) {
;     ...
;                 ss += __shfl_xor(ss, 1); ss += __shfl_xor(ss, 2); ss += __shfl_xor(ss, 4); ss += __shfl_xor(ss, 8);
	s_waitcnt lgkmcnt(0)
	s_nop 1
	v_add_f32_dpp v72, v72, v72 quad_perm:[1,0,3,2] row_mask:0xf bank_mask:0xf


; DEV void gdn_prep_chunk(const Params& p, int item, unsigned char* lds) {
;     ...
;                 ss += __shfl_xor(ss, 1); ss += __shfl_xor(ss, 2); ss += __shfl_xor(ss, 4); ss += __shfl_xor(ss, 8);
	s_nop 1


; DEV void gdn_prep_chunk(const Params& p, int item, unsigned char* lds) {
;     ...
;                 ss += __shfl_xor(ss, 1); ss += __shfl_xor(ss, 2); ss += __shfl_xor(ss, 4); ss += __shfl_xor(ss, 8);
	s_waitcnt lgkmcnt(0)
	s_nop 1
	v_add_f32_dpp v72, v72, v72 quad_perm:[2,3,0,1] row_mask:0xf bank_mask:0xf


; DEV void gdn_prep_chunk(const Params& p, int item, unsigned char* lds) {
;     ...
;                 ss += __shfl_xor(ss, 1); ss += __shfl_xor(ss, 2); ss += __shfl_xor(ss, 4); ss += __shfl_xor(ss, 8);
	s_nop 1


; DEV void gdn_prep_chunk(const Params& p, int item, unsigned char* lds) {
;     ...
;                 ss += __shfl_xor(ss, 1); ss += __shfl_xor(ss, 2); ss += __shfl_xor(ss, 4); ss += __shfl_xor(ss, 8);
	s_waitcnt lgkmcnt(0)
	s_nop 1
	v_add_f32_dpp v72, v72, v72 row_half_mirror row_mask:0xf bank_mask:0xf


; DEV void gdn_prep_chunk(const Params& p, int item, unsigned char* lds) {
;     ...
;                 ss += __shfl_xor(ss, 1); ss += __shfl_xor(ss, 2); ss += __shfl_xor(ss, 4); ss += __shfl_xor(ss, 8);
	s_nop 1


; DEV unsigned cvt_pk_bf16(float lo, float hi) { const f32x2_t v = {lo, hi}; const bf16x2_t b = __builtin_convertvector(v, bf16x2_t); return __builtin_bit_cast(unsigned, b); }
; DEV float bflo(unsigned u) { return __uint_as_float(u << 16); }
; DEV float bfhi(unsigned u) { return __uint_as_float(u & 0xffff0000u); }
; DEV float silu_f(float x) { return x / (1.f + __expf(-x)); }
; DEV void gdn_prep_chunk(const Params& p, int item, unsigned char* lds) {
;     ...
;             for (int e = 0; e < 8; ++e) {
;                 float a = 0.f;
; #pragma unroll
;                 for (int j = 0; j < 4; ++j) {
;                     const uint4 u = raw[r + j];
;                     const unsigned wd = (e < 2 ? u.x : (e < 4 ? u.y : (e < 6 ? u.z : u.w)));
;                     const float xv = (e & 1) ? bfhi(wd) : bflo(wd);
;                     a += w[j][e] * xv;
;                 }
;                 y[e] = silu_f(a); ss += y[e] * y[e];
;     ...
;                 ss += __shfl_xor(ss, 1); ss += __shfl_xor(ss, 2); ss += __shfl_xor(ss, 4); ss += __shfl_xor(ss, 8);
;                 float inv = rsqrtf(ss + EPS); if (mat == 0) inv *= 0.08838834764831845f;
; #pragma unroll
;                 for (int e = 0; e < 8; ++e) y[e] *= inv;
;             }
;             uint4 o; o.x = cvt_pk_bf16(y[0], y[1]); o.y = cvt_pk_bf16(y[2], y[3]); o.z = cvt_pk_bf16(y[4], y[5]); o.w = cvt_pk_bf16(y[6], y[7]);
;             *(uint4*)(dst + (tl0 + r) * QS + cv * 8) = o;
	s_waitcnt lgkmcnt(0)
	s_nop 1
	v_add_f32_dpp v72, v72, v72 row_mirror row_mask:0xf bank_mask:0xf
	v_add_f32_e32 v72, 0x358637bd, v72
	v_mul_f32_e32 v73, 0x4b800000, v72
	v_cmp_gt_f32_e32 vcc, s56, v72
	s_nop 1
	v_cndmask_b32_e32 v72, v72, v73, vcc
	v_rsq_f32_e32 v72, v72
	s_nop 0
	v_mul_f32_e32 v73, 0x45800000, v72
	v_cndmask_b32_e32 v72, v72, v73, vcc
	v_mul_f32_e32 v73, 0x3db504f3, v72
	v_cndmask_b32_e64 v72, v72, v73, s[4:5]
	v_pk_mul_f32 v[70:71], v[70:71], v[72:73] op_sel_hi:[1,0]
	v_pk_mul_f32 v[84:85], v[84:85], v[72:73] op_sel_hi:[1,0]
	v_pk_mul_f32 v[82:83], v[82:83], v[72:73] op_sel_hi:[1,0]
	v_pk_mul_f32 v[52:53], v[52:53], v[72:73] op_sel_hi:[1,0]
.LBB0_496:
	s_or_b64 exec, exec, s[36:37]
	v_pk_fma_f32 v[78:79], v[18:19], v[78:79], 0 op_sel_hi:[1,1,0]
	s_waitcnt vmcnt(3)
	v_lshlrev_b32_e32 v72, 16, v46
	v_pk_fma_f32 v[78:79], v[22:23], v[66:67], v[78:79]
	v_and_b32_e32 v73, 0xffff0000, v46
	v_pk_fma_f32 v[78:79], v[26:27], v[58:59], v[78:79]
	v_pk_fma_f32 v[74:75], v[2:3], v[74:75], 0 op_sel_hi:[1,1,0]
	v_pk_fma_f32 v[86:87], v[30:31], v[72:73], v[78:79]
	v_cvt_pk_bf16_f32 v79, v84, v85
	v_mul_f32_e32 v46, 0xbfb8aa3b, v86
	v_exp_f32_e32 v80, v46
	v_mul_f32_e32 v46, 0xbfb8aa3b, v87
	v_exp_f32_e32 v81, v46
	v_cvt_pk_bf16_f32 v78, v70, v71
	v_pk_fma_f32 v[74:75], v[6:7], v[62:63], v[74:75]
	v_pk_add_f32 v[84:85], v[80:81], 1.0 op_sel_hi:[1,0]
	s_nop 0


; DEV unsigned cvt_pk_bf16(float lo, float hi) { const f32x2_t v = {lo, hi}; const bf16x2_t b = __builtin_convertvector(v, bf16x2_t); return __builtin_bit_cast(unsigned, b); }
; DEV void gdn_prep_chunk(const Params& p, int item, unsigned char* lds) {
;     ...
;             uint4 o; o.x = cvt_pk_bf16(y[0], y[1]); o.y = cvt_pk_bf16(y[2], y[3]); o.z = cvt_pk_bf16(y[4], y[5]); o.w = cvt_pk_bf16(y[6], y[7]);
;             *(uint4*)(dst + (tl0 + r) * QS + cv * 8) = o;
	v_cvt_pk_bf16_f32 v81, v52, v53
	v_cvt_pk_bf16_f32 v80, v82, v83
	ds_write_b128 v104, v[78:81] offset:1360


; DEV float silu_f(float x) { return x / (1.f + __expf(-x)); }
; DEV void gdn_prep_chunk(const Params& p, int item, unsigned char* lds) {
;     ...
;                 y[e] = silu_f(a); ss += y[e] * y[e];
	v_rcp_f32_e32 v46, v85
	s_nop 0
	v_mul_f32_e32 v79, v87, v46


; DEV float bflo(unsigned u) { return __uint_as_float(u << 16); }
; DEV float bfhi(unsigned u) { return __uint_as_float(u & 0xffff0000u); }
; DEV void gdn_prep_chunk(const Params& p, int item, unsigned char* lds) {
;     ...
;                     const uint4 u = raw[r + j];
;                     const unsigned wd = (e < 2 ? u.x : (e < 4 ? u.y : (e < 6 ? u.z : u.w)));
;                     const float xv = (e & 1) ? bfhi(wd) : bflo(wd);
;                     a += w[j][e] * xv;
	v_lshlrev_b32_e32 v70, 16, v47
	v_and_b32_e32 v71, 0xffff0000, v47
	v_pk_fma_f32 v[46:47], v[20:21], v[76:77], 0 op_sel_hi:[1,1,0]

; DEV float bflo(unsigned u) { return __uint_as_float(u << 16); }
; DEV float bfhi(unsigned u) { return __uint_as_float(u & 0xffff0000u); }
; DEV void gdn_prep_chunk(const Params& p, int item, unsigned char* lds) {
;     ...
;                 for (int j = 0; j < 4; ++j) {
;                     const uint4 u = raw[r + j];
;                     const unsigned wd = (e < 2 ? u.x : (e < 4 ? u.y : (e < 6 ? u.z : u.w)));
;                     const float xv = (e & 1) ? bfhi(wd) : bflo(wd);
;                     a += w[j][e] * xv;
	v_pk_fma_f32 v[46:47], v[24:25], v[64:65], v[46:47]

; DEV float bflo(unsigned u) { return __uint_as_float(u << 16); }
; DEV float bfhi(unsigned u) { return __uint_as_float(u & 0xffff0000u); }
; DEV void gdn_prep_chunk(const Params& p, int item, unsigned char* lds) {
;     ...
;                 for (int j = 0; j < 4; ++j) {
;                     const uint4 u = raw[r + j];
;                     const unsigned wd = (e < 2 ? u.x : (e < 4 ? u.y : (e < 6 ? u.z : u.w)));
;                     const float xv = (e & 1) ? bfhi(wd) : bflo(wd);
;                     a += w[j][e] * xv;
	v_pk_fma_f32 v[46:47], v[28:29], v[56:57], v[46:47]

; DEV float bflo(unsigned u) { return __uint_as_float(u << 16); }
; DEV float bfhi(unsigned u) { return __uint_as_float(u & 0xffff0000u); }
; DEV void gdn_prep_chunk(const Params& p, int item, unsigned char* lds) {
;     ...
;                 for (int j = 0; j < 4; ++j) {
;                     const uint4 u = raw[r + j];
;                     const unsigned wd = (e < 2 ? u.x : (e < 4 ? u.y : (e < 6 ? u.z : u.w)));
;                     const float xv = (e & 1) ? bfhi(wd) : bflo(wd);
;                     a += w[j][e] * xv;
	v_pk_fma_f32 v[46:47], v[32:33], v[70:71], v[46:47]

; DEV float silu_f(float x) { return x / (1.f + __expf(-x)); }
; DEV void gdn_prep_chunk(const Params& p, int item, unsigned char* lds) {
;     ...
;                 y[e] = silu_f(a); ss += y[e] * y[e];
	v_mul_f32_e32 v52, 0xbfb8aa3b, v46
	v_mul_f32_e32 v53, 0xbfb8aa3b, v47
	v_exp_f32_e32 v52, v52
	v_exp_f32_e32 v53, v53


; DEV float bflo(unsigned u) { return __uint_as_float(u << 16); }
; DEV float bfhi(unsigned u) { return __uint_as_float(u & 0xffff0000u); }
; DEV float silu_f(float x) { return x / (1.f + __expf(-x)); }
; DEV void gdn_prep_chunk(const Params& p, int item, unsigned char* lds) {
;     ...
;                 for (int j = 0; j < 4; ++j) {
;                     const uint4 u = raw[r + j];
;                     const unsigned wd = (e < 2 ? u.x : (e < 4 ? u.y : (e < 6 ? u.z : u.w)));
;                     const float xv = (e & 1) ? bfhi(wd) : bflo(wd);
;                     a += w[j][e] * xv;
;                 }
;                 y[e] = silu_f(a); ss += y[e] * y[e];
	v_pk_fma_f32 v[74:75], v[10:11], v[54:55], v[74:75]
	v_pk_add_f32 v[76:77], v[52:53], 1.0 op_sel_hi:[1,0]
	v_rcp_f32_e32 v78, v84
	s_nop 0
	v_mul_f32_e32 v78, v86, v78


; DEV float silu_f(float x) { return x / (1.f + __expf(-x)); }
; DEV void gdn_prep_chunk(const Params& p, int item, unsigned char* lds) {
;     ...
;                 y[e] = silu_f(a); ss += y[e] * y[e];
	s_nop 0


; DEV float bflo(unsigned u) { return __uint_as_float(u << 16); }
; DEV float bfhi(unsigned u) { return __uint_as_float(u & 0xffff0000u); }
; DEV float silu_f(float x) { return x / (1.f + __expf(-x)); }
; DEV void gdn_prep_chunk(const Params& p, int item, unsigned char* lds) {
;     ...
;                     const uint4 u = raw[r + j];
;                     const unsigned wd = (e < 2 ? u.x : (e < 4 ? u.y : (e < 6 ? u.z : u.w)));
;                     const float xv = (e & 1) ? bfhi(wd) : bflo(wd);
;                     a += w[j][e] * xv;
;                 }
;                 y[e] = silu_f(a); ss += y[e] * y[e];
	v_rcp_f32_e32 v52, v77
	s_nop 0
	v_mul_f32_e32 v77, v47, v52
	v_lshlrev_b32_e32 v52, 16, v48
	v_and_b32_e32 v53, 0xffff0000, v48

; DEV float bflo(unsigned u) { return __uint_as_float(u << 16); }
; DEV float bfhi(unsigned u) { return __uint_as_float(u & 0xffff0000u); }
; DEV void gdn_prep_chunk(const Params& p, int item, unsigned char* lds) {
;     ...
;                 for (int j = 0; j < 4; ++j) {
;                     const uint4 u = raw[r + j];
;                     const unsigned wd = (e < 2 ? u.x : (e < 4 ? u.y : (e < 6 ? u.z : u.w)));
;                     const float xv = (e & 1) ? bfhi(wd) : bflo(wd);
;                     a += w[j][e] * xv;
	v_pk_fma_f32 v[74:75], v[14:15], v[52:53], v[74:75]

; DEV float silu_f(float x) { return x / (1.f + __expf(-x)); }
; DEV void gdn_prep_chunk(const Params& p, int item, unsigned char* lds) {
;     ...
;                 y[e] = silu_f(a); ss += y[e] * y[e];
	v_mul_f32_e32 v48, 0xbfb8aa3b, v74
	v_exp_f32_e32 v80, v48
	v_mul_f32_e32 v48, 0xbfb8aa3b, v75
	v_exp_f32_e32 v81, v48


; DEV float silu_f(float x) { return x / (1.f + __expf(-x)); }
; DEV void gdn_prep_chunk(const Params& p, int item, unsigned char* lds) {
;     ...
;                 y[e] = silu_f(a); ss += y[e] * y[e];
	s_nop 0
	v_pk_add_f32 v[80:81], v[80:81], 1.0 op_sel_hi:[1,0]


; DEV float silu_f(float x) { return x / (1.f + __expf(-x)); }
; DEV void gdn_prep_chunk(const Params& p, int item, unsigned char* lds) {
;     ...
;                 y[e] = silu_f(a); ss += y[e] * y[e];
	v_rcp_f32_e32 v47, v76
	s_nop 0
	v_mul_f32_e32 v76, v46, v47


; DEV float silu_f(float x) { return x / (1.f + __expf(-x)); }
; DEV void gdn_prep_chunk(const Params& p, int item, unsigned char* lds) {
;     ...
;                 y[e] = silu_f(a); ss += y[e] * y[e];
	v_rcp_f32_e32 v46, v81
	s_nop 0
	v_mul_f32_e32 v75, v75, v46


; DEV float bflo(unsigned u) { return __uint_as_float(u << 16); }
; DEV float bfhi(unsigned u) { return __uint_as_float(u & 0xffff0000u); }
; DEV void gdn_prep_chunk(const Params& p, int item, unsigned char* lds) {
;     ...
;                     const uint4 u = raw[r + j];
;                     const unsigned wd = (e < 2 ? u.x : (e < 4 ? u.y : (e < 6 ? u.z : u.w)));
;                     const float xv = (e & 1) ? bfhi(wd) : bflo(wd);
;                     a += w[j][e] * xv;
	v_lshlrev_b32_e32 v46, 16, v49
	v_and_b32_e32 v47, 0xffff0000, v49
	v_pk_fma_f32 v[48:49], v[4:5], v[68:69], 0 op_sel_hi:[1,1,0]

; DEV float bflo(unsigned u) { return __uint_as_float(u << 16); }
; DEV float bfhi(unsigned u) { return __uint_as_float(u & 0xffff0000u); }
; DEV void gdn_prep_chunk(const Params& p, int item, unsigned char* lds) {
;     ...
;                 for (int j = 0; j < 4; ++j) {
;                     const uint4 u = raw[r + j];
;                     const unsigned wd = (e < 2 ? u.x : (e < 4 ? u.y : (e < 6 ? u.z : u.w)));
;                     const float xv = (e & 1) ? bfhi(wd) : bflo(wd);
;                     a += w[j][e] * xv;
	v_pk_fma_f32 v[48:49], v[8:9], v[60:61], v[48:49]

; DEV float bflo(unsigned u) { return __uint_as_float(u << 16); }
; DEV float bfhi(unsigned u) { return __uint_as_float(u & 0xffff0000u); }
; DEV void gdn_prep_chunk(const Params& p, int item, unsigned char* lds) {
;     ...
;                 for (int j = 0; j < 4; ++j) {
;                     const uint4 u = raw[r + j];
;                     const unsigned wd = (e < 2 ? u.x : (e < 4 ? u.y : (e < 6 ? u.z : u.w)));
;                     const float xv = (e & 1) ? bfhi(wd) : bflo(wd);
;                     a += w[j][e] * xv;
	v_pk_fma_f32 v[48:49], v[12:13], v[50:51], v[48:49]

; DEV float bflo(unsigned u) { return __uint_as_float(u << 16); }
; DEV float bfhi(unsigned u) { return __uint_as_float(u & 0xffff0000u); }
; DEV void gdn_prep_chunk(const Params& p, int item, unsigned char* lds) {
;     ...
;                 for (int j = 0; j < 4; ++j) {
;                     const uint4 u = raw[r + j];
;                     const unsigned wd = (e < 2 ? u.x : (e < 4 ? u.y : (e < 6 ? u.z : u.w)));
;                     const float xv = (e & 1) ? bfhi(wd) : bflo(wd);
;                     a += w[j][e] * xv;
	v_pk_fma_f32 v[48:49], v[16:17], v[46:47], v[48:49]

; DEV float silu_f(float x) { return x / (1.f + __expf(-x)); }
; DEV void gdn_prep_chunk(const Params& p, int item, unsigned char* lds) {
;     ...
;                 y[e] = silu_f(a); ss += y[e] * y[e];
	v_mul_f32_e32 v68, 0xbfb8aa3b, v48
	v_mul_f32_e32 v69, 0xbfb8aa3b, v49
	v_exp_f32_e32 v68, v68
	v_exp_f32_e32 v69, v69


; DEV float silu_f(float x) { return x / (1.f + __expf(-x)); }
; DEV void gdn_prep_chunk(const Params& p, int item, unsigned char* lds) {
;     ...
;                 y[e] = silu_f(a); ss += y[e] * y[e];
	v_rcp_f32_e32 v81, v80
	s_nop 0
	v_mul_f32_e32 v74, v74, v81
	v_pk_add_f32 v[68:69], v[68:69], 1.0 op_sel_hi:[1,0]
	s_nop 0


; DEV float silu_f(float x) { return x / (1.f + __expf(-x)); }
; DEV void gdn_prep_chunk(const Params& p, int item, unsigned char* lds) {
;     ...
;                 y[e] = silu_f(a); ss += y[e] * y[e];
	s_nop 0


; DEV float silu_f(float x) { return x / (1.f + __expf(-x)); }
; DEV void gdn_prep_chunk(const Params& p, int item, unsigned char* lds) {
;     ...
;                 y[e] = silu_f(a); ss += y[e] * y[e];
	v_rcp_f32_e32 v80, v69
	s_nop 0
	v_mul_f32_e32 v49, v49, v80


; DEV float silu_f(float x) { return x / (1.f + __expf(-x)); }
; DEV void gdn_prep_chunk(const Params& p, int item, unsigned char* lds) {
;     ...
;                 y[e] = silu_f(a); ss += y[e] * y[e];
;             }
;             if (mat < 2) {
;                 ss += __shfl_xor(ss, 1); ss += __shfl_xor(ss, 2); ss += __shfl_xor(ss, 4); ss += __shfl_xor(ss, 8);
	v_rcp_f32_e32 v69, v68
	s_nop 0
	v_mul_f32_e32 v48, v48, v69
	s_and_saveexec_b64 s[36:37], s[6:7]
	s_cbranch_execz .LBB0_498
	v_pk_mul_f32 v[68:69], v[78:79], v[78:79]
	v_pk_mul_f32 v[80:81], v[76:77], v[76:77]
	v_add_f32_e32 v68, v68, v69
	v_add_f32_e32 v68, v68, v80
	v_pk_mul_f32 v[82:83], v[74:75], v[74:75]
	v_add_f32_e32 v68, v81, v68
	v_and_b32_e32 v80, 64, v182
	v_add_f32_e32 v68, v82, v68

; DEV void gdn_prep_chunk(const Params& p, int item, unsigned char* lds) {
;     ...
;                 ss += __shfl_xor(ss, 1); ss += __shfl_xor(ss, 2); ss += __shfl_xor(ss, 4); ss += __shfl_xor(ss, 8);
	v_add_u32_e32 v80, 64, v80
	v_pk_mul_f32 v[84:85], v[48:49], v[48:49]
	v_add_f32_e32 v68, v83, v68

; DEV void gdn_prep_chunk(const Params& p, int item, unsigned char* lds) {
;     ...
;                 ss += __shfl_xor(ss, 1); ss += __shfl_xor(ss, 2); ss += __shfl_xor(ss, 4); ss += __shfl_xor(ss, 8);
	v_add_f32_e32 v68, v84, v68
	v_add_f32_e32 v68, v85, v68


; DEV void gdn_prep_chunk(const Params& p, int item, unsigned char* lds) {
;     ...
;                 ss += __shfl_xor(ss, 1); ss += __shfl_xor(ss, 2); ss += __shfl_xor(ss, 4); ss += __shfl_xor(ss, 8);
	s_waitcnt lgkmcnt(0)
	s_nop 1
	v_add_f32_dpp v68, v68, v68 quad_perm:[1,0,3,2] row_mask:0xf bank_mask:0xf


; DEV void gdn_prep_chunk(const Params& p, int item, unsigned char* lds) {
;     ...
;                 ss += __shfl_xor(ss, 1); ss += __shfl_xor(ss, 2); ss += __shfl_xor(ss, 4); ss += __shfl_xor(ss, 8);
	s_nop 1


; DEV void gdn_prep_chunk(const Params& p, int item, unsigned char* lds) {
;     ...
;                 ss += __shfl_xor(ss, 1); ss += __shfl_xor(ss, 2); ss += __shfl_xor(ss, 4); ss += __shfl_xor(ss, 8);
	s_waitcnt lgkmcnt(0)
	s_nop 1
	v_add_f32_dpp v68, v68, v68 quad_perm:[2,3,0,1] row_mask:0xf bank_mask:0xf


; DEV void gdn_prep_chunk(const Params& p, int item, unsigned char* lds) {
;     ...
;                 ss += __shfl_xor(ss, 1); ss += __shfl_xor(ss, 2); ss += __shfl_xor(ss, 4); ss += __shfl_xor(ss, 8);
	s_nop 1


; DEV void gdn_prep_chunk(const Params& p, int item, unsigned char* lds) {
;     ...
;                 ss += __shfl_xor(ss, 1); ss += __shfl_xor(ss, 2); ss += __shfl_xor(ss, 4); ss += __shfl_xor(ss, 8);
	s_waitcnt lgkmcnt(0)
	s_nop 1
	v_add_f32_dpp v68, v68, v68 row_half_mirror row_mask:0xf bank_mask:0xf


; DEV void gdn_prep_chunk(const Params& p, int item, unsigned char* lds) {
;     ...
;                 ss += __shfl_xor(ss, 1); ss += __shfl_xor(ss, 2); ss += __shfl_xor(ss, 4); ss += __shfl_xor(ss, 8);
	s_nop 1


; DEV unsigned cvt_pk_bf16(float lo, float hi) { const f32x2_t v = {lo, hi}; const bf16x2_t b = __builtin_convertvector(v, bf16x2_t); return __builtin_bit_cast(unsigned, b); }
; DEV float bflo(unsigned u) { return __uint_as_float(u << 16); }
; DEV float bfhi(unsigned u) { return __uint_as_float(u & 0xffff0000u); }
; DEV float silu_f(float x) { return x / (1.f + __expf(-x)); }
; DEV void gdn_prep_chunk(const Params& p, int item, unsigned char* lds) {
;     ...
;             for (int e = 0; e < 8; ++e) {
;                 float a = 0.f;
; #pragma unroll
;                 for (int j = 0; j < 4; ++j) {
;                     const uint4 u = raw[r + j];
;                     const unsigned wd = (e < 2 ? u.x : (e < 4 ? u.y : (e < 6 ? u.z : u.w)));
;                     const float xv = (e & 1) ? bfhi(wd) : bflo(wd);
;                     a += w[j][e] * xv;
;                 }
;                 y[e] = silu_f(a); ss += y[e] * y[e];
;     ...
;                 ss += __shfl_xor(ss, 1); ss += __shfl_xor(ss, 2); ss += __shfl_xor(ss, 4); ss += __shfl_xor(ss, 8);
;                 float inv = rsqrtf(ss + EPS); if (mat == 0) inv *= 0.08838834764831845f;
; #pragma unroll
;                 for (int e = 0; e < 8; ++e) y[e] *= inv;
;             }
;             uint4 o; o.x = cvt_pk_bf16(y[0], y[1]); o.y = cvt_pk_bf16(y[2], y[3]); o.z = cvt_pk_bf16(y[4], y[5]); o.w = cvt_pk_bf16(y[6], y[7]);
;             *(uint4*)(dst + (tl0 + r) * QS + cv * 8) = o;
	s_waitcnt lgkmcnt(0)
	s_nop 1
	v_add_f32_dpp v68, v68, v68 row_mirror row_mask:0xf bank_mask:0xf
	v_add_f32_e32 v68, 0x358637bd, v68
	v_mul_f32_e32 v69, 0x4b800000, v68
	v_cmp_gt_f32_e32 vcc, s56, v68
	s_nop 1
	v_cndmask_b32_e32 v68, v68, v69, vcc
	v_rsq_f32_e32 v68, v68
	s_nop 0
	v_mul_f32_e32 v69, 0x45800000, v68
	v_cndmask_b32_e32 v68, v68, v69, vcc
	v_mul_f32_e32 v69, 0x3db504f3, v68
	v_cndmask_b32_e64 v68, v68, v69, s[4:5]
	v_pk_mul_f32 v[78:79], v[78:79], v[68:69] op_sel_hi:[1,0]
	v_pk_mul_f32 v[76:77], v[76:77], v[68:69] op_sel_hi:[1,0]
	v_pk_mul_f32 v[74:75], v[74:75], v[68:69] op_sel_hi:[1,0]
	v_pk_mul_f32 v[48:49], v[48:49], v[68:69] op_sel_hi:[1,0]
.LBB0_498:
	s_or_b64 exec, exec, s[36:37]
	v_pk_fma_f32 v[66:67], v[18:19], v[66:67], 0 op_sel_hi:[1,1,0]
	s_waitcnt vmcnt(2)
	v_lshlrev_b32_e32 v68, 16, v42
	v_pk_fma_f32 v[66:67], v[22:23], v[58:59], v[66:67]
	v_and_b32_e32 v69, 0xffff0000, v42
	v_pk_fma_f32 v[66:67], v[26:27], v[72:73], v[66:67]
	v_cvt_pk_bf16_f32 v78, v78, v79
	v_pk_fma_f32 v[82:83], v[30:31], v[68:69], v[66:67]
	v_cvt_pk_bf16_f32 v79, v76, v77
	v_mul_f32_e32 v42, 0xbfb8aa3b, v82
	v_exp_f32_e32 v66, v42
	v_mul_f32_e32 v42, 0xbfb8aa3b, v83
	v_exp_f32_e32 v67, v42
	v_cvt_pk_bf16_f32 v81, v48, v49
	v_cvt_pk_bf16_f32 v80, v74, v75
	ds_write_b128 v104, v[78:81] offset:1632
	v_pk_add_f32 v[76:77], v[66:67], 1.0 op_sel_hi:[1,0]
	v_pk_fma_f32 v[62:63], v[2:3], v[62:63], 0 op_sel_hi:[1,1,0]


; DEV float silu_f(float x) { return x / (1.f + __expf(-x)); }
; DEV void gdn_prep_chunk(const Params& p, int item, unsigned char* lds) {
;     ...
;                 y[e] = silu_f(a); ss += y[e] * y[e];
	v_rcp_f32_e32 v42, v77
	s_nop 0
	v_mul_f32_e32 v75, v83, v42


; DEV float bflo(unsigned u) { return __uint_as_float(u << 16); }
; DEV float bfhi(unsigned u) { return __uint_as_float(u & 0xffff0000u); }
; DEV void gdn_prep_chunk(const Params& p, int item, unsigned char* lds) {
;     ...
;                     const uint4 u = raw[r + j];
;                     const unsigned wd = (e < 2 ? u.x : (e < 4 ? u.y : (e < 6 ? u.z : u.w)));
;                     const float xv = (e & 1) ? bfhi(wd) : bflo(wd);
;                     a += w[j][e] * xv;
	v_lshlrev_b32_e32 v66, 16, v43
	v_and_b32_e32 v67, 0xffff0000, v43
	v_pk_fma_f32 v[42:43], v[20:21], v[64:65], 0 op_sel_hi:[1,1,0]

; DEV float bflo(unsigned u) { return __uint_as_float(u << 16); }
; DEV float bfhi(unsigned u) { return __uint_as_float(u & 0xffff0000u); }
; DEV void gdn_prep_chunk(const Params& p, int item, unsigned char* lds) {
;     ...
;                 for (int j = 0; j < 4; ++j) {
;                     const uint4 u = raw[r + j];
;                     const unsigned wd = (e < 2 ? u.x : (e < 4 ? u.y : (e < 6 ? u.z : u.w)));
;                     const float xv = (e & 1) ? bfhi(wd) : bflo(wd);
;                     a += w[j][e] * xv;
	v_pk_fma_f32 v[42:43], v[24:25], v[56:57], v[42:43]

; DEV float bflo(unsigned u) { return __uint_as_float(u << 16); }
; DEV float bfhi(unsigned u) { return __uint_as_float(u & 0xffff0000u); }
; DEV void gdn_prep_chunk(const Params& p, int item, unsigned char* lds) {
;     ...
;                 for (int j = 0; j < 4; ++j) {
;                     const uint4 u = raw[r + j];
;                     const unsigned wd = (e < 2 ? u.x : (e < 4 ? u.y : (e < 6 ? u.z : u.w)));
;                     const float xv = (e & 1) ? bfhi(wd) : bflo(wd);
;                     a += w[j][e] * xv;
	v_pk_fma_f32 v[42:43], v[28:29], v[70:71], v[42:43]

; DEV float bflo(unsigned u) { return __uint_as_float(u << 16); }
; DEV float bfhi(unsigned u) { return __uint_as_float(u & 0xffff0000u); }
; DEV void gdn_prep_chunk(const Params& p, int item, unsigned char* lds) {
;     ...
;                 for (int j = 0; j < 4; ++j) {
;                     const uint4 u = raw[r + j];
;                     const unsigned wd = (e < 2 ? u.x : (e < 4 ? u.y : (e < 6 ? u.z : u.w)));
;                     const float xv = (e & 1) ? bfhi(wd) : bflo(wd);
;                     a += w[j][e] * xv;
	v_pk_fma_f32 v[42:43], v[32:33], v[66:67], v[42:43]

; DEV float silu_f(float x) { return x / (1.f + __expf(-x)); }
; DEV void gdn_prep_chunk(const Params& p, int item, unsigned char* lds) {
;     ...
;                 y[e] = silu_f(a); ss += y[e] * y[e];
	v_mul_f32_e32 v48, 0xbfb8aa3b, v42
	v_mul_f32_e32 v49, 0xbfb8aa3b, v43
	v_exp_f32_e32 v48, v48
	v_exp_f32_e32 v49, v49


; DEV float bflo(unsigned u) { return __uint_as_float(u << 16); }
; DEV float bfhi(unsigned u) { return __uint_as_float(u & 0xffff0000u); }
; DEV float silu_f(float x) { return x / (1.f + __expf(-x)); }
; DEV void gdn_prep_chunk(const Params& p, int item, unsigned char* lds) {
;     ...
;                 for (int j = 0; j < 4; ++j) {
;                     const uint4 u = raw[r + j];
;                     const unsigned wd = (e < 2 ? u.x : (e < 4 ? u.y : (e < 6 ? u.z : u.w)));
;                     const float xv = (e & 1) ? bfhi(wd) : bflo(wd);
;                     a += w[j][e] * xv;
;                 }
;                 y[e] = silu_f(a); ss += y[e] * y[e];
	v_rcp_f32_e32 v74, v76
	s_nop 0
	v_mul_f32_e32 v74, v82, v74
	v_pk_add_f32 v[64:65], v[48:49], 1.0 op_sel_hi:[1,0]
	v_pk_fma_f32 v[62:63], v[6:7], v[54:55], v[62:63]


; DEV float bflo(unsigned u) { return __uint_as_float(u << 16); }
; DEV float bfhi(unsigned u) { return __uint_as_float(u & 0xffff0000u); }
; DEV void gdn_prep_chunk(const Params& p, int item, unsigned char* lds) {
;     ...
;                 for (int j = 0; j < 4; ++j) {
;                     const uint4 u = raw[r + j];
;                     const unsigned wd = (e < 2 ? u.x : (e < 4 ? u.y : (e < 6 ? u.z : u.w)));
;                     const float xv = (e & 1) ? bfhi(wd) : bflo(wd);
;                     a += w[j][e] * xv;
	v_pk_fma_f32 v[62:63], v[10:11], v[52:53], v[62:63]


; DEV float bflo(unsigned u) { return __uint_as_float(u << 16); }
; DEV float bfhi(unsigned u) { return __uint_as_float(u & 0xffff0000u); }
; DEV float silu_f(float x) { return x / (1.f + __expf(-x)); }
; DEV void gdn_prep_chunk(const Params& p, int item, unsigned char* lds) {
;     ...
;                     const uint4 u = raw[r + j];
;                     const unsigned wd = (e < 2 ? u.x : (e < 4 ? u.y : (e < 6 ? u.z : u.w)));
;                     const float xv = (e & 1) ? bfhi(wd) : bflo(wd);
;                     a += w[j][e] * xv;
;                 }
;                 y[e] = silu_f(a); ss += y[e] * y[e];
	v_rcp_f32_e32 v48, v65
	s_nop 0
	v_mul_f32_e32 v65, v43, v48
	v_lshlrev_b32_e32 v48, 16, v44
	v_and_b32_e32 v49, 0xffff0000, v44

; DEV float bflo(unsigned u) { return __uint_as_float(u << 16); }
; DEV float bfhi(unsigned u) { return __uint_as_float(u & 0xffff0000u); }
; DEV void gdn_prep_chunk(const Params& p, int item, unsigned char* lds) {
;     ...
;                 for (int j = 0; j < 4; ++j) {
;                     const uint4 u = raw[r + j];
;                     const unsigned wd = (e < 2 ? u.x : (e < 4 ? u.y : (e < 6 ? u.z : u.w)));
;                     const float xv = (e & 1) ? bfhi(wd) : bflo(wd);
;                     a += w[j][e] * xv;
	v_pk_fma_f32 v[62:63], v[14:15], v[48:49], v[62:63]

; DEV float silu_f(float x) { return x / (1.f + __expf(-x)); }
; DEV void gdn_prep_chunk(const Params& p, int item, unsigned char* lds) {
;     ...
;                 y[e] = silu_f(a); ss += y[e] * y[e];
	v_mul_f32_e32 v44, 0xbfb8aa3b, v62
	v_exp_f32_e32 v76, v44
	v_mul_f32_e32 v44, 0xbfb8aa3b, v63
	v_exp_f32_e32 v77, v44


; DEV float silu_f(float x) { return x / (1.f + __expf(-x)); }
; DEV void gdn_prep_chunk(const Params& p, int item, unsigned char* lds) {
;     ...
;                 y[e] = silu_f(a); ss += y[e] * y[e];
	s_nop 0
	v_pk_add_f32 v[76:77], v[76:77], 1.0 op_sel_hi:[1,0]


; DEV float silu_f(float x) { return x / (1.f + __expf(-x)); }
; DEV void gdn_prep_chunk(const Params& p, int item, unsigned char* lds) {
;     ...
;                 y[e] = silu_f(a); ss += y[e] * y[e];
	v_rcp_f32_e32 v43, v64
	s_nop 0
	v_mul_f32_e32 v64, v42, v43


; DEV float silu_f(float x) { return x / (1.f + __expf(-x)); }
; DEV void gdn_prep_chunk(const Params& p, int item, unsigned char* lds) {
;     ...
;                 y[e] = silu_f(a); ss += y[e] * y[e];
	v_rcp_f32_e32 v42, v77
	s_nop 0
	v_mul_f32_e32 v63, v63, v42


; DEV float bflo(unsigned u) { return __uint_as_float(u << 16); }
; DEV float bfhi(unsigned u) { return __uint_as_float(u & 0xffff0000u); }
; DEV void gdn_prep_chunk(const Params& p, int item, unsigned char* lds) {
;     ...
;                     const uint4 u = raw[r + j];
;                     const unsigned wd = (e < 2 ? u.x : (e < 4 ? u.y : (e < 6 ? u.z : u.w)));
;                     const float xv = (e & 1) ? bfhi(wd) : bflo(wd);
;                     a += w[j][e] * xv;
	v_lshlrev_b32_e32 v42, 16, v45
	v_and_b32_e32 v43, 0xffff0000, v45
	v_pk_fma_f32 v[44:45], v[4:5], v[60:61], 0 op_sel_hi:[1,1,0]

; DEV float bflo(unsigned u) { return __uint_as_float(u << 16); }
; DEV float bfhi(unsigned u) { return __uint_as_float(u & 0xffff0000u); }
; DEV void gdn_prep_chunk(const Params& p, int item, unsigned char* lds) {
;     ...
;                 for (int j = 0; j < 4; ++j) {
;                     const uint4 u = raw[r + j];
;                     const unsigned wd = (e < 2 ? u.x : (e < 4 ? u.y : (e < 6 ? u.z : u.w)));
;                     const float xv = (e & 1) ? bfhi(wd) : bflo(wd);
;                     a += w[j][e] * xv;
	v_pk_fma_f32 v[44:45], v[8:9], v[50:51], v[44:45]

; DEV float bflo(unsigned u) { return __uint_as_float(u << 16); }
; DEV float bfhi(unsigned u) { return __uint_as_float(u & 0xffff0000u); }
; DEV void gdn_prep_chunk(const Params& p, int item, unsigned char* lds) {
;     ...
;                 for (int j = 0; j < 4; ++j) {
;                     const uint4 u = raw[r + j];
;                     const unsigned wd = (e < 2 ? u.x : (e < 4 ? u.y : (e < 6 ? u.z : u.w)));
;                     const float xv = (e & 1) ? bfhi(wd) : bflo(wd);
;                     a += w[j][e] * xv;
	v_pk_fma_f32 v[44:45], v[12:13], v[46:47], v[44:45]

; DEV float bflo(unsigned u) { return __uint_as_float(u << 16); }
; DEV float bfhi(unsigned u) { return __uint_as_float(u & 0xffff0000u); }
; DEV void gdn_prep_chunk(const Params& p, int item, unsigned char* lds) {
;     ...
;                 for (int j = 0; j < 4; ++j) {
;                     const uint4 u = raw[r + j];
;                     const unsigned wd = (e < 2 ? u.x : (e < 4 ? u.y : (e < 6 ? u.z : u.w)));
;                     const float xv = (e & 1) ? bfhi(wd) : bflo(wd);
;                     a += w[j][e] * xv;
	v_pk_fma_f32 v[44:45], v[16:17], v[42:43], v[44:45]

; DEV float silu_f(float x) { return x / (1.f + __expf(-x)); }
; DEV void gdn_prep_chunk(const Params& p, int item, unsigned char* lds) {
;     ...
;                 y[e] = silu_f(a); ss += y[e] * y[e];
	v_mul_f32_e32 v60, 0xbfb8aa3b, v44
	v_mul_f32_e32 v61, 0xbfb8aa3b, v45
	v_exp_f32_e32 v60, v60
	v_exp_f32_e32 v61, v61


; DEV float silu_f(float x) { return x / (1.f + __expf(-x)); }
; DEV void gdn_prep_chunk(const Params& p, int item, unsigned char* lds) {
;     ...
;                 y[e] = silu_f(a); ss += y[e] * y[e];
	v_rcp_f32_e32 v77, v76
	s_nop 0
	v_mul_f32_e32 v62, v62, v77
	v_pk_add_f32 v[60:61], v[60:61], 1.0 op_sel_hi:[1,0]
	s_nop 0


; DEV float silu_f(float x) { return x / (1.f + __expf(-x)); }
; DEV void gdn_prep_chunk(const Params& p, int item, unsigned char* lds) {
;     ...
;                 y[e] = silu_f(a); ss += y[e] * y[e];
	s_nop 0


; DEV float silu_f(float x) { return x / (1.f + __expf(-x)); }
; DEV void gdn_prep_chunk(const Params& p, int item, unsigned char* lds) {
;     ...
;                 y[e] = silu_f(a); ss += y[e] * y[e];
	v_rcp_f32_e32 v76, v61
	s_nop 0
	v_mul_f32_e32 v45, v45, v76


; DEV float silu_f(float x) { return x / (1.f + __expf(-x)); }
; DEV void gdn_prep_chunk(const Params& p, int item, unsigned char* lds) {
;     ...
;                 y[e] = silu_f(a); ss += y[e] * y[e];
;             }
;             if (mat < 2) {
;                 ss += __shfl_xor(ss, 1); ss += __shfl_xor(ss, 2); ss += __shfl_xor(ss, 4); ss += __shfl_xor(ss, 8);
	v_rcp_f32_e32 v61, v60
	s_nop 0
	v_mul_f32_e32 v44, v44, v61
	s_and_saveexec_b64 s[36:37], s[6:7]
	s_cbranch_execz .LBB0_500
	v_pk_mul_f32 v[60:61], v[74:75], v[74:75]
	v_pk_mul_f32 v[76:77], v[64:65], v[64:65]
	v_add_f32_e32 v60, v60, v61
	v_add_f32_e32 v60, v60, v76
	v_pk_mul_f32 v[78:79], v[62:63], v[62:63]
	v_add_f32_e32 v60, v77, v60
	v_and_b32_e32 v76, 64, v182
	v_add_f32_e32 v60, v78, v60

; DEV void gdn_prep_chunk(const Params& p, int item, unsigned char* lds) {
;     ...
;                 ss += __shfl_xor(ss, 1); ss += __shfl_xor(ss, 2); ss += __shfl_xor(ss, 4); ss += __shfl_xor(ss, 8);
	v_add_u32_e32 v76, 64, v76
	v_pk_mul_f32 v[80:81], v[44:45], v[44:45]
	v_add_f32_e32 v60, v79, v60

; DEV float silu_f(float x) { return x / (1.f + __expf(-x)); }
; DEV void gdn_prep_chunk(const Params& p, int item, unsigned char* lds) {
;     ...
;                 y[e] = silu_f(a); ss += y[e] * y[e];
;             }
;             if (mat < 2) {
;                 ss += __shfl_xor(ss, 1); ss += __shfl_xor(ss, 2); ss += __shfl_xor(ss, 4); ss += __shfl_xor(ss, 8);
	v_add_f32_e32 v60, v80, v60
	v_add_f32_e32 v60, v81, v60


; DEV void gdn_prep_chunk(const Params& p, int item, unsigned char* lds) {
;     ...
;                 ss += __shfl_xor(ss, 1); ss += __shfl_xor(ss, 2); ss += __shfl_xor(ss, 4); ss += __shfl_xor(ss, 8);
	s_waitcnt lgkmcnt(0)
	s_nop 1
	v_add_f32_dpp v60, v60, v60 quad_perm:[1,0,3,2] row_mask:0xf bank_mask:0xf


; DEV void gdn_prep_chunk(const Params& p, int item, unsigned char* lds) {
;     ...
;                 ss += __shfl_xor(ss, 1); ss += __shfl_xor(ss, 2); ss += __shfl_xor(ss, 4); ss += __shfl_xor(ss, 8);
	s_nop 1


; DEV void gdn_prep_chunk(const Params& p, int item, unsigned char* lds) {
;     ...
;                 ss += __shfl_xor(ss, 1); ss += __shfl_xor(ss, 2); ss += __shfl_xor(ss, 4); ss += __shfl_xor(ss, 8);
	s_waitcnt lgkmcnt(0)
	s_nop 1
	v_add_f32_dpp v60, v60, v60 quad_perm:[2,3,0,1] row_mask:0xf bank_mask:0xf


; DEV void gdn_prep_chunk(const Params& p, int item, unsigned char* lds) {
;     ...
;                 ss += __shfl_xor(ss, 1); ss += __shfl_xor(ss, 2); ss += __shfl_xor(ss, 4); ss += __shfl_xor(ss, 8);
	s_nop 1


; DEV void gdn_prep_chunk(const Params& p, int item, unsigned char* lds) {
;     ...
;                 ss += __shfl_xor(ss, 1); ss += __shfl_xor(ss, 2); ss += __shfl_xor(ss, 4); ss += __shfl_xor(ss, 8);
	s_waitcnt lgkmcnt(0)
	s_nop 1
	v_add_f32_dpp v60, v60, v60 row_half_mirror row_mask:0xf bank_mask:0xf


; DEV void gdn_prep_chunk(const Params& p, int item, unsigned char* lds) {
;     ...
;                 ss += __shfl_xor(ss, 1); ss += __shfl_xor(ss, 2); ss += __shfl_xor(ss, 4); ss += __shfl_xor(ss, 8);
	s_nop 1


; DEV unsigned cvt_pk_bf16(float lo, float hi) { const f32x2_t v = {lo, hi}; const bf16x2_t b = __builtin_convertvector(v, bf16x2_t); return __builtin_bit_cast(unsigned, b); }
; DEV float bflo(unsigned u) { return __uint_as_float(u << 16); }
; DEV float bfhi(unsigned u) { return __uint_as_float(u & 0xffff0000u); }
; DEV float silu_f(float x) { return x / (1.f + __expf(-x)); }
; DEV void gdn_prep_chunk(const Params& p, int item, unsigned char* lds) {
;     ...
;             for (int e = 0; e < 8; ++e) {
;                 float a = 0.f;
; #pragma unroll
;                 for (int j = 0; j < 4; ++j) {
;                     const uint4 u = raw[r + j];
;                     const unsigned wd = (e < 2 ? u.x : (e < 4 ? u.y : (e < 6 ? u.z : u.w)));
;                     const float xv = (e & 1) ? bfhi(wd) : bflo(wd);
;                     a += w[j][e] * xv;
;                 }
;                 y[e] = silu_f(a); ss += y[e] * y[e];
;     ...
;                 ss += __shfl_xor(ss, 1); ss += __shfl_xor(ss, 2); ss += __shfl_xor(ss, 4); ss += __shfl_xor(ss, 8);
;                 float inv = rsqrtf(ss + EPS); if (mat == 0) inv *= 0.08838834764831845f;
; #pragma unroll
;                 for (int e = 0; e < 8; ++e) y[e] *= inv;
;             }
;             uint4 o; o.x = cvt_pk_bf16(y[0], y[1]); o.y = cvt_pk_bf16(y[2], y[3]); o.z = cvt_pk_bf16(y[4], y[5]); o.w = cvt_pk_bf16(y[6], y[7]);
;             *(uint4*)(dst + (tl0 + r) * QS + cv * 8) = o;
	s_waitcnt lgkmcnt(0)
	s_nop 1
	v_add_f32_dpp v60, v60, v60 row_mirror row_mask:0xf bank_mask:0xf
	v_add_f32_e32 v60, 0x358637bd, v60
	v_mul_f32_e32 v61, 0x4b800000, v60
	v_cmp_gt_f32_e32 vcc, s56, v60
	s_nop 1
	v_cndmask_b32_e32 v60, v60, v61, vcc
	v_rsq_f32_e32 v60, v60
	s_nop 0
	v_mul_f32_e32 v61, 0x45800000, v60
	v_cndmask_b32_e32 v60, v60, v61, vcc
	v_mul_f32_e32 v61, 0x3db504f3, v60
	v_cndmask_b32_e64 v60, v60, v61, s[4:5]
	v_pk_mul_f32 v[74:75], v[74:75], v[60:61] op_sel_hi:[1,0]
	v_pk_mul_f32 v[64:65], v[64:65], v[60:61] op_sel_hi:[1,0]
	v_pk_mul_f32 v[62:63], v[62:63], v[60:61] op_sel_hi:[1,0]
	v_pk_mul_f32 v[44:45], v[44:45], v[60:61] op_sel_hi:[1,0]
.LBB0_500:
	s_or_b64 exec, exec, s[36:37]
	v_pk_fma_f32 v[58:59], v[18:19], v[58:59], 0 op_sel_hi:[1,1,0]
	s_waitcnt vmcnt(1)
	v_lshlrev_b32_e32 v60, 16, v38
	v_pk_fma_f32 v[58:59], v[22:23], v[72:73], v[58:59]
	v_and_b32_e32 v61, 0xffff0000, v38
	v_pk_fma_f32 v[58:59], v[26:27], v[68:69], v[58:59]
	v_cvt_pk_bf16_f32 v74, v74, v75
	v_pk_fma_f32 v[78:79], v[30:31], v[60:61], v[58:59]
	v_cvt_pk_bf16_f32 v75, v64, v65
	v_mul_f32_e32 v38, 0xbfb8aa3b, v78
	v_exp_f32_e32 v58, v38
	v_mul_f32_e32 v38, 0xbfb8aa3b, v79
	v_exp_f32_e32 v59, v38
	v_cvt_pk_bf16_f32 v77, v44, v45
	v_cvt_pk_bf16_f32 v76, v62, v63
	ds_write_b128 v104, v[74:77] offset:1904
	v_pk_add_f32 v[64:65], v[58:59], 1.0 op_sel_hi:[1,0]
	v_pk_fma_f32 v[54:55], v[2:3], v[54:55], 0 op_sel_hi:[1,1,0]


; DEV float silu_f(float x) { return x / (1.f + __expf(-x)); }
; DEV void gdn_prep_chunk(const Params& p, int item, unsigned char* lds) {
;     ...
;                 y[e] = silu_f(a); ss += y[e] * y[e];
	v_rcp_f32_e32 v38, v65
	s_nop 0
	v_mul_f32_e32 v63, v79, v38


; DEV float bflo(unsigned u) { return __uint_as_float(u << 16); }
; DEV float bfhi(unsigned u) { return __uint_as_float(u & 0xffff0000u); }
; DEV void gdn_prep_chunk(const Params& p, int item, unsigned char* lds) {
;     ...
;             for (int e = 0; e < 8; ++e) {
;                 float a = 0.f;
; #pragma unroll
;                 for (int j = 0; j < 4; ++j) {
;                     const uint4 u = raw[r + j];
;                     const unsigned wd = (e < 2 ? u.x : (e < 4 ? u.y : (e < 6 ? u.z : u.w)));
;                     const float xv = (e & 1) ? bfhi(wd) : bflo(wd);
;                     a += w[j][e] * xv;
;                 }
	v_lshlrev_b32_e32 v58, 16, v39
	v_and_b32_e32 v59, 0xffff0000, v39
	v_pk_fma_f32 v[38:39], v[20:21], v[56:57], 0 op_sel_hi:[1,1,0]

; DEV void gdn_prep_chunk(const Params& p, int item, unsigned char* lds) {
;     ...
;                     a += w[j][e] * xv;
	v_pk_fma_f32 v[38:39], v[24:25], v[70:71], v[38:39]

; DEV void gdn_prep_chunk(const Params& p, int item, unsigned char* lds) {
;     ...
;                     a += w[j][e] * xv;
	v_pk_fma_f32 v[38:39], v[28:29], v[66:67], v[38:39]

; DEV void gdn_prep_chunk(const Params& p, int item, unsigned char* lds) {
;     ...
;                     a += w[j][e] * xv;
	v_pk_fma_f32 v[38:39], v[32:33], v[58:59], v[38:39]

; DEV float silu_f(float x) { return x / (1.f + __expf(-x)); }
; DEV void gdn_prep_chunk(const Params& p, int item, unsigned char* lds) {
;     ...
;                 y[e] = silu_f(a); ss += y[e] * y[e];
	v_mul_f32_e32 v44, 0xbfb8aa3b, v38
	v_mul_f32_e32 v45, 0xbfb8aa3b, v39
	v_exp_f32_e32 v44, v44
	v_exp_f32_e32 v45, v45


; DEV float silu_f(float x) { return x / (1.f + __expf(-x)); }
; DEV void gdn_prep_chunk(const Params& p, int item, unsigned char* lds) {
;     ...
;                     a += w[j][e] * xv;
;                 }
;                 y[e] = silu_f(a); ss += y[e] * y[e];
	v_rcp_f32_e32 v62, v64
	s_nop 0
	v_mul_f32_e32 v62, v78, v62
	v_pk_add_f32 v[56:57], v[44:45], 1.0 op_sel_hi:[1,0]
	v_pk_fma_f32 v[54:55], v[6:7], v[52:53], v[54:55]


; DEV void gdn_prep_chunk(const Params& p, int item, unsigned char* lds) {
;     ...
;                     a += w[j][e] * xv;
	v_pk_fma_f32 v[54:55], v[10:11], v[48:49], v[54:55]


; DEV float bflo(unsigned u) { return __uint_as_float(u << 16); }
; DEV float bfhi(unsigned u) { return __uint_as_float(u & 0xffff0000u); }
; DEV float silu_f(float x) { return x / (1.f + __expf(-x)); }
; DEV void gdn_prep_chunk(const Params& p, int item, unsigned char* lds) {
;     ...
;                     const float xv = (e & 1) ? bfhi(wd) : bflo(wd);
;     ...
;                 y[e] = silu_f(a); ss += y[e] * y[e];
	v_rcp_f32_e32 v44, v57
	s_nop 0
	v_mul_f32_e32 v57, v39, v44
	v_lshlrev_b32_e32 v44, 16, v40
	v_and_b32_e32 v45, 0xffff0000, v40

; DEV void gdn_prep_chunk(const Params& p, int item, unsigned char* lds) {
;     ...
;                     a += w[j][e] * xv;
	v_pk_fma_f32 v[54:55], v[14:15], v[44:45], v[54:55]

; DEV float silu_f(float x) { return x / (1.f + __expf(-x)); }
; DEV void gdn_prep_chunk(const Params& p, int item, unsigned char* lds) {
;     ...
;                 y[e] = silu_f(a); ss += y[e] * y[e];
	v_mul_f32_e32 v40, 0xbfb8aa3b, v54
	v_exp_f32_e32 v64, v40
	v_mul_f32_e32 v40, 0xbfb8aa3b, v55
	v_exp_f32_e32 v65, v40


; DEV float silu_f(float x) { return x / (1.f + __expf(-x)); }
; DEV void gdn_prep_chunk(const Params& p, int item, unsigned char* lds) {
;     ...
;                 y[e] = silu_f(a); ss += y[e] * y[e];
	s_nop 0
	v_pk_add_f32 v[64:65], v[64:65], 1.0 op_sel_hi:[1,0]


; DEV float silu_f(float x) { return x / (1.f + __expf(-x)); }
; DEV void gdn_prep_chunk(const Params& p, int item, unsigned char* lds) {
;     ...
;                 y[e] = silu_f(a); ss += y[e] * y[e];
	v_rcp_f32_e32 v39, v56
	s_nop 0
	v_mul_f32_e32 v56, v38, v39


; DEV float silu_f(float x) { return x / (1.f + __expf(-x)); }
; DEV void gdn_prep_chunk(const Params& p, int item, unsigned char* lds) {
;     ...
;                 y[e] = silu_f(a); ss += y[e] * y[e];
	v_rcp_f32_e32 v38, v65
	s_nop 0
	v_mul_f32_e32 v55, v55, v38


; DEV float bflo(unsigned u) { return __uint_as_float(u << 16); }
; DEV float bfhi(unsigned u) { return __uint_as_float(u & 0xffff0000u); }
; DEV void gdn_prep_chunk(const Params& p, int item, unsigned char* lds) {
;     ...
;             for (int e = 0; e < 8; ++e) {
;                 float a = 0.f;
; #pragma unroll
;                 for (int j = 0; j < 4; ++j) {
;                     const uint4 u = raw[r + j];
;                     const unsigned wd = (e < 2 ? u.x : (e < 4 ? u.y : (e < 6 ? u.z : u.w)));
;                     const float xv = (e & 1) ? bfhi(wd) : bflo(wd);
;                     a += w[j][e] * xv;
	v_lshlrev_b32_e32 v38, 16, v41
	v_and_b32_e32 v39, 0xffff0000, v41
	v_pk_fma_f32 v[40:41], v[4:5], v[50:51], 0 op_sel_hi:[1,1,0]

; DEV void gdn_prep_chunk(const Params& p, int item, unsigned char* lds) {
;     ...
;                     a += w[j][e] * xv;
	v_pk_fma_f32 v[40:41], v[8:9], v[46:47], v[40:41]

; DEV void gdn_prep_chunk(const Params& p, int item, unsigned char* lds) {
;     ...
;                     a += w[j][e] * xv;
	v_pk_fma_f32 v[40:41], v[12:13], v[42:43], v[40:41]

; DEV void gdn_prep_chunk(const Params& p, int item, unsigned char* lds) {
;     ...
;                     a += w[j][e] * xv;
	v_pk_fma_f32 v[40:41], v[16:17], v[38:39], v[40:41]

; DEV float silu_f(float x) { return x / (1.f + __expf(-x)); }
; DEV void gdn_prep_chunk(const Params& p, int item, unsigned char* lds) {
;     ...
;                 y[e] = silu_f(a); ss += y[e] * y[e];
	v_mul_f32_e32 v50, 0xbfb8aa3b, v40
	v_mul_f32_e32 v51, 0xbfb8aa3b, v41
	v_exp_f32_e32 v50, v50
	v_exp_f32_e32 v51, v51


; DEV float silu_f(float x) { return x / (1.f + __expf(-x)); }
; DEV void gdn_prep_chunk(const Params& p, int item, unsigned char* lds) {
;     ...
;                 y[e] = silu_f(a); ss += y[e] * y[e];
	v_rcp_f32_e32 v65, v64
	s_nop 0
	v_mul_f32_e32 v54, v54, v65
	v_pk_add_f32 v[50:51], v[50:51], 1.0 op_sel_hi:[1,0]
	s_nop 0


; DEV float silu_f(float x) { return x / (1.f + __expf(-x)); }
; DEV void gdn_prep_chunk(const Params& p, int item, unsigned char* lds) {
;     ...
;                 y[e] = silu_f(a); ss += y[e] * y[e];
	s_nop 0


; DEV float silu_f(float x) { return x / (1.f + __expf(-x)); }
; DEV void gdn_prep_chunk(const Params& p, int item, unsigned char* lds) {
;     ...
;                 y[e] = silu_f(a); ss += y[e] * y[e];
	v_rcp_f32_e32 v64, v51
	s_nop 0
	v_mul_f32_e32 v41, v41, v64


; DEV float silu_f(float x) { return x / (1.f + __expf(-x)); }
; DEV void gdn_prep_chunk(const Params& p, int item, unsigned char* lds) {
;     ...
;                 y[e] = silu_f(a); ss += y[e] * y[e];
;             }
;             if (mat < 2) {
;                 ss += __shfl_xor(ss, 1); ss += __shfl_xor(ss, 2); ss += __shfl_xor(ss, 4); ss += __shfl_xor(ss, 8);
	v_rcp_f32_e32 v51, v50
	s_nop 0
	v_mul_f32_e32 v40, v40, v51
	s_and_saveexec_b64 s[36:37], s[6:7]
	s_cbranch_execz .LBB0_502
	v_pk_mul_f32 v[50:51], v[62:63], v[62:63]
	v_pk_mul_f32 v[64:65], v[56:57], v[56:57]
	v_add_f32_e32 v50, v50, v51
	v_add_f32_e32 v50, v50, v64
	v_pk_mul_f32 v[74:75], v[54:55], v[54:55]
	v_add_f32_e32 v50, v65, v50
	v_and_b32_e32 v64, 64, v182
	v_add_f32_e32 v50, v74, v50

; DEV float silu_f(float x) { return x / (1.f + __expf(-x)); }
; DEV void gdn_prep_chunk(const Params& p, int item, unsigned char* lds) {
;     ...
;                 y[e] = silu_f(a); ss += y[e] * y[e];
;             }
;             if (mat < 2) {
;                 ss += __shfl_xor(ss, 1); ss += __shfl_xor(ss, 2); ss += __shfl_xor(ss, 4); ss += __shfl_xor(ss, 8);
	v_add_u32_e32 v64, 64, v64
	v_pk_mul_f32 v[76:77], v[40:41], v[40:41]
	v_add_f32_e32 v50, v75, v50

; DEV float silu_f(float x) { return x / (1.f + __expf(-x)); }
; DEV void gdn_prep_chunk(const Params& p, int item, unsigned char* lds) {
;     ...
;                 y[e] = silu_f(a); ss += y[e] * y[e];
;             }
;             if (mat < 2) {
;                 ss += __shfl_xor(ss, 1); ss += __shfl_xor(ss, 2); ss += __shfl_xor(ss, 4); ss += __shfl_xor(ss, 8);
	v_add_f32_e32 v50, v76, v50
	v_add_f32_e32 v50, v77, v50


; DEV void gdn_prep_chunk(const Params& p, int item, unsigned char* lds) {
;     ...
;                 ss += __shfl_xor(ss, 1); ss += __shfl_xor(ss, 2); ss += __shfl_xor(ss, 4); ss += __shfl_xor(ss, 8);
	s_waitcnt lgkmcnt(0)
	s_nop 1
	v_add_f32_dpp v50, v50, v50 quad_perm:[1,0,3,2] row_mask:0xf bank_mask:0xf


; DEV void gdn_prep_chunk(const Params& p, int item, unsigned char* lds) {
;     ...
;                 ss += __shfl_xor(ss, 1); ss += __shfl_xor(ss, 2); ss += __shfl_xor(ss, 4); ss += __shfl_xor(ss, 8);
	s_nop 1


; DEV void gdn_prep_chunk(const Params& p, int item, unsigned char* lds) {
;     ...
;                 ss += __shfl_xor(ss, 1); ss += __shfl_xor(ss, 2); ss += __shfl_xor(ss, 4); ss += __shfl_xor(ss, 8);
	s_waitcnt lgkmcnt(0)
	s_nop 1
	v_add_f32_dpp v50, v50, v50 quad_perm:[2,3,0,1] row_mask:0xf bank_mask:0xf


; DEV void gdn_prep_chunk(const Params& p, int item, unsigned char* lds) {
;     ...
;                 ss += __shfl_xor(ss, 1); ss += __shfl_xor(ss, 2); ss += __shfl_xor(ss, 4); ss += __shfl_xor(ss, 8);
	s_nop 1


; DEV void gdn_prep_chunk(const Params& p, int item, unsigned char* lds) {
;     ...
;                 ss += __shfl_xor(ss, 1); ss += __shfl_xor(ss, 2); ss += __shfl_xor(ss, 4); ss += __shfl_xor(ss, 8);
	s_waitcnt lgkmcnt(0)
	s_nop 1
	v_add_f32_dpp v50, v50, v50 row_half_mirror row_mask:0xf bank_mask:0xf


; DEV void gdn_prep_chunk(const Params& p, int item, unsigned char* lds) {
;     ...
;                 ss += __shfl_xor(ss, 1); ss += __shfl_xor(ss, 2); ss += __shfl_xor(ss, 4); ss += __shfl_xor(ss, 8);
	s_nop 1


; DEV unsigned cvt_pk_bf16(float lo, float hi) { const f32x2_t v = {lo, hi}; const bf16x2_t b = __builtin_convertvector(v, bf16x2_t); return __builtin_bit_cast(unsigned, b); }
; DEV float bflo(unsigned u) { return __uint_as_float(u << 16); }
; DEV float bfhi(unsigned u) { return __uint_as_float(u & 0xffff0000u); }
; DEV float silu_f(float x) { return x / (1.f + __expf(-x)); }
; DEV void gdn_prep_chunk(const Params& p, int item, unsigned char* lds) {
;     ...
;             for (int e = 0; e < 8; ++e) {
;                 float a = 0.f;
; #pragma unroll
;                 for (int j = 0; j < 4; ++j) {
;                     const uint4 u = raw[r + j];
;                     const unsigned wd = (e < 2 ? u.x : (e < 4 ? u.y : (e < 6 ? u.z : u.w)));
;                     const float xv = (e & 1) ? bfhi(wd) : bflo(wd);
;                     a += w[j][e] * xv;
;                 }
;                 y[e] = silu_f(a); ss += y[e] * y[e];
;     ...
;                 ss += __shfl_xor(ss, 1); ss += __shfl_xor(ss, 2); ss += __shfl_xor(ss, 4); ss += __shfl_xor(ss, 8);
;                 float inv = rsqrtf(ss + EPS); if (mat == 0) inv *= 0.08838834764831845f;
; #pragma unroll
;                 for (int e = 0; e < 8; ++e) y[e] *= inv;
;             }
;             uint4 o; o.x = cvt_pk_bf16(y[0], y[1]); o.y = cvt_pk_bf16(y[2], y[3]); o.z = cvt_pk_bf16(y[4], y[5]); o.w = cvt_pk_bf16(y[6], y[7]);
;             *(uint4*)(dst + (tl0 + r) * QS + cv * 8) = o;
	s_waitcnt lgkmcnt(0)
	s_nop 1
	v_add_f32_dpp v50, v50, v50 row_mirror row_mask:0xf bank_mask:0xf
	v_add_f32_e32 v50, 0x358637bd, v50
	v_mul_f32_e32 v51, 0x4b800000, v50
	v_cmp_gt_f32_e32 vcc, s56, v50
	s_nop 1
	v_cndmask_b32_e32 v50, v50, v51, vcc
	v_rsq_f32_e32 v50, v50
	s_nop 0
	v_mul_f32_e32 v51, 0x45800000, v50
	v_cndmask_b32_e32 v50, v50, v51, vcc
	v_mul_f32_e32 v51, 0x3db504f3, v50
	v_cndmask_b32_e64 v50, v50, v51, s[4:5]
	v_pk_mul_f32 v[62:63], v[62:63], v[50:51] op_sel_hi:[1,0]
	v_pk_mul_f32 v[56:57], v[56:57], v[50:51] op_sel_hi:[1,0]
	v_pk_mul_f32 v[54:55], v[54:55], v[50:51] op_sel_hi:[1,0]
	v_pk_mul_f32 v[40:41], v[40:41], v[50:51] op_sel_hi:[1,0]
.LBB0_502:
	s_or_b64 exec, exec, s[36:37]
	v_pk_fma_f32 v[18:19], v[18:19], v[72:73], 0 op_sel_hi:[1,1,0]
	s_waitcnt vmcnt(0)
	v_lshlrev_b32_e32 v50, 16, v34
	v_pk_fma_f32 v[18:19], v[22:23], v[68:69], v[18:19]
	v_and_b32_e32 v51, 0xffff0000, v34
	v_pk_fma_f32 v[18:19], v[26:27], v[60:61], v[18:19]
	v_pk_fma_f32 v[20:21], v[20:21], v[70:71], 0 op_sel_hi:[1,1,0]
	v_pk_fma_f32 v[18:19], v[30:31], v[50:51], v[18:19]
	v_pk_fma_f32 v[20:21], v[24:25], v[66:67], v[20:21]
	v_mul_f32_e32 v22, 0xbfb8aa3b, v18
	v_mul_f32_e32 v23, 0xbfb8aa3b, v19
	v_exp_f32_e32 v22, v22
	v_exp_f32_e32 v23, v23
	v_pk_fma_f32 v[20:21], v[28:29], v[58:59], v[20:21]
	v_pk_fma_f32 v[2:3], v[2:3], v[52:53], 0 op_sel_hi:[1,1,0]
	v_pk_fma_f32 v[4:5], v[4:5], v[46:47], 0 op_sel_hi:[1,1,0]
	v_pk_add_f32 v[22:23], v[22:23], 1.0 op_sel_hi:[1,0]
	v_pk_fma_f32 v[2:3], v[6:7], v[48:49], v[2:3]


; DEV unsigned cvt_pk_bf16(float lo, float hi) { const f32x2_t v = {lo, hi}; const bf16x2_t b = __builtin_convertvector(v, bf16x2_t); return __builtin_bit_cast(unsigned, b); }
; DEV void gdn_prep_chunk(const Params& p, int item, unsigned char* lds) {
;     ...
;                     a += w[j][e] * xv;
;     ...
;             uint4 o; o.x = cvt_pk_bf16(y[0], y[1]); o.y = cvt_pk_bf16(y[2], y[3]); o.z = cvt_pk_bf16(y[4], y[5]); o.w = cvt_pk_bf16(y[6], y[7]);
	v_pk_fma_f32 v[2:3], v[10:11], v[44:45], v[2:3]
	v_pk_fma_f32 v[4:5], v[8:9], v[42:43], v[4:5]
	v_cvt_pk_bf16_f32 v60, v62, v63


; DEV float silu_f(float x) { return x / (1.f + __expf(-x)); }
; DEV void gdn_prep_chunk(const Params& p, int item, unsigned char* lds) {
;     ...
;                     a += w[j][e] * xv;
;     ...
;                 y[e] = silu_f(a); ss += y[e] * y[e];
	v_rcp_f32_e32 v26, v23
	s_nop 0
	v_mul_f32_e32 v19, v19, v26
	v_lshlrev_b32_e32 v26, 16, v35
	v_and_b32_e32 v27, 0xffff0000, v35
	v_pk_fma_f32 v[20:21], v[32:33], v[26:27], v[20:21]

; DEV float silu_f(float x) { return x / (1.f + __expf(-x)); }
; DEV void gdn_prep_chunk(const Params& p, int item, unsigned char* lds) {
;     ...
;                 y[e] = silu_f(a); ss += y[e] * y[e];
	v_mul_f32_e32 v24, 0xbfb8aa3b, v20
	v_mul_f32_e32 v25, 0xbfb8aa3b, v21
	v_exp_f32_e32 v24, v24
	v_exp_f32_e32 v25, v25


; DEV float silu_f(float x) { return x / (1.f + __expf(-x)); }
; DEV void gdn_prep_chunk(const Params& p, int item, unsigned char* lds) {
;     ...
;                 y[e] = silu_f(a); ss += y[e] * y[e];
	s_nop 0
	v_pk_add_f32 v[24:25], v[24:25], 1.0 op_sel_hi:[1,0]


; DEV float silu_f(float x) { return x / (1.f + __expf(-x)); }
; DEV void gdn_prep_chunk(const Params& p, int item, unsigned char* lds) {
;     ...
;                 y[e] = silu_f(a); ss += y[e] * y[e];
	v_rcp_f32_e32 v23, v22
	s_nop 0
	v_mul_f32_e32 v18, v18, v23


; DEV float silu_f(float x) { return x / (1.f + __expf(-x)); }
; DEV void gdn_prep_chunk(const Params& p, int item, unsigned char* lds) {
;     ...
;                 y[e] = silu_f(a); ss += y[e] * y[e];
	v_rcp_f32_e32 v22, v25
	s_nop 0
	v_mul_f32_e32 v21, v21, v22
	v_and_b32_e32 v23, 0xffff0000, v36


; DEV float bflo(unsigned u) { return __uint_as_float(u << 16); }
; DEV float bfhi(unsigned u) { return __uint_as_float(u & 0xffff0000u); }
; DEV void gdn_prep_chunk(const Params& p, int item, unsigned char* lds) {
;     ...
;                     const float xv = (e & 1) ? bfhi(wd) : bflo(wd);
;                     a += w[j][e] * xv;
	v_lshlrev_b32_e32 v22, 16, v36
	v_pk_fma_f32 v[2:3], v[14:15], v[22:23], v[2:3]

; DEV float silu_f(float x) { return x / (1.f + __expf(-x)); }
; DEV void gdn_prep_chunk(const Params& p, int item, unsigned char* lds) {
;     ...
;                 y[e] = silu_f(a); ss += y[e] * y[e];
	v_mul_f32_e32 v6, 0xbfb8aa3b, v2
	v_mul_f32_e32 v7, 0xbfb8aa3b, v3
	v_exp_f32_e32 v6, v6
	v_exp_f32_e32 v7, v7


; DEV float silu_f(float x) { return x / (1.f + __expf(-x)); }
; DEV void gdn_prep_chunk(const Params& p, int item, unsigned char* lds) {
;     ...
;                 y[e] = silu_f(a); ss += y[e] * y[e];
	s_nop 0
	v_pk_add_f32 v[6:7], v[6:7], 1.0 op_sel_hi:[1,0]


; DEV float silu_f(float x) { return x / (1.f + __expf(-x)); }
; DEV void gdn_prep_chunk(const Params& p, int item, unsigned char* lds) {
;     ...
;                     a += w[j][e] * xv;
;     ...
;                 y[e] = silu_f(a); ss += y[e] * y[e];
	v_rcp_f32_e32 v10, v24
	s_nop 0
	v_mul_f32_e32 v20, v20, v10
	v_pk_fma_f32 v[4:5], v[12:13], v[38:39], v[4:5]


; DEV float silu_f(float x) { return x / (1.f + __expf(-x)); }
; DEV void gdn_prep_chunk(const Params& p, int item, unsigned char* lds) {
;     ...
;                     a += w[j][e] * xv;
;     ...
;                 y[e] = silu_f(a); ss += y[e] * y[e];
	v_rcp_f32_e32 v10, v7
	s_nop 0
	v_mul_f32_e32 v3, v3, v10
	v_lshlrev_b32_e32 v10, 16, v37
	v_and_b32_e32 v11, 0xffff0000, v37
	v_pk_fma_f32 v[4:5], v[16:17], v[10:11], v[4:5]

; DEV float silu_f(float x) { return x / (1.f + __expf(-x)); }
; DEV void gdn_prep_chunk(const Params& p, int item, unsigned char* lds) {
;     ...
;                 y[e] = silu_f(a); ss += y[e] * y[e];
	v_mul_f32_e32 v8, 0xbfb8aa3b, v4
	v_mul_f32_e32 v9, 0xbfb8aa3b, v5
	v_exp_f32_e32 v8, v8
	v_exp_f32_e32 v9, v9


; DEV float silu_f(float x) { return x / (1.f + __expf(-x)); }
; DEV void gdn_prep_chunk(const Params& p, int item, unsigned char* lds) {
;     ...
;                 y[e] = silu_f(a); ss += y[e] * y[e];
	s_nop 0
	v_pk_add_f32 v[8:9], v[8:9], 1.0 op_sel_hi:[1,0]


; DEV float silu_f(float x) { return x / (1.f + __expf(-x)); }
; DEV void gdn_prep_chunk(const Params& p, int item, unsigned char* lds) {
;     ...
;                 y[e] = silu_f(a); ss += y[e] * y[e];
	v_rcp_f32_e32 v7, v6
	s_nop 0
	v_mul_f32_e32 v2, v2, v7


; DEV unsigned cvt_pk_bf16(float lo, float hi) { const f32x2_t v = {lo, hi}; const bf16x2_t b = __builtin_convertvector(v, bf16x2_t); return __builtin_bit_cast(unsigned, b); }
; DEV float silu_f(float x) { return x / (1.f + __expf(-x)); }
; DEV void gdn_prep_chunk(const Params& p, int item, unsigned char* lds) {
;     ...
;                 y[e] = silu_f(a); ss += y[e] * y[e];
;     ...
;             uint4 o; o.x = cvt_pk_bf16(y[0], y[1]); o.y = cvt_pk_bf16(y[2], y[3]); o.z = cvt_pk_bf16(y[4], y[5]); o.w = cvt_pk_bf16(y[6], y[7]);
	v_rcp_f32_e32 v6, v9
	s_nop 0
	v_mul_f32_e32 v5, v5, v6
	v_cvt_pk_bf16_f32 v61, v56, v57


; DEV unsigned cvt_pk_bf16(float lo, float hi) { const f32x2_t v = {lo, hi}; const bf16x2_t b = __builtin_convertvector(v, bf16x2_t); return __builtin_bit_cast(unsigned, b); }
; DEV float silu_f(float x) { return x / (1.f + __expf(-x)); }
; DEV void gdn_prep_chunk(const Params& p, int item, unsigned char* lds) {
;     ...
;                 y[e] = silu_f(a); ss += y[e] * y[e];
;             }
;             if (mat < 2) {
;                 ss += __shfl_xor(ss, 1); ss += __shfl_xor(ss, 2); ss += __shfl_xor(ss, 4); ss += __shfl_xor(ss, 8);
;     ...
;             uint4 o; o.x = cvt_pk_bf16(y[0], y[1]); o.y = cvt_pk_bf16(y[2], y[3]); o.z = cvt_pk_bf16(y[4], y[5]); o.w = cvt_pk_bf16(y[6], y[7]);
;             *(uint4*)(dst + (tl0 + r) * QS + cv * 8) = o;
	v_cvt_pk_bf16_f32 v62, v54, v55
	v_cvt_pk_bf16_f32 v63, v40, v41
	v_rcp_f32_e32 v6, v8
	s_nop 0
	v_mul_f32_e32 v4, v4, v6
	ds_write_b128 v104, v[60:63] offset:2176
	s_and_saveexec_b64 s[36:37], s[6:7]
	s_cbranch_execz .LBB0_504
	v_pk_mul_f32 v[6:7], v[18:19], v[18:19]
	v_pk_mul_f32 v[8:9], v[20:21], v[20:21]
	v_add_f32_e32 v6, v6, v7
	v_add_f32_e32 v6, v6, v8
	v_pk_mul_f32 v[10:11], v[2:3], v[2:3]
	v_add_f32_e32 v6, v9, v6
	v_and_b32_e32 v8, 64, v182
	v_add_f32_e32 v6, v10, v6

; DEV float silu_f(float x) { return x / (1.f + __expf(-x)); }
; DEV void gdn_prep_chunk(const Params& p, int item, unsigned char* lds) {
;     ...
;                 y[e] = silu_f(a); ss += y[e] * y[e];
;             }
;             if (mat < 2) {
;                 ss += __shfl_xor(ss, 1); ss += __shfl_xor(ss, 2); ss += __shfl_xor(ss, 4); ss += __shfl_xor(ss, 8);
	v_add_u32_e32 v8, 64, v8
	v_pk_mul_f32 v[12:13], v[4:5], v[4:5]
	v_add_f32_e32 v6, v11, v6

; DEV float silu_f(float x) { return x / (1.f + __expf(-x)); }
; DEV void gdn_prep_chunk(const Params& p, int item, unsigned char* lds) {
;     ...
;                 y[e] = silu_f(a); ss += y[e] * y[e];
;             }
;             if (mat < 2) {
;                 ss += __shfl_xor(ss, 1); ss += __shfl_xor(ss, 2); ss += __shfl_xor(ss, 4); ss += __shfl_xor(ss, 8);
	v_add_f32_e32 v6, v12, v6
	v_add_f32_e32 v6, v13, v6


; DEV void gdn_prep_chunk(const Params& p, int item, unsigned char* lds) {
;     ...
;                 ss += __shfl_xor(ss, 1); ss += __shfl_xor(ss, 2); ss += __shfl_xor(ss, 4); ss += __shfl_xor(ss, 8);
	s_waitcnt lgkmcnt(0)
	s_nop 1
	v_add_f32_dpp v6, v6, v6 quad_perm:[1,0,3,2] row_mask:0xf bank_mask:0xf


; DEV void gdn_prep_chunk(const Params& p, int item, unsigned char* lds) {
;     ...
;                 ss += __shfl_xor(ss, 1); ss += __shfl_xor(ss, 2); ss += __shfl_xor(ss, 4); ss += __shfl_xor(ss, 8);
	s_nop 1


; DEV void gdn_prep_chunk(const Params& p, int item, unsigned char* lds) {
;     ...
;                 ss += __shfl_xor(ss, 1); ss += __shfl_xor(ss, 2); ss += __shfl_xor(ss, 4); ss += __shfl_xor(ss, 8);
	s_waitcnt lgkmcnt(0)
	s_nop 1
	v_add_f32_dpp v6, v6, v6 quad_perm:[2,3,0,1] row_mask:0xf bank_mask:0xf


; DEV void gdn_prep_chunk(const Params& p, int item, unsigned char* lds) {
;     ...
;                 ss += __shfl_xor(ss, 1); ss += __shfl_xor(ss, 2); ss += __shfl_xor(ss, 4); ss += __shfl_xor(ss, 8);
	s_nop 1


; DEV void gdn_prep_chunk(const Params& p, int item, unsigned char* lds) {
;     ...
;                 ss += __shfl_xor(ss, 1); ss += __shfl_xor(ss, 2); ss += __shfl_xor(ss, 4); ss += __shfl_xor(ss, 8);
	s_waitcnt lgkmcnt(0)
	s_nop 1
	v_add_f32_dpp v6, v6, v6 row_half_mirror row_mask:0xf bank_mask:0xf


; DEV void gdn_prep_chunk(const Params& p, int item, unsigned char* lds) {
;     ...
;                 ss += __shfl_xor(ss, 1); ss += __shfl_xor(ss, 2); ss += __shfl_xor(ss, 4); ss += __shfl_xor(ss, 8);
	s_nop 1


; DEV void gdn_prep_chunk(const Params& p, int item, unsigned char* lds) {
;     ...
;                 ss += __shfl_xor(ss, 1); ss += __shfl_xor(ss, 2); ss += __shfl_xor(ss, 4); ss += __shfl_xor(ss, 8);
;                 float inv = rsqrtf(ss + EPS); if (mat == 0) inv *= 0.08838834764831845f;
; #pragma unroll
;                 for (int e = 0; e < 8; ++e) y[e] *= inv;
	s_waitcnt lgkmcnt(0)
	s_nop 1
	v_add_f32_dpp v6, v6, v6 row_mirror row_mask:0xf bank_mask:0xf
	v_add_f32_e32 v6, 0x358637bd, v6
	v_mul_f32_e32 v7, 0x4b800000, v6
	v_cmp_gt_f32_e32 vcc, s56, v6
	s_nop 1
	v_cndmask_b32_e32 v6, v6, v7, vcc
	v_rsq_f32_e32 v6, v6
	s_nop 0
	v_mul_f32_e32 v7, 0x45800000, v6
	v_cndmask_b32_e32 v6, v6, v7, vcc
	v_mul_f32_e32 v7, 0x3db504f3, v6
	v_cndmask_b32_e64 v6, v6, v7, s[4:5]
	v_pk_mul_f32 v[18:19], v[18:19], v[6:7] op_sel_hi:[1,0]
	v_pk_mul_f32 v[20:21], v[20:21], v[6:7] op_sel_hi:[1,0]
	v_pk_mul_f32 v[2:3], v[2:3], v[6:7] op_sel_hi:[1,0]
	v_pk_mul_f32 v[4:5], v[4:5], v[6:7] op_sel_hi:[1,0]
